# P5 chunk precompute: pre-conv row loads as global loads with counted waits (were flat loads with full waits); on top of v14
# speedup vs baseline: 1.0055x; 1.0055x over previous
.LBB0_1066:
	v_lshl_add_u64 v[44:45], v[22:23], 1, s[6:7]
	s_movk_i32 s2, 0xfc00
	v_add_co_u32_e32 v30, vcc, s2, v44
	s_movk_i32 s4, 0x1000
	s_nop 0
	v_addc_co_u32_e32 v31, vcc, -1, v45, vcc
	global_load_ushort v17, v[30:31], off
	v_add_co_u32_e32 v30, vcc, s4, v44
	s_waitcnt vmcnt(0)
	v_mul_f32_e32 v16, v5, v16
	v_addc_co_u32_e32 v31, vcc, 0, v45, vcc
	v_add_co_u32_e32 v48, vcc, s14, v44
	v_fmac_f32_e32 v16, v9, v70
	s_nop 0
	v_addc_co_u32_e32 v49, vcc, 0, v45, vcc
	global_load_ushort v54, v[30:31], off offset:3072
	global_load_ushort v71, v[30:31], off
	global_load_ushort v47, v[48:49], off
	global_load_ushort v50, v[30:31], off offset:1024
	global_load_ushort v52, v[44:45], off offset:3072
	global_load_ushort v55, v[48:49], off offset:3072
	global_load_ushort v72, v[44:45], off
	v_fmac_f32_e32 v16, v7, v46
	v_mov_b32_e32 v57, 0
	v_mul_f32_e32 v32, 0xbfb8aa3b, v14
	v_exp_f32_e32 v62, v32
	v_mov_b32_e32 v60, 0
	v_add_co_u32_e32 v58, vcc, s12, v44
	s_mov_b64 s[2:3], 0x4000
	s_nop 0
	v_addc_co_u32_e32 v59, vcc, 0, v45, vcc
	global_load_ushort v56, v[44:45], off offset:1024
	global_load_ushort v69, v[58:59], off
	global_load_ushort v53, v[58:59], off offset:1024
	global_load_ushort v51, v[48:49], off offset:1024
	v_add_f32_e32 v48, 1.0, v62
	v_mov_b32_e32 v61, 0
	v_lshl_add_u64 v[32:33], v[44:45], 0, s[2:3]
	v_add_co_u32_e32 v36, vcc, s13, v44
	v_div_scale_f32 v49, s[2:3], v48, v48, 1.0
	s_movk_i32 s4, 0x5000
	v_addc_co_u32_e32 v37, vcc, 0, v45, vcc
	v_rcp_f32_e32 v62, v49
	v_add_co_u32_e32 v42, vcc, s4, v44
	s_movk_i32 s18, 0x6000
	s_nop 0
	v_addc_co_u32_e32 v43, vcc, 0, v45, vcc
	v_add_co_u32_e32 v38, vcc, s18, v44
	v_fma_f32 v67, -v49, v62, 1.0
	s_nop 0
	v_addc_co_u32_e32 v39, vcc, 0, v45, vcc
	v_div_scale_f32 v66, vcc, 1.0, v48, 1.0
	v_fmac_f32_e32 v62, v67, v62
	v_mul_f32_e32 v67, v66, v62
	v_fma_f32 v73, -v49, v67, v66
	v_lshrrev_b32_e32 v21, 3, v22
	v_lshlrev_b32_e32 v87, 1, v22
	v_fmac_f32_e32 v67, v73, v62
	s_mov_b64 s[6:7], 0x5000
	v_and_b32_e32 v64, 14, v87
	v_lshlrev_b32_e32 v65, 4, v21
	v_fma_f32 v49, -v49, v67, v66
	s_mov_b64 s[8:9], 0x6000
	s_mov_b64 s[16:17], 0x7000
	v_lshl_add_u64 v[34:35], v[44:45], 0, s[6:7]
	v_or_b32_e32 v63, v65, v64
	v_div_fmas_f32 v49, v49, v62, v67
	v_mov_b32_e32 v14, v28
	v_lshl_add_u64 v[40:41], v[44:45], 0, s[8:9]
	v_lshl_add_u64 v[30:31], v[44:45], 0, s[16:17]
	v_div_fixup_f32 v102, v49, v48, 1.0
	v_add_u32_e32 v114, s51, v63
	v_pk_mul_f32 v[14:15], v[12:13], v[14:15]
	v_readlane_b32 s6, v102, 0
	v_add_f32_e32 v14, v14, v15
	v_mov_b32_e32 v15, v12
	v_readlane_b32 s7, v102, 1
	v_readlane_b32 s8, v102, 2
	v_readlane_b32 s9, v102, 3
	v_pk_mul_f32 v[26:27], v[2:3], v[26:27] op_sel_hi:[0,1]
	v_pk_fma_f32 v[26:27], v[4:5], v[24:25], v[26:27] op_sel_hi:[0,1,1]
	v_ashrrev_i32_e32 v109, 5, v22
	v_lshlrev_b32_e32 v108, 4, v96
	s_waitcnt lgkmcnt(0)
	v_lshlrev_b32_e32 v68, 16, v17
	v_fmac_f32_e32 v16, v105, v68
	v_mul_f32_e32 v17, 0xbfb8aa3b, v16
	v_exp_f32_e32 v17, v17
	s_waitcnt vmcnt(3)
	v_lshlrev_b32_e32 v54, 16, v54
	v_add_f32_e32 v17, 1.0, v17
	v_rcp_f32_e32 v17, v17
	v_lshlrev_b32_e32 v52, 16, v52
	v_mul_f32_e32 v16, v16, v17
	v_mul_f32_e32 v17, v16, v16
	v_lshlrev_b32_e32 v56, 16, v56
	s_nop 0
	v_mov_b32_dpp v57, v17 quad_perm:[1,0,3,2] row_mask:0xf bank_mask:0xf
	v_fmac_f32_e32 v57, v16, v16
	s_nop 1
	v_add_f32_dpp v17, v57, v57 quad_perm:[2,3,0,1] row_mask:0xf bank_mask:0xf bound_ctrl:1
	s_nop 1
	v_add_f32_dpp v17, v17, v17 row_half_mirror row_mask:0xf bank_mask:0xf bound_ctrl:1
	s_nop 1
	v_add_f32_dpp v17, v17, v17 row_mirror row_mask:0xf bank_mask:0xf bound_ctrl:1
	s_nop 1
	v_mov_b32_dpp v60, v17 row_bcast:15 row_mask:0xa bank_mask:0xf
	v_add_f32_e32 v17, v17, v60
	v_lshlrev_b32_e32 v60, 16, v55
	s_nop 0
	v_mov_b32_dpp v61, v17 row_bcast:31 row_mask:0xc bank_mask:0xf
	v_add_f32_e32 v17, v17, v61
	s_nop 0
	v_readlane_b32 s2, v17, 63
	s_nop 1
	v_add_f32_e32 v17, s2, v86
	v_rsq_f32_e32 v17, v17
	s_movk_i32 s2, 0x7000
	v_mul_f32_e32 v16, v16, v17
	v_mul_f32_e32 v16, 0x3e000000, v16
	v_cvt_pk_bf16_f32 v73, v16, s0
	v_add_co_u32_e32 v16, vcc, s2, v44
	v_readlane_b32 s2, v3, 0
	s_nop 0
	v_addc_co_u32_e32 v17, vcc, 0, v45, vcc
	global_load_ushort v48, v[58:59], off offset:3072
	global_load_ushort v49, v[36:37], off offset:3072
	global_load_ushort v57, v[42:43], off offset:3072
	s_nop 0
	global_load_ushort v59, v[42:43], off
	global_load_ushort v66, v[40:41], off offset:1024
	global_load_ushort v63, v[36:37], off
	global_load_ushort v58, v[32:33], off offset:1024
	global_load_ushort v55, v[34:35], off offset:1024
	s_nop 0
	global_load_ushort v34, v[38:39], off offset:3072
	global_load_ushort v61, v[16:17], off
	global_load_ushort v62, v[38:39], off
	global_load_ushort v67, v[30:31], off offset:1024
	v_lshlrev_b32_e32 v33, 16, v71
	v_lshlrev_b32_e32 v32, 16, v72
	v_pk_mov_b32 v[30:31], v[28:29], v[32:33] op_sel:[1,0]
	v_mov_b32_e32 v38, 0
	v_pk_mul_f32 v[36:37], v[10:11], v[30:31]
	v_mul_f32_e32 v35, v5, v70
	v_add_f32_e32 v14, v36, v14
	v_add_f32_e32 v36, v14, v37
	v_mul_f32_e32 v14, 0xbfb8aa3b, v36
	v_exp_f32_e32 v14, v14
	v_fmac_f32_e32 v35, v9, v46
	v_fmac_f32_e32 v35, v7, v68
	v_pk_mul_f32 v[40:41], v[10:11], v[32:33]
	v_add_f32_e32 v14, 1.0, v14
	v_rcp_f32_e32 v37, v14
	v_mov_b32_e32 v14, v13
	v_pk_mul_f32 v[28:29], v[14:15], v[28:29]
	v_fmac_f32_e32 v35, v105, v52
	v_mul_f32_e32 v36, v36, v37
	v_mul_f32_e32 v37, v36, v36
	v_add_f32_e32 v28, v29, v28
	v_add_f32_e32 v28, v28, v40
	v_mov_b32_dpp v38, v37 quad_perm:[1,0,3,2] row_mask:0xf bank_mask:0xf
	v_fmac_f32_e32 v38, v36, v36
	v_add_f32_e32 v28, v28, v41
	v_mul_f32_e32 v29, 0xbfb8aa3b, v35
	v_add_f32_dpp v37, v38, v38 quad_perm:[2,3,0,1] row_mask:0xf bank_mask:0xf bound_ctrl:1
	v_mov_b32_e32 v38, 0
	v_exp_f32_e32 v29, v29
	v_add_f32_dpp v37, v37, v37 row_half_mirror row_mask:0xf bank_mask:0xf bound_ctrl:1
	v_mul_f32_e32 v40, 0xbfb8aa3b, v28
	v_exp_f32_e32 v40, v40
	v_add_f32_dpp v37, v37, v37 row_mirror row_mask:0xf bank_mask:0xf bound_ctrl:1
	v_mov_b32_e32 v39, s2
	v_add_f32_e32 v29, 1.0, v29
	v_mov_b32_dpp v38, v37 row_bcast:15 row_mask:0xa bank_mask:0xf
	v_add_f32_e32 v37, v37, v38
	v_mov_b32_e32 v38, 0
	v_rcp_f32_e32 v29, v29
	ds_write_b16 v114, v73
	v_mov_b32_dpp v38, v37 row_bcast:31 row_mask:0xc bank_mask:0xf
	v_add_f32_e32 v37, v37, v38
	v_mul_f32_e32 v29, v35, v29
	v_readlane_b32 s3, v37, 63
	v_mul_f32_e32 v35, v29, v29
	s_waitcnt vmcnt(2) lgkmcnt(0)
	v_lshlrev_b32_e32 v103, 16, v57
	v_add_f32_e32 v37, s3, v86
	v_rsq_f32_e32 v38, v37
	v_mov_b32_e32 v37, s6
	v_lshlrev_b32_e32 v57, 16, v50
	v_pk_mov_b32 v[24:25], v[24:25], v[56:57] op_sel:[1,0]
	v_pk_mul_f32 v[36:37], v[36:37], v[38:39]
	v_add_f32_e32 v38, 1.0, v40
	v_rcp_f32_e32 v38, v38
	v_cvt_pk_bf16_f32 v39, v36, s0
	ds_write_b16 v114, v39 offset:4096
	v_pk_fma_f32 v[26:27], v[6:7], v[24:25], v[26:27] op_sel_hi:[0,1,1]
	v_mul_f32_e32 v28, v28, v38
	v_mov_b32_e32 v38, 0
	v_pk_fma_f32 v[26:27], v[8:9], v[56:57], v[26:27] op_sel_hi:[0,1,1]
	v_lshlrev_b32_e32 v98, 16, v34
	v_mov_b32_dpp v38, v35 quad_perm:[1,0,3,2] row_mask:0xf bank_mask:0xf
	v_fmac_f32_e32 v38, v29, v29
	v_mul_f32_e32 v34, 0xbfb8aa3b, v26
	v_exp_f32_e32 v34, v34
	v_add_f32_dpp v35, v38, v38 quad_perm:[2,3,0,1] row_mask:0xf bank_mask:0xf bound_ctrl:1
	v_mov_b32_e32 v38, 0
	v_mul_f32_e32 v88, v36, v37
	v_add_f32_dpp v35, v35, v35 row_half_mirror row_mask:0xf bank_mask:0xf bound_ctrl:1
	v_add_f32_e32 v34, 1.0, v34
	v_rcp_f32_e32 v74, v34
	v_add_f32_dpp v35, v35, v35 row_mirror row_mask:0xf bank_mask:0xf bound_ctrl:1
	v_lshlrev_b32_e32 v55, 16, v55
	v_lshlrev_b32_e32 v61, 16, v61
	v_mov_b32_dpp v38, v35 row_bcast:15 row_mask:0xa bank_mask:0xf
	v_add_f32_e32 v35, v35, v38
	v_mov_b32_e32 v38, 0
	v_mul_f32_e32 v123, v9, v98
	v_fmac_f32_e32 v123, v5, v103
	v_mov_b32_dpp v38, v35 row_bcast:31 row_mask:0xc bank_mask:0xf
	v_add_f32_e32 v35, v35, v38
	v_mov_b32_e32 v38, 0
	v_readlane_b32 s2, v35, 63
	v_mul_f32_e32 v35, v28, v28
	s_nop 0
	v_add_f32_e32 v39, s2, v86
	v_mov_b32_dpp v38, v35 quad_perm:[1,0,3,2] row_mask:0xf bank_mask:0xf
	v_fmac_f32_e32 v38, v28, v28
	v_rsq_f32_e32 v39, v39
	s_nop 0
	v_add_f32_dpp v35, v38, v38 quad_perm:[2,3,0,1] row_mask:0xf bank_mask:0xf bound_ctrl:1
	v_mov_b32_e32 v38, 0
	v_mul_f32_e32 v29, v29, v39
	v_add_f32_dpp v35, v35, v35 row_half_mirror row_mask:0xf bank_mask:0xf bound_ctrl:1
	v_mul_f32_e32 v29, 0x3e000000, v29
	v_cvt_pk_bf16_f32 v29, v29, s0
	v_add_f32_dpp v35, v35, v35 row_mirror row_mask:0xf bank_mask:0xf bound_ctrl:1
	s_nop 1
	v_mov_b32_dpp v38, v35 row_bcast:15 row_mask:0xa bank_mask:0xf
	v_add_f32_e32 v35, v35, v38
	v_mov_b32_e32 v38, 0
	s_nop 1
	v_mov_b32_dpp v38, v35 row_bcast:31 row_mask:0xc bank_mask:0xf
	v_add_f32_e32 v35, v35, v38
	s_nop 0
	v_readlane_b32 s2, v35, 63
	s_nop 1
	v_add_f32_e32 v35, s2, v86
	v_rsq_f32_e32 v38, v35
	v_xor_b32_e32 v35, 16, v65
	v_or_b32_e32 v35, v35, v64
	v_add_u32_e32 v116, s51, v35
	v_mul_f32_e32 v35, v9, v68
	v_fmac_f32_e32 v35, v5, v46
	v_fmac_f32_e32 v35, v7, v52
	v_fmac_f32_e32 v35, v105, v54
	v_mul_f32_e32 v39, 0xbfb8aa3b, v35
	v_exp_f32_e32 v39, v39
	ds_write_b16 v116, v29 offset:128
	v_readlane_b32 s2, v3, 1
	v_add_f32_e32 v29, 1.0, v39
	v_rcp_f32_e32 v40, v29
	v_mov_b32_e32 v29, s7
	v_mov_b32_e32 v39, s2
	v_pk_mul_f32 v[38:39], v[28:29], v[38:39]
	v_mul_f32_e32 v28, v35, v40
	v_mul_f32_e32 v29, v28, v28
	v_mov_b32_e32 v35, 0
	v_pk_mul_f32 v[40:41], v[14:15], v[30:31]
	v_mul_f32_e32 v90, v38, v39
	v_mov_b32_dpp v35, v29 quad_perm:[1,0,3,2] row_mask:0xf bank_mask:0xf
	v_fmac_f32_e32 v35, v28, v28
	v_cvt_pk_bf16_f32 v36, v36, v38
	s_nop 0
	v_add_f32_dpp v29, v35, v35 quad_perm:[2,3,0,1] row_mask:0xf bank_mask:0xf bound_ctrl:1
	v_mov_b32_e32 v35, 0
	s_nop 0
	v_add_f32_dpp v29, v29, v29 row_half_mirror row_mask:0xf bank_mask:0xf bound_ctrl:1
	s_nop 1
	v_add_f32_dpp v29, v29, v29 row_mirror row_mask:0xf bank_mask:0xf bound_ctrl:1
	s_nop 1
	v_mov_b32_dpp v35, v29 row_bcast:15 row_mask:0xa bank_mask:0xf
	v_add_f32_e32 v29, v29, v35
	v_mov_b32_e32 v35, 0
	s_nop 1
	v_mov_b32_dpp v35, v29 row_bcast:31 row_mask:0xc bank_mask:0xf
	v_add_f32_e32 v29, v29, v35
	v_cvt_pk_bf16_f32 v35, v38, s0
	v_readlane_b32 s2, v29, 63
	ds_write_b16 v116, v35 offset:4224
	v_add_f32_e32 v35, v40, v41
	v_add_f32_e32 v29, s2, v86
	v_rsq_f32_e32 v29, v29
	v_mov_b32_e32 v41, 0
	v_readlane_b32 s2, v3, 2
	v_mul_f32_e32 v28, v28, v29
	v_xor_b32_e32 v29, 32, v65
	v_mul_f32_e32 v28, 0x3e000000, v28
	v_or_b32_e32 v29, v29, v64
	v_cvt_pk_bf16_f32 v28, v28, s0
	v_add_u32_e32 v115, s51, v29
	ds_write_b16 v115, v28 offset:256
	v_lshlrev_b32_e32 v29, 16, v69
	v_lshlrev_b32_e32 v28, 16, v47
	v_pk_mov_b32 v[30:31], v[32:33], v[28:29] op_sel:[1,0]
	v_mul_f32_e32 v69, v9, v52
	v_pk_mul_f32 v[42:43], v[10:11], v[30:31]
	v_fmac_f32_e32 v69, v5, v68
	v_add_f32_e32 v35, v35, v42
	v_add_f32_e32 v35, v35, v43
	v_mul_f32_e32 v40, 0xbfb8aa3b, v35
	v_exp_f32_e32 v40, v40
	v_pk_mul_f32 v[32:33], v[14:15], v[32:33]
	v_fmac_f32_e32 v69, v7, v54
	v_pk_mul_f32 v[46:47], v[10:11], v[28:29]
	v_add_f32_e32 v40, 1.0, v40
	v_rcp_f32_e32 v40, v40
	v_add_f32_e32 v32, v32, v33
	v_fmac_f32_e32 v69, v105, v60
	v_add_f32_e32 v32, v32, v46
	v_mul_f32_e32 v40, v35, v40
	v_mul_f32_e32 v35, v40, v40
	v_add_f32_e32 v32, v32, v47
	v_mul_f32_e32 v33, 0xbfb8aa3b, v69
	v_mov_b32_dpp v41, v35 quad_perm:[1,0,3,2] row_mask:0xf bank_mask:0xf
	v_fmac_f32_e32 v41, v40, v40
	v_exp_f32_e32 v33, v33
	v_mov_b32_e32 v43, s2
	v_add_f32_dpp v35, v41, v41 quad_perm:[2,3,0,1] row_mask:0xf bank_mask:0xf bound_ctrl:1
	v_mov_b32_e32 v41, 0
	v_add_f32_e32 v33, 1.0, v33
	v_add_f32_dpp v35, v35, v35 row_half_mirror row_mask:0xf bank_mask:0xf bound_ctrl:1
	v_rcp_f32_e32 v33, v33
	v_lshlrev_b32_e32 v68, 16, v48
	v_add_f32_dpp v35, v35, v35 row_mirror row_mask:0xf bank_mask:0xf bound_ctrl:1
	v_mul_f32_e32 v33, v69, v33
	s_nop 0
	v_mov_b32_dpp v41, v35 row_bcast:15 row_mask:0xa bank_mask:0xf
	v_add_f32_e32 v35, v35, v41
	v_mov_b32_e32 v41, 0
	s_nop 1
	v_mov_b32_dpp v41, v35 row_bcast:31 row_mask:0xc bank_mask:0xf
	v_add_f32_e32 v35, v35, v41
	v_mov_b32_e32 v41, s8
	v_readlane_b32 s3, v35, 63
	s_nop 1
	v_add_f32_e32 v35, s3, v86
	v_rsq_f32_e32 v42, v35
	v_mul_f32_e32 v35, 0xbfb8aa3b, v32
	v_exp_f32_e32 v35, v35
	v_pk_mul_f32 v[40:41], v[40:41], v[42:43]
	s_nop 0
	v_cvt_pk_bf16_f32 v42, v40, s0
	v_add_f32_e32 v35, 1.0, v35
	v_rcp_f32_e32 v35, v35
	ds_write_b16 v115, v42 offset:4352
	v_mov_b32_e32 v42, 0
	v_mul_f32_e32 v89, v40, v41
	v_mul_f32_e32 v32, v32, v35
	v_mul_f32_e32 v35, v33, v33
	s_nop 1
	v_mov_b32_dpp v42, v35 quad_perm:[1,0,3,2] row_mask:0xf bank_mask:0xf
	v_fmac_f32_e32 v42, v33, v33
	s_nop 1
	v_add_f32_dpp v35, v42, v42 quad_perm:[2,3,0,1] row_mask:0xf bank_mask:0xf bound_ctrl:1
	v_mov_b32_e32 v42, 0
	s_nop 0
	v_add_f32_dpp v35, v35, v35 row_half_mirror row_mask:0xf bank_mask:0xf bound_ctrl:1
	s_nop 1
	v_add_f32_dpp v35, v35, v35 row_mirror row_mask:0xf bank_mask:0xf bound_ctrl:1
	s_nop 1
	v_mov_b32_dpp v42, v35 row_bcast:15 row_mask:0xa bank_mask:0xf
	v_add_f32_e32 v35, v35, v42
	v_mov_b32_e32 v42, 0
	s_nop 1
	v_mov_b32_dpp v42, v35 row_bcast:31 row_mask:0xc bank_mask:0xf
	v_add_f32_e32 v35, v35, v42
	v_mov_b32_e32 v42, 0
	v_readlane_b32 s2, v35, 63
	v_mul_f32_e32 v35, v32, v32
	s_nop 0
	v_add_f32_e32 v43, s2, v86
	v_mov_b32_dpp v42, v35 quad_perm:[1,0,3,2] row_mask:0xf bank_mask:0xf
	v_fmac_f32_e32 v42, v32, v32
	v_rsq_f32_e32 v43, v43
	s_nop 0
	v_add_f32_dpp v35, v42, v42 quad_perm:[2,3,0,1] row_mask:0xf bank_mask:0xf bound_ctrl:1
	v_mov_b32_e32 v42, 0
	v_mul_f32_e32 v33, v33, v43
	v_add_f32_dpp v35, v35, v35 row_half_mirror row_mask:0xf bank_mask:0xf bound_ctrl:1
	v_mul_f32_e32 v33, 0x3e000000, v33
	v_cvt_pk_bf16_f32 v33, v33, s0
	v_add_f32_dpp v35, v35, v35 row_mirror row_mask:0xf bank_mask:0xf bound_ctrl:1
	s_nop 1
	v_mov_b32_dpp v42, v35 row_bcast:15 row_mask:0xa bank_mask:0xf
	v_add_f32_e32 v35, v35, v42
	v_mov_b32_e32 v42, 0
	s_nop 1
	v_mov_b32_dpp v42, v35 row_bcast:31 row_mask:0xc bank_mask:0xf
	v_add_f32_e32 v35, v35, v42
	s_nop 0
	v_readlane_b32 s2, v35, 63
	s_nop 1
	v_add_f32_e32 v35, s2, v86
	v_rsq_f32_e32 v42, v35
	v_xor_b32_e32 v35, 48, v65
	v_or_b32_e32 v35, v35, v64
	v_add_u32_e32 v117, s51, v35
	v_readlane_b32 s2, v3, 3
	ds_write_b16 v117, v33 offset:384
	v_mov_b32_e32 v33, s9
	v_mov_b32_e32 v43, s2
	v_pk_mul_f32 v[46:47], v[32:33], v[42:43]
	v_mul_f32_e32 v35, 0xbfb8aa3b, v27
	v_cvt_pk_bf16_f32 v32, v46, s0
	ds_write_b16 v117, v32 offset:4480
	global_load_ushort v33, v[16:17], off offset:3072
	v_exp_f32_e32 v35, v35
	s_mov_b32 s2, 0x8000
	v_add_co_u32_e32 v70, vcc, s2, v44
	v_add_f32_e32 v34, 1.0, v35
	v_rcp_f32_e32 v75, v34
	v_lshlrev_b32_e32 v35, 16, v53
	v_lshlrev_b32_e32 v34, 16, v51
	v_pk_mul_f32 v[50:51], v[4:5], v[56:57] op_sel_hi:[0,1]
	v_pk_fma_f32 v[24:25], v[2:3], v[24:25], v[50:51] op_sel_hi:[0,1,1]
	v_pk_mov_b32 v[50:51], v[56:57], v[34:35] op_sel:[1,0]
	v_lshl_or_b32 v16, v109, 11, v108
	v_pk_fma_f32 v[24:25], v[6:7], v[50:51], v[24:25] op_sel_hi:[0,1,1]
	v_addc_co_u32_e32 v71, vcc, 0, v45, vcc
	s_mov_b32 s2, 0x9000
	v_ashrrev_i32_e32 v17, 31, v16
	v_pk_fma_f32 v[56:57], v[8:9], v[34:35], v[24:25] op_sel_hi:[0,1,1]
	v_add_co_u32_e32 v72, vcc, s2, v44
	v_lshl_add_u64 v[42:43], s[0:1], 0, v[16:17]
	s_mov_b64 s[2:3], 0x2800
	v_mul_f32_e32 v24, 0xbfb8aa3b, v56
	v_addc_co_u32_e32 v73, vcc, 0, v45, vcc
	v_lshl_add_u64 v[16:17], v[42:43], 0, s[2:3]
	s_mov_b32 s2, 0xa000
	v_exp_f32_e32 v37, v24
	v_add_co_u32_e32 v48, vcc, s2, v44
	v_lshlrev_b32_e32 v32, 16, v49
	s_nop 0
	v_addc_co_u32_e32 v49, vcc, 0, v45, vcc
	global_load_ushort v69, v[70:71], off
	global_load_ushort v76, v[70:71], off offset:3072
	global_load_ushort v77, v[72:73], off offset:3072
	global_load_ushort v92, v[48:49], off offset:3072
	v_mul_f32_e32 v24, 0xbfb8aa3b, v57
	v_exp_f32_e32 v53, v24
	v_pk_mul_f32 v[24:25], v[26:27], v[74:75]
	v_add_f32_e32 v26, 1.0, v37
	v_mul_f32_e32 v37, v9, v54
	v_fmac_f32_e32 v37, v5, v52
	v_fmac_f32_e32 v37, v7, v60
	v_fmac_f32_e32 v37, v105, v68
	v_mul_f32_e32 v39, 0xbfb8aa3b, v37
	v_exp_f32_e32 v39, v39
	v_add_f32_e32 v27, 1.0, v53
	v_mov_b32_e32 v53, 0
	v_rcp_f32_e32 v26, v26
	v_rcp_f32_e32 v27, v27
	v_mul_f32_e32 v91, v46, v47
	global_load_ushort v104, v[48:49], off
	global_load_ushort v47, v[72:73], off offset:1024
	global_load_ushort v107, v[72:73], off
	global_load_ushort v78, v[70:71], off offset:1024
	v_pk_mul_f32 v[24:25], v[24:25], s[6:7]
	v_pk_mul_f32 v[26:27], v[56:57], v[26:27]
	v_readlane_b32 s6, v102, 4
	v_readlane_b32 s7, v102, 5
	v_pk_mul_f32 v[26:27], v[26:27], s[8:9]
	s_waitcnt vmcnt(1) lgkmcnt(0)
	v_lshlrev_b32_e32 v100, 16, v33
	v_add_f32_e32 v33, 1.0, v39
	v_rcp_f32_e32 v52, v33
	v_fmac_f32_e32 v123, v7, v100
	v_mul_f32_e32 v52, v37, v52
	v_mul_f32_e32 v37, v52, v52
	v_lshlrev_b32_e32 v33, 16, v69
	s_nop 0
	v_mov_b32_dpp v53, v37 quad_perm:[1,0,3,2] row_mask:0xf bank_mask:0xf
	v_fmac_f32_e32 v53, v52, v52
	v_lshlrev_b32_e32 v41, 16, v76
	v_fmac_f32_e32 v123, v105, v41
	v_add_f32_dpp v37, v53, v53 quad_perm:[2,3,0,1] row_mask:0xf bank_mask:0xf bound_ctrl:1
	v_mov_b32_e32 v53, 0
	v_lshlrev_b32_e32 v39, 16, v77
	v_add_f32_dpp v37, v37, v37 row_half_mirror row_mask:0xf bank_mask:0xf bound_ctrl:1
	v_mul_f32_e32 v132, v9, v39
	v_fmac_f32_e32 v132, v5, v41
	v_add_f32_dpp v37, v37, v37 row_mirror row_mask:0xf bank_mask:0xf bound_ctrl:1
	s_nop 1
	v_mov_b32_dpp v53, v37 row_bcast:15 row_mask:0xa bank_mask:0xf
	v_add_f32_e32 v37, v37, v53
	v_mov_b32_e32 v53, 0
	s_nop 1
	v_mov_b32_dpp v53, v37 row_bcast:31 row_mask:0xc bank_mask:0xf
	v_add_f32_e32 v37, v37, v53
	s_nop 0
	v_readlane_b32 s2, v37, 63
	s_nop 1
	v_add_f32_e32 v37, s2, v86
	v_rsq_f32_e32 v53, v37
	s_mov_b32 s2, 0xb000
	v_add_co_u32_e32 v56, vcc, s2, v44
	v_readlane_b32 s2, v3, 4
	s_nop 0
	v_addc_co_u32_e32 v57, vcc, 0, v45, vcc
	global_load_ushort v79, v[56:57], off offset:1024
	global_load_ushort v97, v[56:57], off
	global_load_ushort v99, v[48:49], off offset:1024
	v_pk_mul_f32 v[48:49], v[14:15], v[30:31]
	v_mul_f32_e32 v30, v52, v53
	v_xor_b32_e32 v31, 64, v65
	v_mul_f32_e32 v30, 0x3e000000, v30
	v_or_b32_e32 v31, v31, v64
	v_cvt_pk_bf16_f32 v30, v30, s0
	v_add_u32_e32 v118, s51, v31
	ds_write_b16 v118, v30 offset:512
	v_lshlrev_b32_e32 v31, 16, v59
	v_lshlrev_b32_e32 v30, 16, v63
	v_pk_mov_b32 v[52:53], v[28:29], v[30:31] op_sel:[1,0]
	v_add_f32_e32 v48, v48, v49
	v_pk_mul_f32 v[70:71], v[10:11], v[52:53]
	v_mul_f32_e32 v59, v9, v60
	v_add_f32_e32 v48, v48, v70
	v_add_f32_e32 v48, v48, v71
	v_mul_f32_e32 v49, 0xbfb8aa3b, v48
	v_exp_f32_e32 v49, v49
	v_fmac_f32_e32 v59, v5, v54
	v_mov_b32_e32 v54, 0
	v_pk_mul_f32 v[28:29], v[14:15], v[28:29]
	v_add_f32_e32 v49, 1.0, v49
	v_rcp_f32_e32 v49, v49
	v_mov_b32_e32 v71, s2
	v_fmac_f32_e32 v59, v7, v68
	v_add_f32_e32 v28, v28, v29
	v_mul_f32_e32 v48, v48, v49
	v_mul_f32_e32 v49, v48, v48
	v_fmac_f32_e32 v59, v105, v32
	v_mul_f32_e32 v29, 0xbfb8aa3b, v59
	v_mov_b32_dpp v54, v49 quad_perm:[1,0,3,2] row_mask:0xf bank_mask:0xf
	v_fmac_f32_e32 v54, v48, v48
	v_exp_f32_e32 v29, v29
	v_lshlrev_b32_e32 v37, 16, v92
	v_add_f32_dpp v49, v54, v54 quad_perm:[2,3,0,1] row_mask:0xf bank_mask:0xf bound_ctrl:1
	v_mov_b32_e32 v54, 0
	v_add_f32_e32 v29, 1.0, v29
	v_add_f32_dpp v49, v49, v49 row_half_mirror row_mask:0xf bank_mask:0xf bound_ctrl:1
	v_rcp_f32_e32 v29, v29
	v_fmac_f32_e32 v132, v7, v37
	v_add_f32_dpp v49, v49, v49 row_mirror row_mask:0xf bank_mask:0xf bound_ctrl:1
	v_mul_f32_e32 v29, v59, v29
	s_nop 0
	v_mov_b32_dpp v54, v49 row_bcast:15 row_mask:0xa bank_mask:0xf
	v_add_f32_e32 v49, v49, v54
	v_mov_b32_e32 v54, 0
	s_nop 1
	v_mov_b32_dpp v54, v49 row_bcast:31 row_mask:0xc bank_mask:0xf
	v_add_f32_e32 v49, v49, v54
	s_nop 0
	v_readlane_b32 s3, v49, 63
	s_nop 1
	v_add_f32_e32 v49, s3, v86
	v_rsq_f32_e32 v70, v49
	v_mov_b32_e32 v49, s6
	v_readlane_b32 s3, v3, 6
	v_pk_mul_f32 v[48:49], v[48:49], v[70:71]
	v_pk_mul_f32 v[70:71], v[10:11], v[30:31]
	v_mul_f32_e32 v92, v48, v49
	v_add_f32_e32 v28, v28, v70
	v_add_f32_e32 v28, v28, v71
	v_mul_f32_e32 v54, 0xbfb8aa3b, v28
	v_exp_f32_e32 v54, v54
	v_mov_b32_e32 v49, 0
	v_cvt_pk_bf16_f32 v63, v48, s0
	ds_write_b16 v118, v63 offset:4608
	v_add_f32_e32 v54, 1.0, v54
	v_rcp_f32_e32 v54, v54
	v_mov_b32_e32 v71, s7
	v_mul_f32_e32 v70, v28, v54
	v_mul_f32_e32 v28, v29, v29
	s_nop 1
	v_mov_b32_dpp v49, v28 quad_perm:[1,0,3,2] row_mask:0xf bank_mask:0xf
	v_fmac_f32_e32 v49, v29, v29
	s_nop 1
	v_add_f32_dpp v28, v49, v49 quad_perm:[2,3,0,1] row_mask:0xf bank_mask:0xf bound_ctrl:1
	v_mov_b32_e32 v49, 0
	s_nop 0
	v_add_f32_dpp v28, v28, v28 row_half_mirror row_mask:0xf bank_mask:0xf bound_ctrl:1
	s_nop 1
	v_add_f32_dpp v28, v28, v28 row_mirror row_mask:0xf bank_mask:0xf bound_ctrl:1
	s_nop 1
	v_mov_b32_dpp v49, v28 row_bcast:15 row_mask:0xa bank_mask:0xf
	v_add_f32_e32 v28, v28, v49
	v_mov_b32_e32 v49, 0
	s_nop 1
	v_mov_b32_dpp v49, v28 row_bcast:31 row_mask:0xc bank_mask:0xf
	v_add_f32_e32 v28, v28, v49
	v_mov_b32_e32 v49, 0
	v_readlane_b32 s2, v28, 63
	v_mul_f32_e32 v28, v70, v70
	s_nop 0
	v_add_f32_e32 v54, s2, v86
	v_mov_b32_dpp v49, v28 quad_perm:[1,0,3,2] row_mask:0xf bank_mask:0xf
	v_fmac_f32_e32 v49, v70, v70
	v_rsq_f32_e32 v54, v54
	s_nop 0
	v_add_f32_dpp v28, v49, v49 quad_perm:[2,3,0,1] row_mask:0xf bank_mask:0xf bound_ctrl:1
	v_mov_b32_e32 v49, 0
	s_nop 0
	v_add_f32_dpp v28, v28, v28 row_half_mirror row_mask:0xf bank_mask:0xf bound_ctrl:1
	s_nop 1
	v_add_f32_dpp v28, v28, v28 row_mirror row_mask:0xf bank_mask:0xf bound_ctrl:1
	s_nop 1
	v_mov_b32_dpp v49, v28 row_bcast:15 row_mask:0xa bank_mask:0xf
	v_add_f32_e32 v28, v28, v49
	v_mov_b32_e32 v49, 0
	s_nop 1
	v_mov_b32_dpp v49, v28 row_bcast:31 row_mask:0xc bank_mask:0xf
	v_add_f32_e32 v28, v28, v49
	v_mul_f32_e32 v49, v9, v68
	v_readlane_b32 s2, v28, 63
	v_mul_f32_e32 v28, v29, v54
	v_mul_f32_e32 v28, 0x3e000000, v28
	v_add_f32_e32 v29, s2, v86
	v_rsq_f32_e32 v72, v29
	v_xor_b32_e32 v29, 0x50, v65
	v_or_b32_e32 v29, v29, v64
	v_cvt_pk_bf16_f32 v28, v28, s0
	v_add_u32_e32 v119, s51, v29
	ds_write_b16 v119, v28 offset:640
	v_lshlrev_b32_e32 v54, 16, v58
	v_pk_mul_f32 v[28:29], v[4:5], v[34:35] op_sel_hi:[0,1]
	v_pk_fma_f32 v[28:29], v[2:3], v[50:51], v[28:29] op_sel_hi:[0,1,1]
	v_pk_mov_b32 v[58:59], v[34:35], v[54:55] op_sel:[1,0]
	v_fmac_f32_e32 v49, v5, v60
	v_pk_fma_f32 v[28:29], v[6:7], v[58:59], v[28:29] op_sel_hi:[0,1,1]
	v_pk_fma_f32 v[28:29], v[8:9], v[54:55], v[28:29] op_sel_hi:[0,1,1]
	v_mul_f32_e32 v34, 0xbfb8aa3b, v28
	v_mul_f32_e32 v35, 0xbfb8aa3b, v29
	v_exp_f32_e32 v34, v34
	v_exp_f32_e32 v35, v35
	v_fmac_f32_e32 v49, v7, v32
	v_fmac_f32_e32 v49, v105, v103
	v_add_f32_e32 v34, 1.0, v34
	v_add_f32_e32 v35, 1.0, v35
	v_mul_f32_e32 v50, 0xbfb8aa3b, v49
	v_rcp_f32_e32 v34, v34
	v_rcp_f32_e32 v35, v35
	v_exp_f32_e32 v50, v50
	v_mov_b32_e32 v60, 0
	v_readlane_b32 s2, v3, 5
	v_pk_mul_f32 v[28:29], v[28:29], v[34:35]
	v_add_f32_e32 v34, 1.0, v50
	v_rcp_f32_e32 v34, v34
	v_mov_b32_e32 v73, s2
	v_pk_mul_f32 v[50:51], v[70:71], v[72:73]
	v_pk_mul_f32 v[28:29], v[28:29], s[6:7]
	v_mul_f32_e32 v49, v49, v34
	v_mul_f32_e32 v34, v49, v49
	v_cvt_pk_bf16_f32 v35, v50, s0
	ds_write_b16 v119, v35 offset:4736
	v_mov_b32_dpp v60, v34 quad_perm:[1,0,3,2] row_mask:0xf bank_mask:0xf
	v_fmac_f32_e32 v60, v49, v49
	v_mul_f32_e32 v93, v50, v51
	v_xor_b32_e32 v51, 0x60, v65
	v_add_f32_dpp v34, v60, v60 quad_perm:[2,3,0,1] row_mask:0xf bank_mask:0xf bound_ctrl:1
	v_mov_b32_e32 v60, 0
	v_or_b32_e32 v51, v51, v64
	v_add_f32_dpp v34, v34, v34 row_half_mirror row_mask:0xf bank_mask:0xf bound_ctrl:1
	v_add_u32_e32 v124, s51, v51
	v_mov_b32_e32 v51, 0
	v_add_f32_dpp v34, v34, v34 row_mirror row_mask:0xf bank_mask:0xf bound_ctrl:1
	v_readlane_b32 s6, v102, 12
	v_readlane_b32 s7, v102, 13
	v_mov_b32_dpp v60, v34 row_bcast:15 row_mask:0xa bank_mask:0xf
	v_add_f32_e32 v34, v34, v60
	v_mov_b32_e32 v60, 0
	s_nop 1
	v_mov_b32_dpp v60, v34 row_bcast:31 row_mask:0xc bank_mask:0xf
	v_add_f32_e32 v34, v34, v60
	s_nop 0
	v_readlane_b32 s2, v34, 63
	s_nop 1
	v_add_f32_e32 v34, s2, v86
	v_rsq_f32_e32 v60, v34
	v_pk_mul_f32 v[34:35], v[14:15], v[52:53]
	v_readlane_b32 s2, v102, 6
	v_add_f32_e32 v34, v34, v35
	v_mul_f32_e32 v49, v49, v60
	v_lshlrev_b32_e32 v60, 16, v62
	v_pk_mov_b32 v[62:63], v[30:31], v[60:61] op_sel:[1,0]
	v_mul_f32_e32 v49, 0x3e000000, v49
	v_pk_mul_f32 v[52:53], v[10:11], v[62:63]
	v_cvt_pk_bf16_f32 v49, v49, s0
	v_add_f32_e32 v34, v34, v52
	v_add_f32_e32 v34, v34, v53
	v_mul_f32_e32 v35, 0xbfb8aa3b, v34
	v_exp_f32_e32 v35, v35
	ds_write_b16 v124, v49 offset:768
	v_mul_f32_e32 v49, v9, v32
	v_fmac_f32_e32 v49, v5, v68
	v_add_f32_e32 v35, 1.0, v35
	v_rcp_f32_e32 v35, v35
	v_pk_mul_f32 v[30:31], v[14:15], v[30:31]
	v_mov_b32_e32 v53, s3
	v_fmac_f32_e32 v49, v7, v103
	v_mul_f32_e32 v34, v34, v35
	v_mul_f32_e32 v35, v34, v34
	v_add_f32_e32 v30, v30, v31
	v_fmac_f32_e32 v49, v105, v98
	v_mov_b32_dpp v51, v35 quad_perm:[1,0,3,2] row_mask:0xf bank_mask:0xf
	v_fmac_f32_e32 v51, v34, v34
	v_mul_f32_e32 v31, 0xbfb8aa3b, v49
	v_exp_f32_e32 v31, v31
	v_add_f32_dpp v35, v51, v51 quad_perm:[2,3,0,1] row_mask:0xf bank_mask:0xf bound_ctrl:1
	v_mov_b32_e32 v51, 0
	v_pk_mul_f32 v[76:77], v[14:15], v[62:63]
	v_add_f32_dpp v35, v35, v35 row_half_mirror row_mask:0xf bank_mask:0xf bound_ctrl:1
	v_add_f32_e32 v31, 1.0, v31
	v_rcp_f32_e32 v31, v31
	v_add_f32_dpp v35, v35, v35 row_mirror row_mask:0xf bank_mask:0xf bound_ctrl:1
	v_mul_f32_e32 v31, v49, v31
	s_nop 0
	v_mov_b32_dpp v51, v35 row_bcast:15 row_mask:0xa bank_mask:0xf
	v_add_f32_e32 v35, v35, v51
	v_mov_b32_e32 v51, 0
	s_nop 1
	v_mov_b32_dpp v51, v35 row_bcast:31 row_mask:0xc bank_mask:0xf
	v_add_f32_e32 v35, v35, v51
	s_nop 0
	v_readlane_b32 s4, v35, 63
	s_nop 1
	v_add_f32_e32 v35, s4, v86
	v_rsq_f32_e32 v52, v35
	v_mov_b32_e32 v35, s2
	v_readlane_b32 s4, v3, 7
	v_pk_mul_f32 v[52:53], v[34:35], v[52:53]
	v_pk_mul_f32 v[34:35], v[10:11], v[60:61]
	v_mul_f32_e32 v94, v52, v53
	v_add_f32_e32 v30, v30, v34
	v_add_f32_e32 v30, v30, v35
	v_mul_f32_e32 v34, 0xbfb8aa3b, v30
	v_exp_f32_e32 v34, v34
	v_cvt_pk_bf16_f32 v35, v52, s0
	ds_write_b16 v124, v35 offset:4864
	v_mov_b32_e32 v71, s4
	v_add_f32_e32 v34, 1.0, v34
	v_rcp_f32_e32 v34, v34
	v_readlane_b32 s4, v3, 9
	v_mul_f32_e32 v68, v30, v34
	v_mul_f32_e32 v30, v31, v31
	v_mov_b32_e32 v34, 0
	s_nop 1
	v_mov_b32_dpp v34, v30 quad_perm:[1,0,3,2] row_mask:0xf bank_mask:0xf
	v_fmac_f32_e32 v34, v31, v31
	s_nop 1
	v_add_f32_dpp v30, v34, v34 quad_perm:[2,3,0,1] row_mask:0xf bank_mask:0xf bound_ctrl:1
	v_mov_b32_e32 v34, 0
	s_nop 0
	v_add_f32_dpp v30, v30, v30 row_half_mirror row_mask:0xf bank_mask:0xf bound_ctrl:1
	s_nop 1
	v_add_f32_dpp v30, v30, v30 row_mirror row_mask:0xf bank_mask:0xf bound_ctrl:1
	s_nop 1
	v_mov_b32_dpp v34, v30 row_bcast:15 row_mask:0xa bank_mask:0xf
	v_add_f32_e32 v30, v30, v34
	v_mov_b32_e32 v34, 0
	s_nop 1
	v_mov_b32_dpp v34, v30 row_bcast:31 row_mask:0xc bank_mask:0xf
	v_add_f32_e32 v30, v30, v34
	v_mov_b32_e32 v34, 0
	v_readlane_b32 s3, v30, 63
	v_mul_f32_e32 v30, v68, v68
	s_nop 0
	v_add_f32_e32 v35, s3, v86
	v_mov_b32_dpp v34, v30 quad_perm:[1,0,3,2] row_mask:0xf bank_mask:0xf
	v_fmac_f32_e32 v34, v68, v68
	v_rsq_f32_e32 v35, v35
	s_nop 0
	v_add_f32_dpp v30, v34, v34 quad_perm:[2,3,0,1] row_mask:0xf bank_mask:0xf bound_ctrl:1
	v_mov_b32_e32 v34, 0
	s_nop 0
	v_add_f32_dpp v30, v30, v30 row_half_mirror row_mask:0xf bank_mask:0xf bound_ctrl:1
	s_nop 1
	v_add_f32_dpp v30, v30, v30 row_mirror row_mask:0xf bank_mask:0xf bound_ctrl:1
	s_nop 1
	v_mov_b32_dpp v34, v30 row_bcast:15 row_mask:0xa bank_mask:0xf
	v_add_f32_e32 v30, v30, v34
	v_mov_b32_e32 v34, 0
	s_nop 1
	v_mov_b32_dpp v34, v30 row_bcast:31 row_mask:0xc bank_mask:0xf
	v_add_f32_e32 v30, v30, v34
	v_lshlrev_b32_e32 v34, 16, v66
	v_readlane_b32 s3, v30, 63
	v_mul_f32_e32 v30, v31, v35
	v_mul_f32_e32 v30, 0x3e000000, v30
	v_add_f32_e32 v31, s3, v86
	v_cvt_pk_bf16_f32 v49, v30, s0
	v_xor_b32_e32 v30, 0x70, v65
	v_rsq_f32_e32 v70, v31
	v_or_b32_e32 v51, v30, v64
	v_lshlrev_b32_e32 v35, 16, v67
	v_pk_mul_f32 v[30:31], v[4:5], v[54:55] op_sel_hi:[0,1]
	v_pk_fma_f32 v[30:31], v[2:3], v[58:59], v[30:31] op_sel_hi:[0,1,1]
	v_pk_mov_b32 v[58:59], v[54:55], v[34:35] op_sel:[1,0]
	v_add_u32_e32 v125, s51, v51
	v_pk_fma_f32 v[30:31], v[6:7], v[58:59], v[30:31] op_sel_hi:[0,1,1]
	v_pk_fma_f32 v[30:31], v[8:9], v[34:35], v[30:31] op_sel_hi:[0,1,1]
	v_mul_f32_e32 v53, 0xbfb8aa3b, v30
	v_exp_f32_e32 v53, v53
	v_mul_f32_e32 v54, 0xbfb8aa3b, v31
	v_exp_f32_e32 v55, v54
	v_readlane_b32 s3, v102, 7
	v_add_f32_e32 v51, 1.0, v53
	v_rcp_f32_e32 v54, v51
	v_add_f32_e32 v51, 1.0, v55
	v_rcp_f32_e32 v55, v51
	v_mov_b32_e32 v69, s3
	ds_write_b16 v125, v49 offset:896
	v_mov_b32_e32 v51, 0
	v_pk_mul_f32 v[30:31], v[30:31], v[54:55]
	v_pk_mul_f32 v[54:55], v[68:69], v[70:71]
	v_pk_mul_f32 v[30:31], v[30:31], s[2:3]
	v_cvt_pk_bf16_f32 v49, v54, s0
	ds_write_b16 v125, v49 offset:4992
	v_mul_f32_e32 v49, v9, v103
	v_fmac_f32_e32 v49, v5, v32
	v_fmac_f32_e32 v49, v7, v98
	v_fmac_f32_e32 v49, v105, v100
	v_mul_f32_e32 v32, 0xbfb8aa3b, v49
	v_exp_f32_e32 v32, v32
	s_mov_b64 s[2:3], 0xc000
	v_lshl_add_u64 v[64:65], v[44:45], 0, s[2:3]
	s_mov_b64 s[2:3], 0xd000
	v_add_f32_e32 v32, 1.0, v32
	v_rcp_f32_e32 v32, v32
	v_lshl_add_u64 v[68:69], v[44:45], 0, s[2:3]
	s_mov_b32 s2, 0xc000
	v_add_co_u32_e32 v70, vcc, s2, v44
	v_mul_f32_e32 v49, v49, v32
	v_mul_f32_e32 v32, v49, v49
	s_mov_b64 s[2:3], 0xe000
	v_addc_co_u32_e32 v71, vcc, 0, v45, vcc
	v_mov_b32_dpp v51, v32 quad_perm:[1,0,3,2] row_mask:0xf bank_mask:0xf
	v_fmac_f32_e32 v51, v49, v49
	v_lshl_add_u64 v[72:73], v[44:45], 0, s[2:3]
	s_mov_b32 s2, 0xd000
	v_add_f32_dpp v32, v51, v51 quad_perm:[2,3,0,1] row_mask:0xf bank_mask:0xf bound_ctrl:1
	v_mov_b32_e32 v51, 0
	v_add_co_u32_e32 v74, vcc, s2, v44
	v_add_f32_dpp v32, v32, v32 row_half_mirror row_mask:0xf bank_mask:0xf bound_ctrl:1
	s_mov_b64 s[2:3], 0xf000
	v_addc_co_u32_e32 v75, vcc, 0, v45, vcc
	v_add_f32_dpp v32, v32, v32 row_mirror row_mask:0xf bank_mask:0xf bound_ctrl:1
	v_lshl_add_u64 v[120:121], v[44:45], 0, s[2:3]
	s_mov_b32 s2, 0xe000
	v_mov_b32_dpp v51, v32 row_bcast:15 row_mask:0xa bank_mask:0xf
	v_add_f32_e32 v32, v32, v51
	v_mov_b32_e32 v51, 0
	v_add_co_u32_e32 v128, vcc, s2, v44
	s_nop 0
	v_mov_b32_dpp v51, v32 row_bcast:31 row_mask:0xc bank_mask:0xf
	v_add_f32_e32 v32, v32, v51
	v_addc_co_u32_e32 v129, vcc, 0, v45, vcc
	v_readlane_b32 s2, v32, 63
	v_mul_f32_e32 v95, v54, v55
	s_mov_b32 s3, 0x12000
	v_add_f32_e32 v32, s2, v86
	v_rsq_f32_e32 v51, v32
	s_mov_b32 s2, 0xf000
	v_add_co_u32_e32 v66, vcc, s2, v44
	v_mul_f32_e32 v49, v49, v51
	v_mul_f32_e32 v49, 0x3e000000, v49
	v_cvt_pk_bf16_f32 v113, v49, s0
	v_mul_f32_e32 v49, 0xbfb8aa3b, v123
	v_exp_f32_e32 v51, v49
	global_load_ushort v110, v[56:57], off offset:3072
	global_load_ushort v111, v[70:71], off offset:3072
	global_load_ushort v112, v[74:75], off offset:3072
	global_load_ushort v106, v[74:75], off
	global_load_ushort v49, v[72:73], off offset:1024
	global_load_ushort v53, v[70:71], off
	global_load_ushort v122, v[64:65], off offset:1024
	global_load_ushort v126, v[68:69], off offset:1024
	v_mov_b32_e32 v64, 0
	v_mov_b32_e32 v32, v61
	v_add_f32_e32 v51, 1.0, v51
	v_rcp_f32_e32 v56, v51
	v_pk_mul_f32 v[62:63], v[10:11], v[32:33]
	v_mul_f32_e32 v61, v12, v61
	v_mul_f32_e32 v69, v10, v33
	v_mul_f32_e32 v56, v123, v56
	v_mul_f32_e32 v57, v56, v56
	v_mov_b32_e32 v68, v62
	v_lshlrev_b32_e32 v62, 16, v107
	v_mov_b32_dpp v64, v57 quad_perm:[1,0,3,2] row_mask:0xf bank_mask:0xf
	v_fmac_f32_e32 v64, v56, v56
	v_mul_f32_e32 v70, v9, v100
	v_fmac_f32_e32 v70, v5, v98
	v_add_f32_dpp v57, v64, v64 quad_perm:[2,3,0,1] row_mask:0xf bank_mask:0xf bound_ctrl:1
	v_mov_b32_e32 v64, 0
	v_fmac_f32_e32 v70, v7, v41
	v_add_f32_dpp v57, v57, v57 row_half_mirror row_mask:0xf bank_mask:0xf bound_ctrl:1
	v_fmac_f32_e32 v70, v105, v39
	v_addc_co_u32_e32 v67, vcc, 0, v45, vcc
	v_add_f32_dpp v57, v57, v57 row_mirror row_mask:0xf bank_mask:0xf bound_ctrl:1
	global_load_ushort v65, v[128:129], off offset:3072
	global_load_ushort v55, v[66:67], off
	global_load_ushort v103, v[128:129], off
	global_load_ushort v51, v[120:121], off offset:1024
	v_mov_b32_dpp v64, v57 row_bcast:15 row_mask:0xa bank_mask:0xf
	v_add_f32_e32 v57, v57, v64
	v_mov_b32_e32 v64, 0
	ds_write_b16 v114, v113 offset:1024
	s_waitcnt vmcnt(3) lgkmcnt(0)
	v_lshlrev_b32_e32 v107, 16, v111
	v_mov_b32_dpp v64, v57 row_bcast:31 row_mask:0xc bank_mask:0xf
	v_add_f32_e32 v57, v57, v64
	v_lshlrev_b32_e32 v121, 16, v112
	v_readlane_b32 s2, v57, 63
	s_nop 1
	v_add_f32_e32 v57, s2, v86
	v_rsq_f32_e32 v64, v57
	v_mul_f32_e32 v57, v13, v60
	v_mov_b32_e32 v60, v77
	v_mul_f32_e32 v56, v56, v64
	v_mul_f32_e32 v64, 0x3e000000, v56
	v_mov_b32_e32 v56, v76
	v_pk_add_f32 v[56:57], v[56:57], v[60:61]
	v_mul_f32_e32 v61, v11, v62
	v_pk_add_f32 v[56:57], v[56:57], v[68:69]
	v_mov_b32_e32 v60, v63
	v_pk_add_f32 v[56:57], v[56:57], v[60:61]
	v_mov_b32_e32 v63, 0
	v_mul_f32_e32 v60, 0xbfb8aa3b, v56
	v_mul_f32_e32 v61, 0xbfb8aa3b, v57
	v_exp_f32_e32 v60, v60
	v_exp_f32_e32 v61, v61
	v_pk_mul_f32 v[68:69], v[14:15], v[32:33]
	v_cvt_pk_bf16_f32 v64, v64, s0
	v_add_f32_e32 v60, 1.0, v60
	v_add_f32_e32 v61, 1.0, v61
	v_rcp_f32_e32 v60, v60
	v_rcp_f32_e32 v61, v61
	v_mul_f32_e32 v33, v13, v33
	v_mov_b32_e32 v76, 0
	v_pk_mul_f32 v[56:57], v[56:57], v[60:61]
	s_nop 0
	v_pk_mul_f32 v[60:61], v[56:57], v[56:57]
	s_nop 1
	v_add_f32_dpp v60, v60, v60 quad_perm:[1,0,3,2] row_mask:0xf bank_mask:0xf bound_ctrl:1
	v_add_f32_dpp v61, v61, v61 quad_perm:[1,0,3,2] row_mask:0xf bank_mask:0xf bound_ctrl:1
	s_nop 0
	v_add_f32_dpp v60, v60, v60 quad_perm:[2,3,0,1] row_mask:0xf bank_mask:0xf bound_ctrl:1
	v_add_f32_dpp v61, v61, v61 quad_perm:[2,3,0,1] row_mask:0xf bank_mask:0xf bound_ctrl:1
	s_nop 0
	v_add_f32_dpp v60, v60, v60 row_half_mirror row_mask:0xf bank_mask:0xf bound_ctrl:1
	v_add_f32_dpp v61, v61, v61 row_half_mirror row_mask:0xf bank_mask:0xf bound_ctrl:1
	s_nop 0
	v_add_f32_dpp v60, v60, v60 row_mirror row_mask:0xf bank_mask:0xf bound_ctrl:1
	v_add_f32_dpp v61, v61, v61 row_mirror row_mask:0xf bank_mask:0xf bound_ctrl:1
	s_nop 0
	v_mov_b32_dpp v63, v60 row_bcast:15 row_mask:0xa bank_mask:0xf
	v_add_f32_e32 v60, v60, v63
	v_mov_b32_e32 v63, 0
	s_nop 1
	v_mov_b32_dpp v63, v60 row_bcast:31 row_mask:0xc bank_mask:0xf
	v_add_f32_e32 v60, v60, v63
	v_mov_b32_e32 v63, 0
	v_readlane_b32 s2, v60, 63
	s_nop 0
	v_mov_b32_dpp v63, v61 row_bcast:15 row_mask:0xa bank_mask:0xf
	v_add_f32_e32 v61, v61, v63
	v_mov_b32_e32 v63, 0
	v_add_f32_e32 v60, s2, v86
	v_rsq_f32_e32 v60, v60
	v_mov_b32_dpp v63, v61 row_bcast:31 row_mask:0xc bank_mask:0xf
	v_add_f32_e32 v61, v61, v63
	v_mul_f32_e32 v63, 0xbfb8aa3b, v70
	v_exp_f32_e32 v71, v63
	v_readlane_b32 s2, v61, 63
	v_lshlrev_b32_e32 v63, 16, v104
	v_mul_f32_e32 v73, v10, v63
	v_add_f32_e32 v61, s2, v86
	v_rsq_f32_e32 v61, v61
	v_add_f32_e32 v32, 1.0, v71
	v_rcp_f32_e32 v32, v32
	v_mul_f32_e32 v71, v12, v62
	v_pk_mul_f32 v[56:57], v[56:57], v[60:61]
	v_mov_b32_e32 v61, 0
	v_cvt_pk_bf16_f32 v60, v56, s0
	v_mul_f32_e32 v32, v70, v32
	ds_write_b16 v114, v60 offset:5120
	ds_write_b16 v116, v64 offset:1152
	v_mul_f32_e32 v60, v32, v32
	v_lshlrev_b32_e32 v104, 16, v110
	v_lshlrev_b32_e32 v110, 16, v65
	v_mov_b32_dpp v61, v60 quad_perm:[1,0,3,2] row_mask:0xf bank_mask:0xf
	v_fmac_f32_e32 v61, v32, v32
	v_fmac_f32_e32 v132, v105, v104
	v_cvt_pk_bf16_f32 v38, v56, v57
	v_add_f32_dpp v60, v61, v61 quad_perm:[2,3,0,1] row_mask:0xf bank_mask:0xf bound_ctrl:1
	v_mov_b32_e32 v61, 0
	s_nop 0
	v_add_f32_dpp v60, v60, v60 row_half_mirror row_mask:0xf bank_mask:0xf bound_ctrl:1
	s_nop 1
	v_add_f32_dpp v60, v60, v60 row_mirror row_mask:0xf bank_mask:0xf bound_ctrl:1
	s_nop 1
	v_mov_b32_dpp v61, v60 row_bcast:15 row_mask:0xa bank_mask:0xf
	v_add_f32_e32 v60, v60, v61
	v_mov_b32_e32 v61, 0
	s_nop 1
	v_mov_b32_dpp v61, v60 row_bcast:31 row_mask:0xc bank_mask:0xf
	v_add_f32_e32 v60, v60, v61
	s_nop 0
	v_readlane_b32 s2, v60, 63
	s_nop 1
	v_add_f32_e32 v60, s2, v86
	v_rsq_f32_e32 v64, v60
	v_cvt_pk_bf16_f32 v60, v57, s0
	ds_write_b16 v116, v60 offset:5248
	v_pk_mul_f32 v[60:61], v[10:11], v[62:63]
	v_mul_f32_e32 v32, v32, v64
	v_mul_f32_e32 v64, v9, v41
	v_fmac_f32_e32 v64, v5, v100
	v_fmac_f32_e32 v64, v7, v39
	v_fmac_f32_e32 v64, v105, v37
	v_mul_f32_e32 v70, 0xbfb8aa3b, v64
	v_exp_f32_e32 v70, v70
	v_mul_f32_e32 v32, 0x3e000000, v32
	v_cvt_pk_bf16_f32 v32, v32, s0
	ds_write_b16 v115, v32 offset:1280
	v_add_f32_e32 v32, 1.0, v70
	v_rcp_f32_e32 v32, v32
	v_mov_b32_e32 v70, v69
	v_mov_b32_e32 v72, v60
	v_mul_f32_e32 v41, 0xbfb8aa3b, v132
	v_mul_f32_e32 v74, v64, v32
	v_mul_f32_e32 v32, v74, v74
	v_mov_b32_e32 v64, 0
	v_exp_f32_e32 v41, v41
	s_nop 0
	v_mov_b32_dpp v64, v32 quad_perm:[1,0,3,2] row_mask:0xf bank_mask:0xf
	v_fmac_f32_e32 v64, v74, v74
	v_add_f32_e32 v41, 1.0, v41
	v_rcp_f32_e32 v41, v41
	v_add_f32_dpp v32, v64, v64 quad_perm:[2,3,0,1] row_mask:0xf bank_mask:0xf bound_ctrl:1
	v_mov_b32_e32 v64, 0
	v_mul_f32_e32 v41, v132, v41
	v_add_f32_dpp v32, v32, v32 row_half_mirror row_mask:0xf bank_mask:0xf bound_ctrl:1
	s_nop 1
	v_add_f32_dpp v32, v32, v32 row_mirror row_mask:0xf bank_mask:0xf bound_ctrl:1
	s_nop 1
	v_mov_b32_dpp v64, v32 row_bcast:15 row_mask:0xa bank_mask:0xf
	v_add_f32_e32 v75, v32, v64
	v_mov_b32_e32 v32, v68
	v_pk_add_f32 v[32:33], v[32:33], v[70:71]
	v_lshlrev_b32_e32 v64, 16, v97
	v_pk_add_f32 v[32:33], v[32:33], v[72:73]
	v_mul_f32_e32 v69, v11, v64
	v_mov_b32_e32 v68, v61
	v_pk_add_f32 v[32:33], v[32:33], v[68:69]
	v_mov_b32_e32 v69, 0
	v_mul_f32_e32 v60, 0xbfb8aa3b, v32
	v_mul_f32_e32 v61, 0xbfb8aa3b, v33
	v_exp_f32_e32 v60, v60
	v_exp_f32_e32 v61, v61
	v_mov_b32_dpp v76, v75 row_bcast:31 row_mask:0xc bank_mask:0xf
	v_add_f32_e32 v68, v75, v76
	v_add_f32_e32 v60, 1.0, v60
	v_add_f32_e32 v61, 1.0, v61
	v_rcp_f32_e32 v60, v60
	v_rcp_f32_e32 v61, v61
	v_readlane_b32 s2, v68, 63
	v_pk_mul_f32 v[32:33], v[32:33], v[60:61]
	s_nop 0
	v_pk_mul_f32 v[60:61], v[32:33], v[32:33]
	v_add_f32_e32 v68, s2, v86
	v_rsq_f32_e32 v68, v68
	v_add_f32_dpp v60, v60, v60 quad_perm:[1,0,3,2] row_mask:0xf bank_mask:0xf bound_ctrl:1
	v_add_f32_dpp v61, v61, v61 quad_perm:[1,0,3,2] row_mask:0xf bank_mask:0xf bound_ctrl:1
	v_mul_f32_e32 v68, v74, v68
	v_add_f32_dpp v60, v60, v60 quad_perm:[2,3,0,1] row_mask:0xf bank_mask:0xf bound_ctrl:1
	v_add_f32_dpp v61, v61, v61 quad_perm:[2,3,0,1] row_mask:0xf bank_mask:0xf bound_ctrl:1
	v_mul_f32_e32 v68, 0x3e000000, v68
	v_add_f32_dpp v60, v60, v60 row_half_mirror row_mask:0xf bank_mask:0xf bound_ctrl:1
	v_add_f32_dpp v61, v61, v61 row_half_mirror row_mask:0xf bank_mask:0xf bound_ctrl:1
	v_cvt_pk_bf16_f32 v68, v68, s0
	v_add_f32_dpp v60, v60, v60 row_mirror row_mask:0xf bank_mask:0xf bound_ctrl:1
	v_add_f32_dpp v61, v61, v61 row_mirror row_mask:0xf bank_mask:0xf bound_ctrl:1
	s_nop 0
	v_mov_b32_dpp v69, v60 row_bcast:15 row_mask:0xa bank_mask:0xf
	v_add_f32_e32 v60, v60, v69
	v_mov_b32_e32 v69, 0
	s_nop 1
	v_mov_b32_dpp v69, v60 row_bcast:31 row_mask:0xc bank_mask:0xf
	v_add_f32_e32 v60, v60, v69
	v_mov_b32_e32 v69, 0
	v_readlane_b32 s2, v60, 63
	s_nop 0
	v_mov_b32_dpp v69, v61 row_bcast:15 row_mask:0xa bank_mask:0xf
	v_add_f32_e32 v61, v61, v69
	v_mov_b32_e32 v69, 0
	v_add_f32_e32 v60, s2, v86
	v_rsq_f32_e32 v60, v60
	v_mov_b32_dpp v69, v61 row_bcast:31 row_mask:0xc bank_mask:0xf
	v_add_f32_e32 v61, v61, v69
	s_nop 0
	v_readlane_b32 s2, v61, 63
	s_nop 1
	v_add_f32_e32 v61, s2, v86
	v_rsq_f32_e32 v61, v61
	s_mov_b32 s2, 0x10000
	v_add_co_u32_e32 v72, vcc, s2, v44
	v_pk_mul_f32 v[60:61], v[32:33], v[60:61]
	s_nop 0
	v_addc_co_u32_e32 v73, vcc, 0, v45, vcc
	v_cvt_pk_bf16_f32 v32, v60, s0
	ds_write_b16 v115, v32 offset:5376
	ds_write_b16 v117, v68 offset:1408
	v_cvt_pk_bf16_f32 v32, v61, s0
	ds_write_b16 v117, v32 offset:5504
	s_mov_b32 s2, 0x11000
	v_add_co_u32_e32 v76, vcc, s2, v44
	v_pk_mul_f32 v[32:33], v[4:5], v[34:35] op_sel_hi:[0,1]
	s_nop 0
	v_addc_co_u32_e32 v77, vcc, 0, v45, vcc
	global_load_ushort v113, v[66:67], off offset:3072
	global_load_ushort v129, v[72:73], off offset:3072
	global_load_ushort v130, v[76:77], off offset:3072
	v_add_co_u32_e32 v74, vcc, s3, v44
	v_lshlrev_b32_e32 v67, 16, v47
	s_nop 0
	v_addc_co_u32_e32 v75, vcc, 0, v45, vcc
	global_load_ushort v131, v[74:75], off offset:3072
	v_lshlrev_b32_e32 v66, 16, v78
	v_pk_fma_f32 v[32:33], v[2:3], v[58:59], v[32:33] op_sel_hi:[0,1,1]
	v_pk_mov_b32 v[34:35], v[34:35], v[66:67] op_sel:[1,0]
	v_readlane_b32 s3, v3, 8
	v_pk_fma_f32 v[32:33], v[6:7], v[34:35], v[32:33] op_sel_hi:[0,1,1]
	v_pk_fma_f32 v[32:33], v[8:9], v[66:67], v[32:33] op_sel_hi:[0,1,1]
	v_mul_f32_e32 v47, 0xbfb8aa3b, v32
	v_exp_f32_e32 v47, v47
	v_mul_f32_e32 v58, 0xbfb8aa3b, v33
	v_exp_f32_e32 v59, v58
	v_mov_b32_e32 v65, s3
	v_add_f32_e32 v47, 1.0, v47
	v_rcp_f32_e32 v58, v47
	v_add_f32_e32 v47, 1.0, v59
	v_rcp_f32_e32 v59, v47
	v_readlane_b32 s3, v102, 9
	v_pk_mul_f32 v[68:69], v[4:5], v[66:67] op_sel_hi:[0,1]
	v_pk_fma_f32 v[34:35], v[2:3], v[34:35], v[68:69] op_sel_hi:[0,1,1]
	v_pk_mul_f32 v[32:33], v[32:33], v[58:59]
	v_mov_b32_e32 v58, s4
	v_mul_f32_e32 v58, s3, v58
	v_mul_f32_e32 v97, v57, v58
	v_lshlrev_b32_e32 v59, 16, v79
	v_lshlrev_b32_e32 v58, 16, v99
	v_pk_mov_b32 v[70:71], v[66:67], v[58:59] op_sel:[1,0]
	v_readlane_b32 s2, v102, 8
	v_pk_fma_f32 v[34:35], v[6:7], v[70:71], v[34:35] op_sel_hi:[0,1,1]
	v_pk_fma_f32 v[34:35], v[8:9], v[58:59], v[34:35] op_sel_hi:[0,1,1]
	v_mul_f32_e32 v47, s2, v65
	v_mul_f32_e32 v98, v56, v47
	v_mul_f32_e32 v47, 0xbfb8aa3b, v34
	v_exp_f32_e32 v47, v47
	v_mul_f32_e32 v65, 0xbfb8aa3b, v35
	v_exp_f32_e32 v65, v65
	v_pk_mul_f32 v[32:33], v[32:33], s[2:3]
	v_readlane_b32 s3, v3, 10
	v_add_f32_e32 v47, 1.0, v47
	v_readlane_b32 s2, v102, 10
	v_mov_b32_e32 v68, s3
	v_rcp_f32_e32 v66, v47
	v_add_f32_e32 v47, 1.0, v65
	v_rcp_f32_e32 v67, v47
	v_mul_f32_e32 v47, s2, v68
	v_pk_mul_f32 v[68:69], v[14:15], v[62:63]
	v_mul_f32_e32 v100, v60, v47
	v_mul_f32_e32 v47, v41, v41
	v_mov_b32_e32 v62, 0
	v_readlane_b32 s4, v3, 11
	v_readlane_b32 s3, v102, 11
	v_mov_b32_dpp v62, v47 quad_perm:[1,0,3,2] row_mask:0xf bank_mask:0xf
	v_fmac_f32_e32 v62, v41, v41
	v_pk_mul_f32 v[34:35], v[34:35], v[66:67]
	v_mov_b32_e32 v65, s4
	v_add_f32_dpp v47, v62, v62 quad_perm:[2,3,0,1] row_mask:0xf bank_mask:0xf bound_ctrl:1
	v_mov_b32_e32 v62, 0
	v_pk_mul_f32 v[34:35], v[34:35], s[2:3]
	v_add_f32_dpp v47, v47, v47 row_half_mirror row_mask:0xf bank_mask:0xf bound_ctrl:1
	v_mul_f32_e32 v66, s3, v65
	s_mov_b32 s2, 0x13000
	v_add_f32_dpp v47, v47, v47 row_mirror row_mask:0xf bank_mask:0xf bound_ctrl:1
	v_mul_f32_e32 v99, v61, v66
	v_add_co_u32_e32 v66, vcc, s2, v44
	v_mov_b32_dpp v62, v47 row_bcast:15 row_mask:0xa bank_mask:0xf
	v_add_f32_e32 v47, v47, v62
	v_mov_b32_e32 v62, 0
	v_addc_co_u32_e32 v67, vcc, 0, v45, vcc
	s_nop 0
	v_mov_b32_dpp v62, v47 row_bcast:31 row_mask:0xc bank_mask:0xf
	v_add_f32_e32 v47, v47, v62
	v_mul_f32_e32 v62, v9, v37
	v_fmac_f32_e32 v62, v5, v39
	v_fmac_f32_e32 v62, v7, v104
	v_fmac_f32_e32 v62, v105, v107
	v_mul_f32_e32 v39, 0xbfb8aa3b, v62
	v_exp_f32_e32 v39, v39
	v_readlane_b32 s2, v47, 63
	v_lshlrev_b32_e32 v65, 16, v53
	global_load_ushort v128, v[72:73], off
	global_load_ushort v123, v[74:75], off
	global_load_ushort v53, v[76:77], off offset:1024
	global_load_ushort v127, v[76:77], off
	global_load_ushort v79, v[72:73], off offset:1024
	v_add_f32_e32 v47, s2, v86
	v_rsq_f32_e32 v47, v47
	v_add_f32_e32 v39, 1.0, v39
	v_rcp_f32_e32 v39, v39
	s_waitcnt vmcnt(2) lgkmcnt(0)
	v_lshlrev_b32_e32 v120, 16, v113
	v_mul_f32_e32 v41, v41, v47
	v_mul_f32_e32 v41, 0x3e000000, v41
	v_cvt_pk_bf16_f32 v41, v41, s0
	v_mul_f32_e32 v39, v62, v39
	global_load_ushort v112, v[66:67], off offset:1024
	global_load_ushort v111, v[66:67], off
	global_load_ushort v113, v[74:75], off offset:1024
	ds_write_b16 v118, v41 offset:1536
	v_mul_f32_e32 v41, v39, v39
	v_mov_b32_e32 v47, 0
	v_mul_f32_e32 v63, v13, v63
	v_mul_f32_e32 v73, v12, v64
	v_mov_b32_dpp v47, v41 quad_perm:[1,0,3,2] row_mask:0xf bank_mask:0xf
	v_fmac_f32_e32 v47, v39, v39
	v_mov_b32_e32 v62, v68
	v_mov_b32_e32 v72, v69
	v_add_f32_dpp v41, v47, v47 quad_perm:[2,3,0,1] row_mask:0xf bank_mask:0xf bound_ctrl:1
	v_mov_b32_e32 v47, 0
	v_pk_add_f32 v[62:63], v[62:63], v[72:73]
	v_add_f32_dpp v41, v41, v41 row_half_mirror row_mask:0xf bank_mask:0xf bound_ctrl:1
	v_lshlrev_b32_e32 v69, 16, v126
	v_lshlrev_b32_e32 v68, 16, v122
	v_add_f32_dpp v41, v41, v41 row_mirror row_mask:0xf bank_mask:0xf bound_ctrl:1
	v_pk_mul_f32 v[72:73], v[4:5], v[58:59] op_sel_hi:[0,1]
	v_pk_fma_f32 v[72:73], v[2:3], v[70:71], v[72:73] op_sel_hi:[0,1,1]
	v_mov_b32_dpp v47, v41 row_bcast:15 row_mask:0xa bank_mask:0xf
	v_add_f32_e32 v41, v41, v47
	v_mov_b32_e32 v47, 0
	v_pk_mov_b32 v[70:71], v[58:59], v[68:69] op_sel:[1,0]
	v_pk_mul_f32 v[74:75], v[10:11], v[64:65]
	v_mov_b32_dpp v47, v41 row_bcast:31 row_mask:0xc bank_mask:0xf
	v_pk_fma_f32 v[58:59], v[6:7], v[70:71], v[72:73] op_sel_hi:[0,1,1]
	v_lshlrev_b32_e32 v77, 16, v130
	v_lshlrev_b32_e32 v76, 16, v131
	v_add_f32_e32 v41, v41, v47
	v_mul_f32_e32 v131, v10, v65
	v_mov_b32_e32 v130, v74
	v_pk_fma_f32 v[72:73], v[8:9], v[68:69], v[58:59] op_sel_hi:[0,1,1]
	v_lshlrev_b32_e32 v58, 16, v106
	v_readlane_b32 s3, v41, 63
	v_pk_add_f32 v[62:63], v[62:63], v[130:131]
	v_mul_f32_e32 v131, v11, v58
	v_mov_b32_e32 v130, v75
	v_add_f32_e32 v41, s3, v86
	v_pk_add_f32 v[62:63], v[62:63], v[130:131]
	v_rsq_f32_e32 v41, v41
	v_mul_f32_e32 v47, 0xbfb8aa3b, v62
	v_exp_f32_e32 v47, v47
	v_mul_f32_e32 v59, 0xbfb8aa3b, v63
	v_exp_f32_e32 v59, v59
	v_mul_f32_e32 v39, v39, v41
	v_mul_f32_e32 v41, v9, v104
	v_fmac_f32_e32 v41, v5, v37
	v_add_f32_e32 v37, 1.0, v47
	v_rcp_f32_e32 v74, v37
	v_add_f32_e32 v37, 1.0, v59
	v_rcp_f32_e32 v75, v37
	v_mov_b32_e32 v47, 0
	v_fmac_f32_e32 v41, v7, v107
	v_fmac_f32_e32 v41, v105, v121
	v_pk_mul_f32 v[62:63], v[62:63], v[74:75]
	v_mul_f32_e32 v39, 0x3e000000, v39
	v_pk_mul_f32 v[74:75], v[62:63], v[62:63]
	v_cvt_pk_bf16_f32 v39, v39, s0
	v_pk_mul_f32 v[130:131], v[14:15], v[64:65]
	v_add_f32_dpp v37, v74, v74 quad_perm:[1,0,3,2] row_mask:0xf bank_mask:0xf bound_ctrl:1
	v_lshlrev_b32_e32 v59, 16, v103
	v_mul_f32_e32 v65, v13, v65
	v_add_f32_dpp v37, v37, v37 quad_perm:[2,3,0,1] row_mask:0xf bank_mask:0xf bound_ctrl:1
	v_mul_f32_e32 v133, v12, v58
	v_mov_b32_e32 v132, v131
	v_add_f32_dpp v37, v37, v37 row_half_mirror row_mask:0xf bank_mask:0xf bound_ctrl:1
	v_mul_f32_e32 v135, v10, v59
	v_readlane_b32 s2, v3, 12
	v_add_f32_dpp v37, v37, v37 row_mirror row_mask:0xf bank_mask:0xf bound_ctrl:1
	v_readlane_b32 s4, v3, 15
	v_lshlrev_b32_e32 v78, 16, v129
	v_mov_b32_dpp v47, v37 row_bcast:15 row_mask:0xa bank_mask:0xf
	v_add_f32_e32 v37, v37, v47
	v_mov_b32_e32 v47, 0
	v_lshlrev_b32_e32 v53, 16, v53
	v_mul_f32_e32 v126, v9, v77
	v_mov_b32_dpp v47, v37 row_bcast:31 row_mask:0xc bank_mask:0xf
	v_add_f32_e32 v37, v37, v47
	v_mov_b32_e32 v47, 0
	v_readlane_b32 s3, v37, 63
	v_fmac_f32_e32 v126, v5, v78
	v_fmac_f32_e32 v126, v7, v76
	v_add_f32_e32 v37, s3, v86
	v_rsq_f32_e32 v74, v37
	s_nop 0
	v_add_f32_dpp v37, v75, v75 quad_perm:[1,0,3,2] row_mask:0xf bank_mask:0xf bound_ctrl:1
	s_nop 1
	v_add_f32_dpp v37, v37, v37 quad_perm:[2,3,0,1] row_mask:0xf bank_mask:0xf bound_ctrl:1
	s_nop 1
	v_add_f32_dpp v37, v37, v37 row_half_mirror row_mask:0xf bank_mask:0xf bound_ctrl:1
	s_nop 1
	v_add_f32_dpp v37, v37, v37 row_mirror row_mask:0xf bank_mask:0xf bound_ctrl:1
	s_nop 1
	v_mov_b32_dpp v47, v37 row_bcast:15 row_mask:0xa bank_mask:0xf
	v_add_f32_e32 v37, v37, v47
	v_mov_b32_e32 v47, 0
	s_nop 1
	v_mov_b32_dpp v47, v37 row_bcast:31 row_mask:0xc bank_mask:0xf
	v_add_f32_e32 v37, v37, v47
	s_nop 0
	v_readlane_b32 s3, v37, 63
	s_nop 1
	v_add_f32_e32 v37, s3, v86
	v_rsq_f32_e32 v75, v37
	v_mul_f32_e32 v37, 0xbfb8aa3b, v41
	v_exp_f32_e32 v37, v37
	v_pk_mul_f32 v[74:75], v[62:63], v[74:75]
	s_nop 0
	v_cvt_pk_bf16_f32 v47, v74, s0
	v_add_f32_e32 v37, 1.0, v37
	v_rcp_f32_e32 v37, v37
	ds_write_b16 v118, v47 offset:5632
	ds_write_b16 v119, v39 offset:1664
	v_mov_b32_e32 v47, 0
	v_cvt_pk_bf16_f32 v39, v75, s0
	v_mul_f32_e32 v37, v41, v37
	v_mul_f32_e32 v41, v37, v37
	ds_write_b16 v119, v39 offset:5760
	s_nop 0
	v_mov_b32_dpp v47, v41 quad_perm:[1,0,3,2] row_mask:0xf bank_mask:0xf
	v_fmac_f32_e32 v47, v37, v37
	s_nop 1
	v_add_f32_dpp v41, v47, v47 quad_perm:[2,3,0,1] row_mask:0xf bank_mask:0xf bound_ctrl:1
	v_mov_b32_e32 v47, 0
	s_nop 0
	v_add_f32_dpp v41, v41, v41 row_half_mirror row_mask:0xf bank_mask:0xf bound_ctrl:1
	s_nop 1
	v_add_f32_dpp v41, v41, v41 row_mirror row_mask:0xf bank_mask:0xf bound_ctrl:1
	s_nop 1
	v_mov_b32_dpp v47, v41 row_bcast:15 row_mask:0xa bank_mask:0xf
	v_add_f32_e32 v41, v41, v47
	v_mov_b32_e32 v47, 0
	s_nop 1
	v_mov_b32_dpp v47, v41 row_bcast:31 row_mask:0xc bank_mask:0xf
	v_add_f32_e32 v41, v41, v47
	v_mul_f32_e32 v47, v9, v107
	v_fmac_f32_e32 v47, v5, v104
	v_fmac_f32_e32 v47, v7, v121
	v_fmac_f32_e32 v47, v105, v110
	v_mul_f32_e32 v62, 0xbfb8aa3b, v47
	v_readlane_b32 s3, v41, 63
	v_exp_f32_e32 v64, v62
	v_pk_mul_f32 v[62:63], v[10:11], v[58:59]
	v_add_f32_e32 v41, s3, v86
	v_rsq_f32_e32 v41, v41
	v_add_f32_e32 v39, 1.0, v64
	v_rcp_f32_e32 v39, v39
	v_mov_b32_e32 v64, v130
	v_mul_f32_e32 v37, v37, v41
	v_mul_f32_e32 v37, 0x3e000000, v37
	v_cvt_pk_bf16_f32 v37, v37, s0
	ds_write_b16 v124, v37 offset:1792
	v_mul_f32_e32 v37, v47, v39
	v_mul_f32_e32 v39, v37, v37
	v_mov_b32_e32 v41, 0
	v_pk_add_f32 v[64:65], v[64:65], v[132:133]
	v_mov_b32_e32 v134, v62
	v_mov_b32_dpp v41, v39 quad_perm:[1,0,3,2] row_mask:0xf bank_mask:0xf
	v_fmac_f32_e32 v41, v37, v37
	v_lshlrev_b32_e32 v62, 16, v55
	v_pk_add_f32 v[64:65], v[64:65], v[134:135]
	v_add_f32_dpp v39, v41, v41 quad_perm:[2,3,0,1] row_mask:0xf bank_mask:0xf bound_ctrl:1
	v_mov_b32_e32 v41, 0
	v_mul_f32_e32 v131, v11, v62
	v_add_f32_dpp v39, v39, v39 row_half_mirror row_mask:0xf bank_mask:0xf bound_ctrl:1
	v_mov_b32_e32 v130, v63
	v_pk_add_f32 v[64:65], v[64:65], v[130:131]
	v_add_f32_dpp v39, v39, v39 row_mirror row_mask:0xf bank_mask:0xf bound_ctrl:1
	v_mov_b32_e32 v55, 0
	v_cvt_pk_bf16_f32 v132, v74, v75
	v_mov_b32_dpp v41, v39 row_bcast:15 row_mask:0xa bank_mask:0xf
	v_add_f32_e32 v39, v39, v41
	v_mov_b32_e32 v41, 0
	v_lshlrev_b32_e32 v63, 16, v128
	s_nop 0
	v_mov_b32_dpp v41, v39 row_bcast:31 row_mask:0xc bank_mask:0xf
	v_add_f32_e32 v39, v39, v41
	s_nop 0
	v_readlane_b32 s3, v39, 63
	s_nop 1
	v_add_f32_e32 v39, s3, v86
	v_rsq_f32_e32 v39, v39
	s_nop 0
	v_mul_f32_e32 v37, v37, v39
	v_mul_f32_e32 v37, 0x3e000000, v37
	v_cvt_pk_bf16_f32 v103, v37, s0
	v_mul_f32_e32 v37, 0xbfb8aa3b, v64
	v_exp_f32_e32 v37, v37
	v_mul_f32_e32 v39, 0xbfb8aa3b, v65
	v_exp_f32_e32 v39, v39
	v_add_f32_e32 v37, 1.0, v37
	v_rcp_f32_e32 v130, v37
	v_add_f32_e32 v37, 1.0, v39
	v_rcp_f32_e32 v131, v37
	v_cvt_pk_bf16_f32 v37, v40, v46
	v_cvt_pk_bf16_f32 v39, v60, v61
	v_pk_mul_f32 v[40:41], v[64:65], v[130:131]
	s_nop 0
	v_pk_mul_f32 v[46:47], v[40:41], v[40:41]
	v_cvt_pk_bf16_f32 v131, v52, v54
	v_cvt_pk_bf16_f32 v130, v48, v50
	v_add_f32_dpp v46, v46, v46 quad_perm:[1,0,3,2] row_mask:0xf bank_mask:0xf bound_ctrl:1
	v_add_f32_dpp v47, v47, v47 quad_perm:[1,0,3,2] row_mask:0xf bank_mask:0xf bound_ctrl:1
	s_nop 0
	v_add_f32_dpp v46, v46, v46 quad_perm:[2,3,0,1] row_mask:0xf bank_mask:0xf bound_ctrl:1
	v_add_f32_dpp v47, v47, v47 quad_perm:[2,3,0,1] row_mask:0xf bank_mask:0xf bound_ctrl:1
	s_nop 0
	v_add_f32_dpp v46, v46, v46 row_half_mirror row_mask:0xf bank_mask:0xf bound_ctrl:1
	v_add_f32_dpp v47, v47, v47 row_half_mirror row_mask:0xf bank_mask:0xf bound_ctrl:1
	s_nop 0
	v_add_f32_dpp v46, v46, v46 row_mirror row_mask:0xf bank_mask:0xf bound_ctrl:1
	v_add_f32_dpp v47, v47, v47 row_mirror row_mask:0xf bank_mask:0xf bound_ctrl:1
	s_nop 0
	v_mov_b32_dpp v55, v46 row_bcast:15 row_mask:0xa bank_mask:0xf
	v_add_f32_e32 v46, v46, v55
	v_mov_b32_e32 v55, 0
	s_nop 1
	v_mov_b32_dpp v55, v46 row_bcast:31 row_mask:0xc bank_mask:0xf
	v_add_f32_e32 v46, v46, v55
	v_mov_b32_e32 v55, 0
	v_readlane_b32 s3, v46, 63
	s_nop 0
	v_mov_b32_dpp v55, v47 row_bcast:15 row_mask:0xa bank_mask:0xf
	v_add_f32_e32 v47, v47, v55
	v_mov_b32_e32 v55, 0
	v_add_f32_e32 v46, s3, v86
	v_rsq_f32_e32 v46, v46
	v_mov_b32_dpp v55, v47 row_bcast:31 row_mask:0xc bank_mask:0xf
	v_add_f32_e32 v47, v47, v55
	s_nop 0
	v_readlane_b32 s3, v47, 63
	s_nop 1
	v_add_f32_e32 v47, s3, v86
	v_rsq_f32_e32 v47, v47
	s_mov_b32 s3, 0x14000
	v_pk_mul_f32 v[54:55], v[40:41], v[46:47]
	s_nop 0
	v_cvt_pk_bf16_f32 v40, v54, s0
	ds_write_b16 v124, v40 offset:5888
	ds_write_b16 v125, v103 offset:1920
	v_cvt_pk_bf16_f32 v40, v55, s0
	ds_write_b16 v125, v40 offset:6016
	v_add_co_u32_e32 v40, vcc, s14, v42
	v_cvt_pk_bf16_f32 v133, v54, v55
	s_nop 0
	v_addc_co_u32_e32 v41, vcc, 0, v43, vcc
	global_store_dwordx4 v[40:41], v[36:39], off offset:2048
	global_store_dwordx4 v[16:17], v[130:133], off offset:512
	v_add_co_u32_e32 v56, vcc, s3, v44
	v_mov_b32_e32 v38, s2
	s_nop 0
	v_addc_co_u32_e32 v57, vcc, 0, v45, vcc
	global_load_ushort v52, v[66:67], off offset:3072
	global_load_ushort v122, v[56:57], off offset:3072
	v_readlane_b32 s2, v3, 13
	v_mul_f32_e32 v38, s6, v38
	v_mul_f32_e32 v104, v74, v38
	v_mov_b32_e32 v39, s2
	v_mul_f32_e32 v39, s7, v39
	v_mul_f32_e32 v103, v75, v39
	v_lshlrev_b32_e32 v41, 16, v51
	v_lshlrev_b32_e32 v40, 16, v49
	v_pk_mul_f32 v[38:39], v[4:5], v[68:69] op_sel_hi:[0,1]
	v_pk_fma_f32 v[38:39], v[2:3], v[70:71], v[38:39] op_sel_hi:[0,1,1]
	v_pk_mov_b32 v[42:43], v[68:69], v[40:41] op_sel:[1,0]
	v_mul_f32_e32 v69, v9, v121
	v_pk_fma_f32 v[38:39], v[6:7], v[42:43], v[38:39] op_sel_hi:[0,1,1]
	v_pk_fma_f32 v[38:39], v[8:9], v[40:41], v[38:39] op_sel_hi:[0,1,1]
	v_mul_f32_e32 v46, 0xbfb8aa3b, v38
	v_mul_f32_e32 v47, 0xbfb8aa3b, v39
	v_exp_f32_e32 v46, v46
	v_exp_f32_e32 v47, v47
	v_readlane_b32 s3, v3, 14
	v_fmac_f32_e32 v69, v5, v107
	v_add_f32_e32 v46, 1.0, v46
	v_add_f32_e32 v47, 1.0, v47
	v_rcp_f32_e32 v46, v46
	v_rcp_f32_e32 v47, v47
	v_readlane_b32 s2, v102, 14
	v_mov_b32_e32 v48, s3
	v_fmac_f32_e32 v69, v7, v110
	v_mul_f32_e32 v66, s2, v48
	v_fmac_f32_e32 v69, v105, v120
	v_mul_f32_e32 v36, 0xbfb8aa3b, v72
	v_mul_f32_e32 v37, 0xbfb8aa3b, v73
	v_readlane_b32 s3, v102, 15
	v_pk_mul_f32 v[38:39], v[38:39], v[46:47]
	v_mov_b32_e32 v46, s4
	v_mul_f32_e32 v107, v54, v66
	v_mul_f32_e32 v54, 0xbfb8aa3b, v69
	v_exp_f32_e32 v36, v36
	v_exp_f32_e32 v37, v37
	v_mul_f32_e32 v67, s3, v46
	v_pk_mul_f32 v[46:47], v[14:15], v[58:59]
	v_exp_f32_e32 v58, v54
	v_pk_mul_f32 v[38:39], v[38:39], s[2:3]
	s_mov_b64 s[2:3], 0x14000
	v_lshl_add_u64 v[48:49], v[44:45], 0, s[2:3]
	s_mov_b64 s[2:3], 0x15000
	v_add_f32_e32 v36, 1.0, v36
	v_add_f32_e32 v37, 1.0, v37
	v_lshl_add_u64 v[50:51], v[44:45], 0, s[2:3]
	s_mov_b64 s[2:3], 0x16000
	v_add_f32_e32 v58, 1.0, v58
	v_rcp_f32_e32 v36, v36
	v_rcp_f32_e32 v37, v37
	v_lshl_add_u64 v[60:61], v[44:45], 0, s[2:3]
	s_mov_b64 s[2:3], 0x17000
	v_rcp_f32_e32 v58, v58
	v_lshl_add_u64 v[64:65], v[44:45], 0, s[2:3]
	s_mov_b32 s2, 0x15000
	v_add_co_u32_e32 v54, vcc, s2, v44
	v_mul_f32_e32 v106, v55, v67
	s_nop 0
	v_addc_co_u32_e32 v55, vcc, 0, v45, vcc
	v_pk_mul_f32 v[36:37], v[72:73], v[36:37]
	global_load_ushort v73, v[54:55], off
	global_load_ushort v68, v[56:57], off
	global_load_ushort v66, v[48:49], off offset:1024
	global_load_ushort v67, v[50:51], off offset:1024
	global_load_ushort v74, v[60:61], off offset:1024
	global_load_ushort v75, v[64:65], off offset:1024
	v_mul_f32_e32 v50, v69, v58
	v_mul_f32_e32 v48, v50, v50
	v_mov_b32_e32 v49, 0
	v_mul_f32_e32 v61, v9, v110
	v_fmac_f32_e32 v61, v5, v121
	v_mov_b32_dpp v49, v48 quad_perm:[1,0,3,2] row_mask:0xf bank_mask:0xf
	v_fmac_f32_e32 v49, v50, v50
	v_fmac_f32_e32 v61, v7, v120
	v_fmac_f32_e32 v61, v105, v78
	v_add_f32_dpp v48, v49, v49 quad_perm:[2,3,0,1] row_mask:0xf bank_mask:0xf bound_ctrl:1
	v_mov_b32_e32 v49, 0
	s_mov_b32 s2, 0x16000
	v_add_f32_dpp v48, v48, v48 row_half_mirror row_mask:0xf bank_mask:0xf bound_ctrl:1
	v_add_co_u32_e32 v56, vcc, s2, v44
	s_nop 0
	v_add_f32_dpp v48, v48, v48 row_mirror row_mask:0xf bank_mask:0xf bound_ctrl:1
	s_waitcnt vmcnt(6) lgkmcnt(0)
	v_lshlrev_b32_e32 v71, 16, v52
	v_addc_co_u32_e32 v57, vcc, 0, v45, vcc
	v_mov_b32_dpp v49, v48 row_bcast:15 row_mask:0xa bank_mask:0xf
	v_add_f32_e32 v48, v48, v49
	v_mov_b32_e32 v49, 0
	s_mov_b32 s2, 0x17000
	v_readlane_b32 s4, v3, 17
	v_mov_b32_dpp v49, v48 row_bcast:31 row_mask:0xc bank_mask:0xf
	v_add_f32_e32 v48, v48, v49
	v_fmac_f32_e32 v126, v105, v71
	v_readlane_b32 s3, v48, 63
	v_lshlrev_b32_e32 v122, 16, v122
	v_pk_mul_f32 v[36:37], v[36:37], s[6:7]
	v_add_f32_e32 v48, s3, v86
	v_rsq_f32_e32 v51, v48
	v_pk_mul_f32 v[48:49], v[10:11], v[62:63]
	v_readlane_b32 s3, v3, 16
	v_readlane_b32 s7, v102, 21
	v_mul_f32_e32 v50, v50, v51
	v_mul_f32_e32 v50, 0x3e000000, v50
	v_cvt_pk_bf16_f32 v58, v50, s0
	v_mul_f32_e32 v50, 0xbfb8aa3b, v61
	v_exp_f32_e32 v52, v50
	v_add_co_u32_e32 v50, vcc, s2, v44
	v_readlane_b32 s6, v102, 20
	v_add_f32_e32 v52, 1.0, v52
	v_rcp_f32_e32 v64, v52
	v_addc_co_u32_e32 v51, vcc, 0, v45, vcc
	global_load_ushort v52, v[54:55], off offset:3072
	global_load_ushort v60, v[56:57], off offset:3072
	global_load_ushort v70, v[50:51], off
	global_load_ushort v72, v[56:57], off
	v_mul_f32_e32 v54, v61, v64
	v_mul_f32_e32 v55, v54, v54
	v_mov_b32_e32 v56, 0
	v_mul_f32_e32 v57, v12, v62
	ds_write_b16 v114, v58 offset:2048
	v_mov_b32_dpp v56, v55 quad_perm:[1,0,3,2] row_mask:0xf bank_mask:0xf
	v_fmac_f32_e32 v56, v54, v54
	v_mov_b32_e32 v58, v48
	v_mul_f32_e32 v64, v9, v120
	v_add_f32_dpp v55, v56, v56 quad_perm:[2,3,0,1] row_mask:0xf bank_mask:0xf bound_ctrl:1
	v_mov_b32_e32 v56, 0
	v_fmac_f32_e32 v64, v5, v110
	v_add_f32_dpp v55, v55, v55 row_half_mirror row_mask:0xf bank_mask:0xf bound_ctrl:1
	v_fmac_f32_e32 v64, v7, v78
	v_fmac_f32_e32 v64, v105, v77
	v_add_f32_dpp v55, v55, v55 row_mirror row_mask:0xf bank_mask:0xf bound_ctrl:1
	v_mov_b32_e32 v110, 0
	s_waitcnt vmcnt(2) lgkmcnt(0)
	v_lshlrev_b32_e32 v134, 16, v52
	v_mov_b32_dpp v56, v55 row_bcast:15 row_mask:0xa bank_mask:0xf
	v_add_f32_e32 v55, v55, v56
	v_mov_b32_e32 v56, 0
	v_lshlrev_b32_e32 v52, 16, v79
	v_lshlrev_b32_e32 v129, 16, v60
	v_mov_b32_dpp v56, v55 row_bcast:31 row_mask:0xc bank_mask:0xf
	v_add_f32_e32 v55, v55, v56
	v_mul_f32_e32 v149, v9, v134
	v_readlane_b32 s2, v55, 63
	v_fmac_f32_e32 v149, v5, v122
	v_fmac_f32_e32 v149, v7, v129
	v_add_f32_e32 v55, s2, v86
	v_rsq_f32_e32 v56, v55
	v_mul_f32_e32 v55, v13, v59
	v_mul_f32_e32 v59, v10, v63
	v_mul_f32_e32 v54, v54, v56
	v_mul_f32_e32 v61, 0x3e000000, v54
	v_mov_b32_e32 v54, v46
	v_mov_b32_e32 v56, v47
	v_pk_add_f32 v[46:47], v[54:55], v[56:57]
	v_mov_b32_e32 v56, v49
	v_pk_add_f32 v[54:55], v[46:47], v[58:59]
	v_lshlrev_b32_e32 v46, 16, v127
	v_mul_f32_e32 v57, v11, v46
	v_pk_add_f32 v[48:49], v[54:55], v[56:57]
	v_cvt_pk_bf16_f32 v61, v61, s0
	v_mul_f32_e32 v47, 0xbfb8aa3b, v48
	v_exp_f32_e32 v47, v47
	v_mul_f32_e32 v54, 0xbfb8aa3b, v49
	v_exp_f32_e32 v55, v54
	v_pk_mul_f32 v[58:59], v[14:15], v[62:63]
	v_add_f32_e32 v47, 1.0, v47
	v_rcp_f32_e32 v54, v47
	v_add_f32_e32 v47, 1.0, v55
	v_rcp_f32_e32 v55, v47
	v_mov_b32_e32 v62, 0
	v_pk_mul_f32 v[48:49], v[48:49], v[54:55]
	s_nop 0
	v_pk_mul_f32 v[54:55], v[48:49], v[48:49]
	s_nop 1
	v_add_f32_dpp v47, v54, v54 quad_perm:[1,0,3,2] row_mask:0xf bank_mask:0xf bound_ctrl:1
	v_mov_b32_e32 v54, 0
	s_nop 0
	v_add_f32_dpp v47, v47, v47 quad_perm:[2,3,0,1] row_mask:0xf bank_mask:0xf bound_ctrl:1
	s_nop 1
	v_add_f32_dpp v47, v47, v47 row_half_mirror row_mask:0xf bank_mask:0xf bound_ctrl:1
	s_nop 1
	v_add_f32_dpp v47, v47, v47 row_mirror row_mask:0xf bank_mask:0xf bound_ctrl:1
	s_nop 1
	v_mov_b32_dpp v54, v47 row_bcast:15 row_mask:0xa bank_mask:0xf
	v_add_f32_e32 v47, v47, v54
	v_mov_b32_e32 v54, 0
	s_nop 1
	v_mov_b32_dpp v54, v47 row_bcast:31 row_mask:0xc bank_mask:0xf
	v_add_f32_e32 v47, v47, v54
	s_nop 0
	v_readlane_b32 s2, v47, 63
	s_nop 1
	v_add_f32_e32 v47, s2, v86
	v_rsq_f32_e32 v54, v47
	s_nop 0
	v_add_f32_dpp v47, v55, v55 quad_perm:[1,0,3,2] row_mask:0xf bank_mask:0xf bound_ctrl:1
	v_mov_b32_e32 v55, 0
	s_nop 0
	v_add_f32_dpp v47, v47, v47 quad_perm:[2,3,0,1] row_mask:0xf bank_mask:0xf bound_ctrl:1
	s_nop 1
	v_add_f32_dpp v47, v47, v47 row_half_mirror row_mask:0xf bank_mask:0xf bound_ctrl:1
	s_nop 1
	v_add_f32_dpp v47, v47, v47 row_mirror row_mask:0xf bank_mask:0xf bound_ctrl:1
	s_nop 1
	v_mov_b32_dpp v55, v47 row_bcast:15 row_mask:0xa bank_mask:0xf
	v_add_f32_e32 v47, v47, v55
	v_mov_b32_e32 v55, 0
	s_nop 1
	v_mov_b32_dpp v55, v47 row_bcast:31 row_mask:0xc bank_mask:0xf
	v_add_f32_e32 v47, v47, v55
	s_nop 0
	v_readlane_b32 s2, v47, 63
	s_nop 1
	v_add_f32_e32 v47, s2, v86
	v_rsq_f32_e32 v55, v47
	v_mul_f32_e32 v47, 0xbfb8aa3b, v64
	v_exp_f32_e32 v65, v47
	v_lshlrev_b32_e32 v47, 16, v123
	v_pk_mul_f32 v[56:57], v[48:49], v[54:55]
	v_add_f32_e32 v48, 1.0, v65
	v_rcp_f32_e32 v48, v48
	v_cvt_pk_bf16_f32 v49, v56, s0
	ds_write_b16 v114, v49 offset:6144
	ds_write_b16 v116, v61 offset:2176
	v_mov_b32_e32 v49, 0
	v_mul_f32_e32 v54, v64, v48
	v_mul_f32_e32 v48, v54, v54
	v_mul_f32_e32 v61, v9, v78
	v_fmac_f32_e32 v61, v5, v120
	v_mov_b32_dpp v49, v48 quad_perm:[1,0,3,2] row_mask:0xf bank_mask:0xf
	v_fmac_f32_e32 v49, v54, v54
	v_fmac_f32_e32 v61, v7, v77
	v_fmac_f32_e32 v61, v105, v76
	v_add_f32_dpp v48, v49, v49 quad_perm:[2,3,0,1] row_mask:0xf bank_mask:0xf bound_ctrl:1
	v_mov_b32_e32 v49, 0
	v_mul_f32_e32 v65, v10, v47
	v_add_f32_dpp v48, v48, v48 row_half_mirror row_mask:0xf bank_mask:0xf bound_ctrl:1
	s_nop 1
	v_add_f32_dpp v48, v48, v48 row_mirror row_mask:0xf bank_mask:0xf bound_ctrl:1
	s_nop 1
	v_mov_b32_dpp v49, v48 row_bcast:15 row_mask:0xa bank_mask:0xf
	v_add_f32_e32 v48, v48, v49
	v_mov_b32_e32 v49, 0
	s_nop 1
	v_mov_b32_dpp v49, v48 row_bcast:31 row_mask:0xc bank_mask:0xf
	v_add_f32_e32 v48, v48, v49
	s_nop 0
	v_readlane_b32 s2, v48, 63
	s_nop 1
	v_add_f32_e32 v48, s2, v86
	v_rsq_f32_e32 v55, v48
	v_cvt_pk_bf16_f32 v48, v57, s0
	ds_write_b16 v116, v48 offset:6272
	v_pk_mul_f32 v[48:49], v[10:11], v[46:47]
	v_mul_f32_e32 v54, v54, v55
	v_mul_f32_e32 v55, 0xbfb8aa3b, v61
	v_exp_f32_e32 v55, v55
	v_mul_f32_e32 v54, 0x3e000000, v54
	v_cvt_pk_bf16_f32 v54, v54, s0
	ds_write_b16 v115, v54 offset:2304
	v_add_f32_e32 v54, 1.0, v55
	v_rcp_f32_e32 v54, v54
	v_mul_f32_e32 v55, v13, v63
	v_mul_f32_e32 v63, v12, v46
	v_mov_b32_e32 v64, v48
	v_mul_f32_e32 v61, v61, v54
	v_mul_f32_e32 v54, v61, v61
	v_lshlrev_b32_e32 v48, 16, v111
	s_nop 0
	v_mov_b32_dpp v62, v54 quad_perm:[1,0,3,2] row_mask:0xf bank_mask:0xf
	v_fmac_f32_e32 v62, v61, v61
	s_nop 1
	v_add_f32_dpp v54, v62, v62 quad_perm:[2,3,0,1] row_mask:0xf bank_mask:0xf bound_ctrl:1
	v_mov_b32_e32 v62, 0
	s_nop 0
	v_add_f32_dpp v54, v54, v54 row_half_mirror row_mask:0xf bank_mask:0xf bound_ctrl:1
	s_nop 1
	v_add_f32_dpp v54, v54, v54 row_mirror row_mask:0xf bank_mask:0xf bound_ctrl:1
	s_nop 1
	v_mov_b32_dpp v62, v54 row_bcast:15 row_mask:0xa bank_mask:0xf
	v_add_f32_e32 v69, v54, v62
	v_mov_b32_e32 v54, v58
	v_mov_b32_e32 v62, v59
	v_pk_add_f32 v[54:55], v[54:55], v[62:63]
	v_mul_f32_e32 v59, v11, v48
	v_pk_add_f32 v[54:55], v[54:55], v[64:65]
	v_mov_b32_e32 v58, v49
	v_pk_add_f32 v[54:55], v[54:55], v[58:59]
	v_mov_b32_dpp v110, v69 row_bcast:31 row_mask:0xc bank_mask:0xf
	v_mul_f32_e32 v49, 0xbfb8aa3b, v54
	v_exp_f32_e32 v49, v49
	v_mul_f32_e32 v58, 0xbfb8aa3b, v55
	v_exp_f32_e32 v59, v58
	v_add_f32_e32 v62, v69, v110
	v_add_f32_e32 v49, 1.0, v49
	v_rcp_f32_e32 v58, v49
	v_add_f32_e32 v49, 1.0, v59
	v_rcp_f32_e32 v59, v49
	v_readlane_b32 s2, v62, 63
	v_mov_b32_e32 v62, 0
	v_pk_mul_f32 v[54:55], v[54:55], v[58:59]
	s_nop 0
	v_pk_mul_f32 v[58:59], v[54:55], v[54:55]
	v_add_f32_e32 v49, s2, v86
	v_rsq_f32_e32 v49, v49
	v_add_f32_dpp v58, v58, v58 quad_perm:[1,0,3,2] row_mask:0xf bank_mask:0xf bound_ctrl:1
	v_add_f32_dpp v59, v59, v59 quad_perm:[1,0,3,2] row_mask:0xf bank_mask:0xf bound_ctrl:1
	v_mul_f32_e32 v49, v61, v49
	v_add_f32_dpp v58, v58, v58 quad_perm:[2,3,0,1] row_mask:0xf bank_mask:0xf bound_ctrl:1
	v_add_f32_dpp v59, v59, v59 quad_perm:[2,3,0,1] row_mask:0xf bank_mask:0xf bound_ctrl:1
	v_mul_f32_e32 v49, 0x3e000000, v49
	v_add_f32_dpp v58, v58, v58 row_half_mirror row_mask:0xf bank_mask:0xf bound_ctrl:1
	v_add_f32_dpp v59, v59, v59 row_half_mirror row_mask:0xf bank_mask:0xf bound_ctrl:1
	v_cvt_pk_bf16_f32 v49, v49, s0
	v_add_f32_dpp v58, v58, v58 row_mirror row_mask:0xf bank_mask:0xf bound_ctrl:1
	v_add_f32_dpp v59, v59, v59 row_mirror row_mask:0xf bank_mask:0xf bound_ctrl:1
	v_pk_mov_b32 v[60:61], v[40:41], v[52:53] op_sel:[1,0]
	v_mov_b32_dpp v62, v58 row_bcast:15 row_mask:0xa bank_mask:0xf
	v_add_f32_e32 v58, v58, v62
	v_mov_b32_e32 v62, 0
	s_nop 1
	v_mov_b32_dpp v62, v58 row_bcast:31 row_mask:0xc bank_mask:0xf
	v_add_f32_e32 v58, v58, v62
	v_mov_b32_e32 v62, 0
	v_readlane_b32 s2, v58, 63
	s_nop 0
	v_mov_b32_dpp v62, v59 row_bcast:15 row_mask:0xa bank_mask:0xf
	v_add_f32_e32 v59, v59, v62
	v_mov_b32_e32 v62, 0
	v_add_f32_e32 v58, s2, v86
	v_rsq_f32_e32 v58, v58
	v_mov_b32_dpp v62, v59 row_bcast:31 row_mask:0xc bank_mask:0xf
	v_add_f32_e32 v59, v59, v62
	s_nop 0
	v_readlane_b32 s2, v59, 63
	s_nop 1
	v_add_f32_e32 v59, s2, v86
	v_rsq_f32_e32 v59, v59
	s_mov_b32 s2, 0x18000
	v_pk_mul_f32 v[58:59], v[54:55], v[58:59]
	s_nop 0
	v_cvt_pk_bf16_f32 v54, v58, s0
	ds_write_b16 v115, v54 offset:6400
	ds_write_b16 v117, v49 offset:2432
	v_cvt_pk_bf16_f32 v49, v59, s0
	v_add_co_u32_e32 v54, vcc, s2, v44
	ds_write_b16 v117, v49 offset:6528
	s_nop 0
	v_addc_co_u32_e32 v55, vcc, 0, v45, vcc
	s_mov_b32 s2, 0x19000
	v_add_co_u32_e32 v62, vcc, s2, v44
	v_mov_b32_e32 v49, s3
	s_nop 0
	v_addc_co_u32_e32 v63, vcc, 0, v45, vcc
	global_load_ushort v69, v[50:51], off offset:3072
	global_load_ushort v120, v[54:55], off offset:3072
	global_load_ushort v121, v[62:63], off offset:3072
	v_pk_mul_f32 v[50:51], v[4:5], v[40:41] op_sel_hi:[0,1]
	v_pk_fma_f32 v[42:43], v[2:3], v[42:43], v[50:51] op_sel_hi:[0,1,1]
	v_pk_fma_f32 v[40:41], v[6:7], v[60:61], v[42:43] op_sel_hi:[0,1,1]
	v_pk_fma_f32 v[40:41], v[8:9], v[52:53], v[40:41] op_sel_hi:[0,1,1]
	v_mul_f32_e32 v42, 0xbfb8aa3b, v40
	v_mul_f32_e32 v43, 0xbfb8aa3b, v41
	v_exp_f32_e32 v42, v42
	v_exp_f32_e32 v43, v43
	s_mov_b32 s3, 0x1a000
	v_add_co_u32_e32 v64, vcc, s3, v44
	v_add_f32_e32 v42, 1.0, v42
	v_add_f32_e32 v43, 1.0, v43
	v_rcp_f32_e32 v42, v42
	v_rcp_f32_e32 v43, v43
	v_readlane_b32 s3, v102, 17
	v_lshlrev_b32_e32 v51, 16, v112
	v_lshlrev_b32_e32 v50, 16, v113
	v_pk_mul_f32 v[40:41], v[40:41], v[42:43]
	v_mov_b32_e32 v42, s4
	v_mul_f32_e32 v42, s3, v42
	v_mul_f32_e32 v110, v57, v42
	v_pk_mul_f32 v[42:43], v[4:5], v[52:53] op_sel_hi:[0,1]
	v_pk_fma_f32 v[42:43], v[2:3], v[60:61], v[42:43] op_sel_hi:[0,1,1]
	v_pk_mov_b32 v[52:53], v[52:53], v[50:51] op_sel:[1,0]
	v_readlane_b32 s2, v102, 16
	v_pk_fma_f32 v[42:43], v[6:7], v[52:53], v[42:43] op_sel_hi:[0,1,1]
	v_pk_fma_f32 v[42:43], v[8:9], v[50:51], v[42:43] op_sel_hi:[0,1,1]
	v_mul_f32_e32 v49, s2, v49
	v_mul_f32_e32 v111, v56, v49
	v_mul_f32_e32 v49, 0xbfb8aa3b, v42
	v_exp_f32_e32 v49, v49
	v_mul_f32_e32 v60, 0xbfb8aa3b, v43
	v_exp_f32_e32 v61, v60
	v_pk_mul_f32 v[40:41], v[40:41], s[2:3]
	v_add_f32_e32 v49, 1.0, v49
	v_rcp_f32_e32 v60, v49
	v_add_f32_e32 v49, 1.0, v61
	v_rcp_f32_e32 v61, v49
	v_readlane_b32 s3, v3, 18
	v_readlane_b32 s4, v3, 19
	v_readlane_b32 s2, v102, 18
	v_pk_mul_f32 v[42:43], v[42:43], v[60:61]
	v_pk_mul_f32 v[60:61], v[14:15], v[46:47]
	v_mul_f32_e32 v46, 0xbfb8aa3b, v126
	v_exp_f32_e32 v46, v46
	v_mov_b32_e32 v112, s3
	v_readlane_b32 s3, v102, 19
	v_mov_b32_e32 v49, s4
	v_add_f32_e32 v46, 1.0, v46
	v_rcp_f32_e32 v46, v46
	v_addc_co_u32_e32 v65, vcc, 0, v45, vcc
	v_mul_f32_e32 v112, s2, v112
	v_mul_f32_e32 v123, s3, v49
	v_mul_f32_e32 v46, v126, v46
	global_load_ushort v79, v[64:65], off offset:3072
	v_mul_f32_e32 v113, v58, v112
	v_mul_f32_e32 v112, v59, v123
	global_load_ushort v123, v[54:55], off
	global_load_ushort v135, v[64:65], off
	global_load_ushort v137, v[62:63], off offset:1024
	global_load_ushort v136, v[62:63], off
	global_load_ushort v138, v[54:55], off offset:1024
	v_mul_f32_e32 v54, v46, v46
	v_mov_b32_e32 v55, 0
	v_pk_mul_f32 v[42:43], v[42:43], s[2:3]
	v_lshlrev_b32_e32 v49, 16, v68
	v_mov_b32_dpp v55, v54 quad_perm:[1,0,3,2] row_mask:0xf bank_mask:0xf
	v_fmac_f32_e32 v55, v46, v46
	v_pk_mul_f32 v[62:63], v[10:11], v[48:49]
	v_mul_f32_e32 v47, v13, v47
	v_add_f32_dpp v54, v55, v55 quad_perm:[2,3,0,1] row_mask:0xf bank_mask:0xf bound_ctrl:1
	v_mov_b32_e32 v55, 0
	v_readlane_b32 s3, v3, 22
	v_add_f32_dpp v54, v54, v54 row_half_mirror row_mask:0xf bank_mask:0xf bound_ctrl:1
	v_readlane_b32 s4, v3, 23
	s_waitcnt vmcnt(4) lgkmcnt(0)
	v_lshlrev_b32_e32 v133, 16, v69
	v_add_f32_dpp v54, v54, v54 row_mirror row_mask:0xf bank_mask:0xf bound_ctrl:1
	v_mul_f32_e32 v69, v10, v49
	v_lshlrev_b32_e32 v128, 16, v120
	v_mov_b32_dpp v55, v54 row_bcast:15 row_mask:0xa bank_mask:0xf
	v_add_f32_e32 v54, v54, v55
	v_mov_b32_e32 v55, 0
	v_mov_b32_e32 v120, 0
	v_lshlrev_b32_e32 v127, 16, v121
	v_mov_b32_dpp v55, v54 row_bcast:31 row_mask:0xc bank_mask:0xf
	v_add_f32_e32 v54, v54, v55
	v_fmac_f32_e32 v149, v105, v133
	v_readlane_b32 s2, v54, 63
	v_lshlrev_b32_e32 v126, 16, v79
	s_nop 0
	v_add_f32_e32 v54, s2, v86
	s_mov_b32 s2, 0x1b000
	v_rsq_f32_e32 v68, v54
	v_add_co_u32_e32 v54, vcc, s2, v44
	v_readlane_b32 s2, v3, 20
	s_nop 0
	v_addc_co_u32_e32 v55, vcc, 0, v45, vcc
	global_load_ushort v131, v[54:55], off offset:1024
	global_load_ushort v130, v[54:55], off
	global_load_ushort v132, v[64:65], off offset:1024
	v_mul_f32_e32 v64, v9, v76
	v_fmac_f32_e32 v64, v5, v77
	v_fmac_f32_e32 v64, v7, v71
	v_fmac_f32_e32 v64, v105, v122
	v_mul_f32_e32 v65, 0xbfb8aa3b, v64
	v_exp_f32_e32 v65, v65
	v_mul_f32_e32 v46, v46, v68
	v_mul_f32_e32 v46, 0x3e000000, v46
	v_cvt_pk_bf16_f32 v46, v46, s0
	ds_write_b16 v118, v46 offset:2560
	v_add_f32_e32 v46, 1.0, v65
	v_rcp_f32_e32 v46, v46
	v_mov_b32_e32 v65, 0
	v_mov_b32_e32 v77, s2
	v_mov_b32_e32 v68, v62
	v_mul_f32_e32 v46, v64, v46
	v_mul_f32_e32 v64, v46, v46
	s_nop 1
	v_mov_b32_dpp v65, v64 quad_perm:[1,0,3,2] row_mask:0xf bank_mask:0xf
	v_fmac_f32_e32 v65, v46, v46
	s_nop 1
	v_add_f32_dpp v64, v65, v65 quad_perm:[2,3,0,1] row_mask:0xf bank_mask:0xf bound_ctrl:1
	v_mov_b32_e32 v65, 0
	s_nop 0
	v_add_f32_dpp v64, v64, v64 row_half_mirror row_mask:0xf bank_mask:0xf bound_ctrl:1
	s_nop 1
	v_add_f32_dpp v64, v64, v64 row_mirror row_mask:0xf bank_mask:0xf bound_ctrl:1
	s_nop 1
	v_mov_b32_dpp v65, v64 row_bcast:15 row_mask:0xa bank_mask:0xf
	v_add_f32_e32 v64, v64, v65
	v_mov_b32_e32 v65, 0
	s_nop 1
	v_mov_b32_dpp v65, v64 row_bcast:31 row_mask:0xc bank_mask:0xf
	v_add_f32_e32 v64, v64, v65
	v_mul_f32_e32 v65, v12, v48
	v_readlane_b32 s2, v64, 63
	s_nop 1
	v_add_f32_e32 v64, s2, v86
	v_rsq_f32_e32 v64, v64
	s_nop 0
	v_mul_f32_e32 v46, v46, v64
	v_mul_f32_e32 v78, 0x3e000000, v46
	v_mov_b32_e32 v46, v60
	v_mov_b32_e32 v64, v61
	v_pk_add_f32 v[46:47], v[46:47], v[64:65]
	v_lshlrev_b32_e32 v65, 16, v67
	v_pk_add_f32 v[60:61], v[46:47], v[68:69]
	v_lshlrev_b32_e32 v64, 16, v66
	v_pk_mul_f32 v[46:47], v[4:5], v[50:51] op_sel_hi:[0,1]
	v_pk_fma_f32 v[46:47], v[2:3], v[52:53], v[46:47] op_sel_hi:[0,1,1]
	v_pk_mov_b32 v[66:67], v[50:51], v[64:65] op_sel:[1,0]
	v_mov_b32_e32 v52, v63
	v_pk_fma_f32 v[46:47], v[6:7], v[66:67], v[46:47] op_sel_hi:[0,1,1]
	v_pk_fma_f32 v[46:47], v[8:9], v[64:65], v[46:47] op_sel_hi:[0,1,1]
	v_mul_f32_e32 v50, 0xbfb8aa3b, v46
	v_exp_f32_e32 v50, v50
	v_mul_f32_e32 v51, 0xbfb8aa3b, v47
	v_exp_f32_e32 v51, v51
	v_pk_mul_f32 v[62:63], v[14:15], v[48:49]
	v_add_f32_e32 v50, 1.0, v50
	v_rcp_f32_e32 v68, v50
	v_add_f32_e32 v50, 1.0, v51
	v_rcp_f32_e32 v69, v50
	v_lshlrev_b32_e32 v50, 16, v73
	v_mul_f32_e32 v53, v11, v50
	v_pk_add_f32 v[52:53], v[60:61], v[52:53]
	v_mul_f32_e32 v73, v9, v71
	v_mul_f32_e32 v51, 0xbfb8aa3b, v52
	v_exp_f32_e32 v51, v51
	v_mul_f32_e32 v60, 0xbfb8aa3b, v53
	v_exp_f32_e32 v61, v60
	v_fmac_f32_e32 v73, v5, v76
	v_add_f32_e32 v51, 1.0, v51
	v_rcp_f32_e32 v60, v51
	v_add_f32_e32 v51, 1.0, v61
	v_rcp_f32_e32 v61, v51
	v_fmac_f32_e32 v73, v7, v122
	v_fmac_f32_e32 v73, v105, v134
	v_cvt_pk_bf16_f32 v78, v78, s0
	v_pk_mul_f32 v[52:53], v[52:53], v[60:61]
	v_mul_f32_e32 v49, v13, v49
	v_pk_mul_f32 v[60:61], v[52:53], v[52:53]
	v_pk_mul_f32 v[46:47], v[46:47], v[68:69]
	v_lshlrev_b32_e32 v69, 16, v75
	v_add_f32_dpp v51, v60, v60 quad_perm:[1,0,3,2] row_mask:0xf bank_mask:0xf bound_ctrl:1
	v_mov_b32_e32 v60, 0
	v_pk_mul_f32 v[46:47], v[46:47], s[6:7]
	v_add_f32_dpp v51, v51, v51 quad_perm:[2,3,0,1] row_mask:0xf bank_mask:0xf bound_ctrl:1
	s_nop 1
	v_add_f32_dpp v51, v51, v51 row_half_mirror row_mask:0xf bank_mask:0xf bound_ctrl:1
	s_nop 1
	v_add_f32_dpp v51, v51, v51 row_mirror row_mask:0xf bank_mask:0xf bound_ctrl:1
	s_nop 1
	v_mov_b32_dpp v60, v51 row_bcast:15 row_mask:0xa bank_mask:0xf
	v_add_f32_e32 v51, v51, v60
	v_mov_b32_e32 v60, 0
	s_nop 1
	v_mov_b32_dpp v60, v51 row_bcast:31 row_mask:0xc bank_mask:0xf
	v_add_f32_e32 v51, v51, v60
	s_nop 0
	v_readlane_b32 s2, v51, 63
	s_nop 1
	v_add_f32_e32 v51, s2, v86
	v_rsq_f32_e32 v60, v51
	s_nop 0
	v_add_f32_dpp v51, v61, v61 quad_perm:[1,0,3,2] row_mask:0xf bank_mask:0xf bound_ctrl:1
	v_mov_b32_e32 v61, 0
	s_nop 0
	v_add_f32_dpp v51, v51, v51 quad_perm:[2,3,0,1] row_mask:0xf bank_mask:0xf bound_ctrl:1
	s_nop 1
	v_add_f32_dpp v51, v51, v51 row_half_mirror row_mask:0xf bank_mask:0xf bound_ctrl:1
	s_nop 1
	v_add_f32_dpp v51, v51, v51 row_mirror row_mask:0xf bank_mask:0xf bound_ctrl:1
	s_nop 1
	v_mov_b32_dpp v61, v51 row_bcast:15 row_mask:0xa bank_mask:0xf
	v_add_f32_e32 v51, v51, v61
	v_mov_b32_e32 v61, 0
	s_nop 1
	v_mov_b32_dpp v61, v51 row_bcast:31 row_mask:0xc bank_mask:0xf
	v_add_f32_e32 v51, v51, v61
	s_nop 0
	v_readlane_b32 s2, v51, 63
	s_nop 1
	v_add_f32_e32 v51, s2, v86
	v_rsq_f32_e32 v61, v51
	v_mul_f32_e32 v51, 0xbfb8aa3b, v73
	v_exp_f32_e32 v76, v51
	v_lshlrev_b32_e32 v51, 16, v72
	v_pk_mul_f32 v[60:61], v[52:53], v[60:61]
	v_mov_b32_e32 v53, 0
	v_add_f32_e32 v48, 1.0, v76
	v_rcp_f32_e32 v48, v48
	v_cvt_pk_bf16_f32 v52, v60, s0
	ds_write_b16 v118, v52 offset:6656
	ds_write_b16 v119, v78 offset:2688
	v_mul_f32_e32 v79, v10, v51
	v_mul_f32_e32 v48, v73, v48
	v_mul_f32_e32 v52, v48, v48
	v_mul_f32_e32 v73, v12, v50
	s_nop 0
	v_mov_b32_dpp v53, v52 quad_perm:[1,0,3,2] row_mask:0xf bank_mask:0xf
	v_fmac_f32_e32 v53, v48, v48
	s_nop 1
	v_add_f32_dpp v52, v53, v53 quad_perm:[2,3,0,1] row_mask:0xf bank_mask:0xf bound_ctrl:1
	v_mov_b32_e32 v53, 0
	s_nop 0
	v_add_f32_dpp v52, v52, v52 row_half_mirror row_mask:0xf bank_mask:0xf bound_ctrl:1
	s_nop 1
	v_add_f32_dpp v52, v52, v52 row_mirror row_mask:0xf bank_mask:0xf bound_ctrl:1
	s_nop 1
	v_mov_b32_dpp v53, v52 row_bcast:15 row_mask:0xa bank_mask:0xf
	v_add_f32_e32 v52, v52, v53
	v_mov_b32_e32 v53, 0
	s_nop 1
	v_mov_b32_dpp v53, v52 row_bcast:31 row_mask:0xc bank_mask:0xf
	v_add_f32_e32 v52, v52, v53
	s_nop 0
	v_readlane_b32 s2, v52, 63
	s_nop 1
	v_add_f32_e32 v52, s2, v86
	v_rsq_f32_e32 v72, v52
	v_cvt_pk_bf16_f32 v52, v61, s0
	ds_write_b16 v119, v52 offset:6784
	v_pk_mul_f32 v[52:53], v[10:11], v[50:51]
	v_mul_f32_e32 v48, v48, v72
	v_mul_f32_e32 v72, v9, v122
	v_fmac_f32_e32 v72, v5, v71
	v_fmac_f32_e32 v72, v7, v134
	v_fmac_f32_e32 v72, v105, v129
	v_mul_f32_e32 v71, 0xbfb8aa3b, v72
	v_exp_f32_e32 v71, v71
	v_mul_f32_e32 v48, 0x3e000000, v48
	v_cvt_pk_bf16_f32 v48, v48, s0
	ds_write_b16 v124, v48 offset:2816
	v_add_f32_e32 v48, 1.0, v71
	v_rcp_f32_e32 v48, v48
	v_mov_b32_e32 v78, v52
	v_lshlrev_b32_e32 v52, 16, v70
	v_mul_f32_e32 v71, v72, v48
	v_mul_f32_e32 v48, v71, v71
	v_mov_b32_e32 v72, 0
	s_nop 1
	v_mov_b32_dpp v72, v48 quad_perm:[1,0,3,2] row_mask:0xf bank_mask:0xf
	v_fmac_f32_e32 v72, v71, v71
	s_nop 1
	v_add_f32_dpp v48, v72, v72 quad_perm:[2,3,0,1] row_mask:0xf bank_mask:0xf bound_ctrl:1
	v_mov_b32_e32 v72, 0
	s_nop 0
	v_add_f32_dpp v48, v48, v48 row_half_mirror row_mask:0xf bank_mask:0xf bound_ctrl:1
	s_nop 1
	v_add_f32_dpp v48, v48, v48 row_mirror row_mask:0xf bank_mask:0xf bound_ctrl:1
	s_nop 1
	v_mov_b32_dpp v72, v48 row_bcast:15 row_mask:0xa bank_mask:0xf
	v_add_f32_e32 v76, v48, v72
	v_mov_b32_e32 v48, v62
	v_mov_b32_e32 v72, v63
	v_pk_add_f32 v[48:49], v[48:49], v[72:73]
	v_mul_f32_e32 v63, v11, v52
	v_pk_add_f32 v[48:49], v[48:49], v[78:79]
	v_mov_b32_e32 v62, v53
	v_pk_add_f32 v[48:49], v[48:49], v[62:63]
	v_mov_b32_dpp v120, v76 row_bcast:31 row_mask:0xc bank_mask:0xf
	v_mul_f32_e32 v53, 0xbfb8aa3b, v48
	v_exp_f32_e32 v53, v53
	v_mul_f32_e32 v62, 0xbfb8aa3b, v49
	v_exp_f32_e32 v63, v62
	v_add_f32_e32 v70, v76, v120
	v_add_f32_e32 v53, 1.0, v53
	v_rcp_f32_e32 v62, v53
	v_add_f32_e32 v53, 1.0, v63
	v_rcp_f32_e32 v63, v53
	v_readlane_b32 s2, v70, 63
	v_mov_b32_e32 v70, 0
	v_pk_mul_f32 v[48:49], v[48:49], v[62:63]
	s_nop 0
	v_pk_mul_f32 v[62:63], v[48:49], v[48:49]
	v_add_f32_e32 v53, s2, v86
	v_rsq_f32_e32 v53, v53
	v_add_f32_dpp v62, v62, v62 quad_perm:[1,0,3,2] row_mask:0xf bank_mask:0xf bound_ctrl:1
	v_add_f32_dpp v63, v63, v63 quad_perm:[1,0,3,2] row_mask:0xf bank_mask:0xf bound_ctrl:1
	v_mul_f32_e32 v53, v71, v53
	v_add_f32_dpp v62, v62, v62 quad_perm:[2,3,0,1] row_mask:0xf bank_mask:0xf bound_ctrl:1
	v_add_f32_dpp v63, v63, v63 quad_perm:[2,3,0,1] row_mask:0xf bank_mask:0xf bound_ctrl:1
	v_mul_f32_e32 v53, 0x3e000000, v53
	v_add_f32_dpp v62, v62, v62 row_half_mirror row_mask:0xf bank_mask:0xf bound_ctrl:1
	v_add_f32_dpp v63, v63, v63 row_half_mirror row_mask:0xf bank_mask:0xf bound_ctrl:1
	v_cvt_pk_bf16_f32 v53, v53, s0
	v_add_f32_dpp v62, v62, v62 row_mirror row_mask:0xf bank_mask:0xf bound_ctrl:1
	v_add_f32_dpp v63, v63, v63 row_mirror row_mask:0xf bank_mask:0xf bound_ctrl:1
	s_nop 0
	v_mov_b32_dpp v70, v62 row_bcast:15 row_mask:0xa bank_mask:0xf
	v_add_f32_e32 v62, v62, v70
	v_mov_b32_e32 v70, 0
	s_nop 1
	v_mov_b32_dpp v70, v62 row_bcast:31 row_mask:0xc bank_mask:0xf
	v_add_f32_e32 v62, v62, v70
	v_mov_b32_e32 v70, 0
	v_readlane_b32 s2, v62, 63
	s_nop 0
	v_mov_b32_dpp v70, v63 row_bcast:15 row_mask:0xa bank_mask:0xf
	v_add_f32_e32 v63, v63, v70
	v_mov_b32_e32 v70, 0
	v_add_f32_e32 v62, s2, v86
	v_rsq_f32_e32 v62, v62
	v_mov_b32_dpp v70, v63 row_bcast:31 row_mask:0xc bank_mask:0xf
	v_add_f32_e32 v63, v63, v70
	s_nop 0
	v_readlane_b32 s2, v63, 63
	s_nop 1
	v_add_f32_e32 v63, s2, v86
	v_rsq_f32_e32 v63, v63
	s_mov_b32 s2, 0x1c000
	v_add_co_u32_e32 v70, vcc, s2, v44
	v_pk_mul_f32 v[62:63], v[48:49], v[62:63]
	s_nop 0
	v_addc_co_u32_e32 v71, vcc, 0, v45, vcc
	v_cvt_pk_bf16_f32 v48, v62, s0
	ds_write_b16 v124, v48 offset:6912
	ds_write_b16 v125, v53 offset:2944
	v_cvt_pk_bf16_f32 v48, v63, s0
	ds_write_b16 v125, v48 offset:7040
	s_mov_b32 s2, 0x1d000
	global_load_ushort v141, v[54:55], off offset:3072
	global_load_ushort v142, v[70:71], off offset:3072
	v_add_co_u32_e32 v54, vcc, s2, v44
	v_readlane_b32 s2, v3, 21
	s_nop 0
	v_addc_co_u32_e32 v55, vcc, 0, v45, vcc
	v_mov_b32_e32 v48, s2
	s_mov_b32 s2, 0x1e000
	v_add_co_u32_e32 v72, vcc, s2, v44
	s_mov_b32 s2, 0x1f000
	s_nop 0
	v_addc_co_u32_e32 v73, vcc, 0, v45, vcc
	v_mul_f32_e32 v68, s7, v48
	v_add_co_u32_e32 v48, vcc, s2, v44
	global_load_ushort v143, v[54:55], off offset:3072
	s_nop 0
	v_addc_co_u32_e32 v49, vcc, 0, v45, vcc
	global_load_ushort v147, v[72:73], off offset:3072
	global_load_ushort v148, v[48:49], off
	v_mul_f32_e32 v120, v61, v68
	v_lshlrev_b32_e32 v68, 16, v74
	v_pk_mul_f32 v[48:49], v[4:5], v[64:65] op_sel_hi:[0,1]
	v_pk_fma_f32 v[48:49], v[2:3], v[66:67], v[48:49] op_sel_hi:[0,1,1]
	v_pk_mov_b32 v[64:65], v[64:65], v[68:69] op_sel:[1,0]
	v_mul_f32_e32 v53, s6, v77
	v_pk_fma_f32 v[48:49], v[6:7], v[64:65], v[48:49] op_sel_hi:[0,1,1]
	v_pk_fma_f32 v[48:49], v[8:9], v[68:69], v[48:49] op_sel_hi:[0,1,1]
	v_mul_f32_e32 v121, v60, v53
	v_mul_f32_e32 v53, 0xbfb8aa3b, v48
	v_exp_f32_e32 v53, v53
	v_mul_f32_e32 v66, 0xbfb8aa3b, v49
	v_exp_f32_e32 v67, v66
	v_readlane_b32 s2, v102, 22
	v_add_f32_e32 v53, 1.0, v53
	v_rcp_f32_e32 v66, v53
	v_add_f32_e32 v53, 1.0, v67
	v_rcp_f32_e32 v67, v53
	v_mov_b32_e32 v74, s3
	v_readlane_b32 s3, v102, 23
	v_mov_b32_e32 v53, s4
	v_pk_mul_f32 v[48:49], v[48:49], v[66:67]
	v_mul_f32_e32 v139, s2, v74
	v_pk_mul_f32 v[48:49], v[48:49], s[2:3]
	v_mul_f32_e32 v140, s3, v53
	s_mov_b64 s[2:3], 0x1c000
	v_lshl_add_u64 v[76:77], v[44:45], 0, s[2:3]
	s_mov_b64 s[2:3], 0x1d000
	v_lshl_add_u64 v[78:79], v[44:45], 0, s[2:3]
	s_mov_b64 s[2:3], 0x1e000
	v_lshl_add_u64 v[66:67], v[44:45], 0, s[2:3]
	s_mov_b64 s[2:3], 0x1f000
	v_lshl_add_u64 v[74:75], v[44:45], 0, s[2:3]
	v_pk_mul_f32 v[44:45], v[14:15], v[50:51]
	v_mul_f32_e32 v50, 0xbfb8aa3b, v149
	v_exp_f32_e32 v50, v50
	v_lshlrev_b32_e32 v53, 16, v123
	v_mul_f32_e32 v123, v62, v139
	v_mul_f32_e32 v122, v63, v140
	v_add_f32_e32 v50, 1.0, v50
	v_rcp_f32_e32 v50, v50
	global_load_ushort v144, v[54:55], off
	global_load_ushort v146, v[70:71], off
	global_load_ushort v145, v[76:77], off offset:1024
	s_nop 0
	global_load_ushort v79, v[78:79], off offset:1024
	s_nop 0
	global_load_ushort v139, v[74:75], off offset:1024
	global_load_ushort v140, v[66:67], off offset:1024
	v_mov_b32_e32 v66, 0
	global_load_ushort v78, v[72:73], off
	v_mul_f32_e32 v50, v149, v50
	v_mul_f32_e32 v55, v50, v50
	v_readlane_b32 s3, v3, 24
	v_mul_f32_e32 v51, v13, v51
	v_mov_b32_dpp v66, v55 quad_perm:[1,0,3,2] row_mask:0xf bank_mask:0xf
	v_fmac_f32_e32 v66, v50, v50
	v_pk_mul_f32 v[70:71], v[10:11], v[52:53]
	v_mul_f32_e32 v73, v10, v53
	v_add_f32_dpp v55, v66, v66 quad_perm:[2,3,0,1] row_mask:0xf bank_mask:0xf bound_ctrl:1
	v_mov_b32_e32 v66, 0
	v_mov_b32_e32 v72, v70
	v_add_f32_dpp v55, v55, v55 row_half_mirror row_mask:0xf bank_mask:0xf bound_ctrl:1
	v_readlane_b32 s4, v3, 25
	v_mul_f32_e32 v77, v9, v133
	v_add_f32_dpp v55, v55, v55 row_mirror row_mask:0xf bank_mask:0xf bound_ctrl:1
	v_fmac_f32_e32 v77, v5, v129
	v_fmac_f32_e32 v77, v7, v128
	v_mov_b32_dpp v66, v55 row_bcast:15 row_mask:0xa bank_mask:0xf
	v_add_f32_e32 v55, v55, v66
	v_mov_b32_e32 v66, 0
	v_fmac_f32_e32 v77, v105, v127
	s_waitcnt vmcnt(0) lgkmcnt(0)
	v_lshlrev_b32_e32 v54, 16, v141
	v_mov_b32_dpp v66, v55 row_bcast:31 row_mask:0xc bank_mask:0xf
	v_add_f32_e32 v55, v55, v66
	v_lshlrev_b32_e32 v142, 16, v142
	v_readlane_b32 s2, v55, 63
	v_cmp_gt_u32_e32 vcc, 32, v22
	v_lshlrev_b32_e32 v141, 16, v143
	v_add_f32_e32 v55, s2, v86
	v_rsq_f32_e32 v66, v55
	v_readlane_b32 s2, v102, 24
	v_lshlrev_b32_e32 v55, 16, v148
	v_lshlrev_b32_e32 v143, 16, v147
	v_mul_f32_e32 v50, v50, v66
	v_mul_f32_e32 v66, v9, v129
	v_fmac_f32_e32 v66, v5, v134
	v_fmac_f32_e32 v66, v7, v133
	v_fmac_f32_e32 v66, v105, v128
	v_mul_f32_e32 v67, 0xbfb8aa3b, v66
	v_exp_f32_e32 v67, v67
	v_mul_f32_e32 v50, 0x3e000000, v50
	v_cvt_pk_bf16_f32 v50, v50, s0
	ds_write_b16 v114, v50 offset:3072
	v_add_f32_e32 v50, 1.0, v67
	v_rcp_f32_e32 v50, v50
	v_mov_b32_e32 v67, s3
	v_mul_f32_e32 v74, s2, v67
	v_mov_b32_e32 v67, 0
	v_mul_f32_e32 v50, v66, v50
	v_mul_f32_e32 v66, v50, v50
	s_nop 1
	v_mov_b32_dpp v67, v66 quad_perm:[1,0,3,2] row_mask:0xf bank_mask:0xf
	v_fmac_f32_e32 v67, v50, v50
	s_nop 1
	v_add_f32_dpp v66, v67, v67 quad_perm:[2,3,0,1] row_mask:0xf bank_mask:0xf bound_ctrl:1
	v_mov_b32_e32 v67, 0
	s_nop 0
	v_add_f32_dpp v66, v66, v66 row_half_mirror row_mask:0xf bank_mask:0xf bound_ctrl:1
	s_nop 1
	v_add_f32_dpp v66, v66, v66 row_mirror row_mask:0xf bank_mask:0xf bound_ctrl:1
	s_nop 1
	v_mov_b32_dpp v67, v66 row_bcast:15 row_mask:0xa bank_mask:0xf
	v_add_f32_e32 v66, v66, v67
	v_mov_b32_e32 v67, 0
	s_nop 1
	v_mov_b32_dpp v67, v66 row_bcast:31 row_mask:0xc bank_mask:0xf
	v_add_f32_e32 v66, v66, v67
	v_mul_f32_e32 v67, v12, v52
	v_readlane_b32 s3, v66, 63
	s_nop 1
	v_add_f32_e32 v66, s3, v86
	v_rsq_f32_e32 v66, v66
	v_readlane_b32 s3, v102, 25
	v_mul_f32_e32 v50, v50, v66
	v_mul_f32_e32 v75, 0x3e000000, v50
	v_mov_b32_e32 v50, v44
	v_mov_b32_e32 v66, v45
	v_pk_add_f32 v[44:45], v[50:51], v[66:67]
	v_lshlrev_b32_e32 v51, 16, v137
	v_lshlrev_b32_e32 v50, 16, v138
	v_pk_mul_f32 v[66:67], v[4:5], v[68:69] op_sel_hi:[0,1]
	v_pk_fma_f32 v[64:65], v[2:3], v[64:65], v[66:67] op_sel_hi:[0,1,1]
	v_pk_mov_b32 v[66:67], v[68:69], v[50:51] op_sel:[1,0]
	v_pk_add_f32 v[72:73], v[44:45], v[72:73]
	v_pk_fma_f32 v[64:65], v[6:7], v[66:67], v[64:65] op_sel_hi:[0,1,1]
	v_pk_fma_f32 v[64:65], v[8:9], v[50:51], v[64:65] op_sel_hi:[0,1,1]
	v_mul_f32_e32 v68, 0xbfb8aa3b, v64
	v_mul_f32_e32 v69, 0xbfb8aa3b, v65
	v_exp_f32_e32 v68, v68
	v_exp_f32_e32 v69, v69
	v_cvt_pk_bf16_f32 v75, v75, s0
	v_add_f32_e32 v44, 1.0, v68
	v_add_f32_e32 v45, 1.0, v69
	v_rcp_f32_e32 v44, v44
	v_rcp_f32_e32 v45, v45
	v_lshlrev_b32_e32 v68, 16, v136
	v_pk_mul_f32 v[44:45], v[64:65], v[44:45]
	v_mov_b32_e32 v64, s4
	v_mul_f32_e32 v76, s3, v64
	v_mul_f32_e32 v65, v11, v68
	v_mov_b32_e32 v64, v71
	v_pk_add_f32 v[64:65], v[72:73], v[64:65]
	v_pk_mul_f32 v[72:73], v[14:15], v[52:53]
	v_mul_f32_e32 v69, 0xbfb8aa3b, v64
	v_exp_f32_e32 v69, v69
	v_mul_f32_e32 v70, 0xbfb8aa3b, v65
	v_exp_f32_e32 v71, v70
	v_pk_mul_f32 v[44:45], v[44:45], s[2:3]
	v_add_f32_e32 v69, 1.0, v69
	v_rcp_f32_e32 v70, v69
	v_add_f32_e32 v69, 1.0, v71
	v_rcp_f32_e32 v71, v69
	v_mov_b32_e32 v69, 0
	v_readlane_b32 s3, v3, 26
	v_mul_f32_e32 v53, v13, v53
	v_pk_mul_f32 v[64:65], v[64:65], v[70:71]
	v_readlane_b32 s4, v3, 27
	v_pk_mul_f32 v[70:71], v[64:65], v[64:65]
	s_nop 1
	v_add_f32_dpp v52, v70, v70 quad_perm:[1,0,3,2] row_mask:0xf bank_mask:0xf bound_ctrl:1
	s_nop 1
	v_add_f32_dpp v52, v52, v52 quad_perm:[2,3,0,1] row_mask:0xf bank_mask:0xf bound_ctrl:1
	s_nop 1
	v_add_f32_dpp v52, v52, v52 row_half_mirror row_mask:0xf bank_mask:0xf bound_ctrl:1
	s_nop 1
	v_add_f32_dpp v52, v52, v52 row_mirror row_mask:0xf bank_mask:0xf bound_ctrl:1
	s_nop 1
	v_mov_b32_dpp v69, v52 row_bcast:15 row_mask:0xa bank_mask:0xf
	v_add_f32_e32 v52, v52, v69
	v_mov_b32_e32 v69, 0
	s_nop 1
	v_mov_b32_dpp v69, v52 row_bcast:31 row_mask:0xc bank_mask:0xf
	v_add_f32_e32 v52, v52, v69
	v_mov_b32_e32 v69, 0
	v_readlane_b32 s2, v52, 63
	s_nop 1
	v_add_f32_e32 v52, s2, v86
	v_rsq_f32_e32 v70, v52
	s_nop 0
	v_add_f32_dpp v52, v71, v71 quad_perm:[1,0,3,2] row_mask:0xf bank_mask:0xf bound_ctrl:1
	s_nop 1
	v_add_f32_dpp v52, v52, v52 quad_perm:[2,3,0,1] row_mask:0xf bank_mask:0xf bound_ctrl:1
	s_nop 1
	v_add_f32_dpp v52, v52, v52 row_half_mirror row_mask:0xf bank_mask:0xf bound_ctrl:1
	s_nop 1
	v_add_f32_dpp v52, v52, v52 row_mirror row_mask:0xf bank_mask:0xf bound_ctrl:1
	s_nop 1
	v_mov_b32_dpp v69, v52 row_bcast:15 row_mask:0xa bank_mask:0xf
	v_add_f32_e32 v52, v52, v69
	v_mov_b32_e32 v69, 0
	s_nop 1
	v_mov_b32_dpp v69, v52 row_bcast:31 row_mask:0xc bank_mask:0xf
	v_add_f32_e32 v52, v52, v69
	v_lshlrev_b32_e32 v69, 16, v135
	v_readlane_b32 s2, v52, 63
	v_mul_f32_e32 v135, v10, v69
	v_mul_f32_e32 v13, v13, v69
	v_add_f32_e32 v52, s2, v86
	v_rsq_f32_e32 v71, v52
	v_mul_f32_e32 v52, 0xbfb8aa3b, v77
	v_exp_f32_e32 v52, v52
	v_pk_mul_f32 v[64:65], v[64:65], v[70:71]
	s_nop 0
	v_cvt_pk_bf16_f32 v70, v64, s0
	v_add_f32_e32 v52, 1.0, v52
	v_rcp_f32_e32 v52, v52
	ds_write_b16 v114, v70 offset:7168
	ds_write_b16 v116, v75 offset:3200
	v_mov_b32_e32 v75, 0
	v_mul_f32_e32 v52, v77, v52
	v_mul_f32_e32 v71, v52, v52
	v_cvt_pk_bf16_f32 v70, v65, s0
	ds_write_b16 v116, v70 offset:7296
	v_mov_b32_dpp v75, v71 quad_perm:[1,0,3,2] row_mask:0xf bank_mask:0xf
	v_fmac_f32_e32 v75, v52, v52
	v_mul_f32_e32 v74, v64, v74
	s_nop 0
	v_add_f32_dpp v71, v75, v75 quad_perm:[2,3,0,1] row_mask:0xf bank_mask:0xf bound_ctrl:1
	v_mov_b32_e32 v75, 0
	s_nop 0
	v_add_f32_dpp v71, v71, v71 row_half_mirror row_mask:0xf bank_mask:0xf bound_ctrl:1
	s_nop 1
	v_add_f32_dpp v71, v71, v71 row_mirror row_mask:0xf bank_mask:0xf bound_ctrl:1
	s_nop 1
	v_mov_b32_dpp v75, v71 row_bcast:15 row_mask:0xa bank_mask:0xf
	v_add_f32_e32 v71, v71, v75
	v_mov_b32_e32 v75, 0
	s_nop 1
	v_mov_b32_dpp v75, v71 row_bcast:31 row_mask:0xc bank_mask:0xf
	v_add_f32_e32 v71, v71, v75
	v_mul_f32_e32 v75, v65, v76
	v_readlane_b32 s2, v71, 63
	v_mul_f32_e32 v76, v9, v128
	v_fmac_f32_e32 v76, v5, v133
	v_add_f32_e32 v71, s2, v86
	v_rsq_f32_e32 v77, v71
	v_fmac_f32_e32 v76, v7, v127
	v_fmac_f32_e32 v76, v105, v126
	v_readlane_b32 s2, v102, 26
	v_mul_f32_e32 v52, v52, v77
	v_mul_f32_e32 v77, 0xbfb8aa3b, v76
	v_exp_f32_e32 v77, v77
	v_mul_f32_e32 v52, 0x3e000000, v52
	v_cvt_pk_bf16_f32 v52, v52, s0
	ds_write_b16 v115, v52 offset:3328
	v_add_f32_e32 v52, 1.0, v77
	v_rcp_f32_e32 v52, v52
	v_mov_b32_e32 v77, s3
	v_mul_f32_e32 v114, s2, v77
	v_mov_b32_e32 v77, 0
	v_mul_f32_e32 v52, v76, v52
	v_mul_f32_e32 v76, v52, v52
	v_pk_mul_f32 v[70:71], v[10:11], v[68:69]
	s_nop 0
	v_mov_b32_dpp v77, v76 quad_perm:[1,0,3,2] row_mask:0xf bank_mask:0xf
	v_fmac_f32_e32 v77, v52, v52
	v_mov_b32_e32 v134, v70
	s_nop 0
	v_add_f32_dpp v76, v77, v77 quad_perm:[2,3,0,1] row_mask:0xf bank_mask:0xf bound_ctrl:1
	v_mov_b32_e32 v77, 0
	s_nop 0
	v_add_f32_dpp v76, v76, v76 row_half_mirror row_mask:0xf bank_mask:0xf bound_ctrl:1
	s_nop 1
	v_add_f32_dpp v76, v76, v76 row_mirror row_mask:0xf bank_mask:0xf bound_ctrl:1
	s_nop 1
	v_mov_b32_dpp v77, v76 row_bcast:15 row_mask:0xa bank_mask:0xf
	v_add_f32_e32 v76, v76, v77
	v_mov_b32_e32 v77, 0
	s_nop 1
	v_mov_b32_dpp v77, v76 row_bcast:31 row_mask:0xc bank_mask:0xf
	v_add_f32_e32 v76, v76, v77
	v_mul_f32_e32 v77, v12, v68
	v_readlane_b32 s3, v76, 63
	s_nop 1
	v_add_f32_e32 v76, s3, v86
	v_rsq_f32_e32 v76, v76
	v_readlane_b32 s3, v102, 27
	v_mul_f32_e32 v52, v52, v76
	v_mul_f32_e32 v116, 0x3e000000, v52
	v_mov_b32_e32 v52, v72
	v_mov_b32_e32 v76, v73
	v_pk_add_f32 v[76:77], v[52:53], v[76:77]
	v_lshlrev_b32_e32 v53, 16, v131
	v_lshlrev_b32_e32 v52, 16, v132
	v_pk_mul_f32 v[72:73], v[4:5], v[50:51] op_sel_hi:[0,1]
	v_pk_fma_f32 v[66:67], v[2:3], v[66:67], v[72:73] op_sel_hi:[0,1,1]
	v_pk_mov_b32 v[72:73], v[50:51], v[52:53] op_sel:[1,0]
	v_mul_f32_e32 v131, v9, v127
	v_pk_fma_f32 v[50:51], v[6:7], v[72:73], v[66:67] op_sel_hi:[0,1,1]
	v_pk_fma_f32 v[50:51], v[8:9], v[52:53], v[50:51] op_sel_hi:[0,1,1]
	v_mul_f32_e32 v66, 0xbfb8aa3b, v50
	v_exp_f32_e32 v70, v66
	v_mul_f32_e32 v66, 0xbfb8aa3b, v51
	v_exp_f32_e32 v129, v66
	v_pk_add_f32 v[66:67], v[76:77], v[134:135]
	v_add_f32_e32 v70, 1.0, v70
	v_rcp_f32_e32 v76, v70
	v_add_f32_e32 v70, 1.0, v129
	v_rcp_f32_e32 v77, v70
	v_lshlrev_b32_e32 v70, 16, v130
	v_fmac_f32_e32 v131, v5, v128
	v_fmac_f32_e32 v131, v7, v126
	v_pk_mul_f32 v[50:51], v[50:51], v[76:77]
	v_mul_f32_e32 v77, v11, v70
	v_mov_b32_e32 v76, v71
	v_pk_add_f32 v[66:67], v[66:67], v[76:77]
	v_pk_mul_f32 v[50:51], v[50:51], s[2:3]
	v_mul_f32_e32 v71, 0xbfb8aa3b, v66
	v_exp_f32_e32 v71, v71
	v_mul_f32_e32 v76, 0xbfb8aa3b, v67
	v_exp_f32_e32 v77, v76
	v_mov_b32_e32 v129, s4
	v_add_f32_e32 v71, 1.0, v71
	v_rcp_f32_e32 v76, v71
	v_add_f32_e32 v71, 1.0, v77
	v_rcp_f32_e32 v77, v71
	v_fmac_f32_e32 v131, v105, v54
	v_mul_f32_e32 v130, s3, v129
	v_pk_mul_f32 v[128:129], v[14:15], v[68:69]
	v_pk_mul_f32 v[66:67], v[66:67], v[76:77]
	v_mul_f32_e32 v68, 0xbfb8aa3b, v131
	v_pk_mul_f32 v[76:77], v[66:67], v[66:67]
	v_exp_f32_e32 v68, v68
	v_cvt_pk_bf16_f32 v116, v116, s0
	v_add_f32_dpp v71, v76, v76 quad_perm:[1,0,3,2] row_mask:0xf bank_mask:0xf bound_ctrl:1
	v_mov_b32_e32 v76, 0
	v_add_f32_e32 v68, 1.0, v68
	v_add_f32_dpp v71, v71, v71 quad_perm:[2,3,0,1] row_mask:0xf bank_mask:0xf bound_ctrl:1
	v_rcp_f32_e32 v68, v68
	v_readlane_b32 s3, v3, 28
	v_add_f32_dpp v71, v71, v71 row_half_mirror row_mask:0xf bank_mask:0xf bound_ctrl:1
	v_mul_f32_e32 v69, v12, v70
	v_mul_f32_e32 v68, v131, v68
	v_add_f32_dpp v71, v71, v71 row_mirror row_mask:0xf bank_mask:0xf bound_ctrl:1
	v_readlane_b32 s4, v3, 29
	s_nop 0
	v_mov_b32_dpp v76, v71 row_bcast:15 row_mask:0xa bank_mask:0xf
	v_add_f32_e32 v71, v71, v76
	v_mov_b32_e32 v76, 0
	s_nop 1
	v_mov_b32_dpp v76, v71 row_bcast:31 row_mask:0xc bank_mask:0xf
	v_add_f32_e32 v71, v71, v76
	s_nop 0
	v_readlane_b32 s2, v71, 63
	s_nop 1
	v_add_f32_e32 v71, s2, v86
	v_rsq_f32_e32 v76, v71
	s_nop 0
	v_add_f32_dpp v71, v77, v77 quad_perm:[1,0,3,2] row_mask:0xf bank_mask:0xf bound_ctrl:1
	v_mov_b32_e32 v77, 0
	s_nop 0
	v_add_f32_dpp v71, v71, v71 quad_perm:[2,3,0,1] row_mask:0xf bank_mask:0xf bound_ctrl:1
	s_nop 1
	v_add_f32_dpp v71, v71, v71 row_half_mirror row_mask:0xf bank_mask:0xf bound_ctrl:1
	s_nop 1
	v_add_f32_dpp v71, v71, v71 row_mirror row_mask:0xf bank_mask:0xf bound_ctrl:1
	s_nop 1
	v_mov_b32_dpp v77, v71 row_bcast:15 row_mask:0xa bank_mask:0xf
	v_add_f32_e32 v71, v71, v77
	v_mov_b32_e32 v77, 0
	s_nop 1
	v_mov_b32_dpp v77, v71 row_bcast:31 row_mask:0xc bank_mask:0xf
	v_add_f32_e32 v71, v71, v77
	s_nop 0
	v_readlane_b32 s2, v71, 63
	s_nop 1
	v_add_f32_e32 v71, s2, v86
	v_rsq_f32_e32 v77, v71
	v_lshlrev_b32_e32 v71, 16, v146
	v_pk_mul_f32 v[66:67], v[66:67], v[76:77]
	s_nop 0
	v_cvt_pk_bf16_f32 v76, v66, s0
	v_cvt_pk_bf16_f32 v77, v67, s0
	ds_write_b16 v115, v76 offset:7424
	v_mul_f32_e32 v76, v66, v114
	ds_write_b16 v117, v77 offset:7552
	v_mul_f32_e32 v77, v68, v68
	v_mov_b32_e32 v114, 0
	ds_write_b16 v117, v116 offset:3456
	s_nop 0
	v_mov_b32_dpp v114, v77 quad_perm:[1,0,3,2] row_mask:0xf bank_mask:0xf
	v_fmac_f32_e32 v114, v68, v68
	s_nop 1
	v_add_f32_dpp v77, v114, v114 quad_perm:[2,3,0,1] row_mask:0xf bank_mask:0xf bound_ctrl:1
	v_mov_b32_e32 v114, 0
	s_nop 0
	v_add_f32_dpp v77, v77, v77 row_half_mirror row_mask:0xf bank_mask:0xf bound_ctrl:1
	s_nop 1
	v_add_f32_dpp v77, v77, v77 row_mirror row_mask:0xf bank_mask:0xf bound_ctrl:1
	s_nop 1
	v_mov_b32_dpp v114, v77 row_bcast:15 row_mask:0xa bank_mask:0xf
	v_add_f32_e32 v77, v77, v114
	v_mov_b32_e32 v114, 0
	s_nop 1
	v_mov_b32_dpp v114, v77 row_bcast:31 row_mask:0xc bank_mask:0xf
	v_add_f32_e32 v77, v77, v114
	v_pk_mul_f32 v[114:115], v[10:11], v[70:71]
	v_readlane_b32 s2, v77, 63
	s_nop 1
	v_add_f32_e32 v77, s2, v86
	v_rsq_f32_e32 v116, v77
	v_readlane_b32 s2, v102, 28
	v_mul_f32_e32 v77, v67, v130
	v_mul_f32_e32 v68, v68, v116
	v_mul_f32_e32 v116, v9, v126
	v_fmac_f32_e32 v116, v5, v127
	v_fmac_f32_e32 v116, v7, v54
	v_fmac_f32_e32 v116, v105, v142
	v_mul_f32_e32 v117, 0xbfb8aa3b, v116
	v_exp_f32_e32 v117, v117
	v_mul_f32_e32 v68, 0x3e000000, v68
	v_cvt_pk_bf16_f32 v68, v68, s0
	ds_write_b16 v118, v68 offset:3584
	v_add_f32_e32 v68, 1.0, v117
	v_rcp_f32_e32 v68, v68
	v_mov_b32_e32 v117, s3
	v_mul_f32_e32 v130, s2, v117
	v_mov_b32_e32 v117, 0
	v_mul_f32_e32 v68, v116, v68
	v_mul_f32_e32 v116, v68, v68
	s_nop 1
	v_mov_b32_dpp v117, v116 quad_perm:[1,0,3,2] row_mask:0xf bank_mask:0xf
	v_fmac_f32_e32 v117, v68, v68
	s_nop 1
	v_add_f32_dpp v116, v117, v117 quad_perm:[2,3,0,1] row_mask:0xf bank_mask:0xf bound_ctrl:1
	v_mov_b32_e32 v117, 0
	s_nop 0
	v_add_f32_dpp v116, v116, v116 row_half_mirror row_mask:0xf bank_mask:0xf bound_ctrl:1
	s_nop 1
	v_add_f32_dpp v116, v116, v116 row_mirror row_mask:0xf bank_mask:0xf bound_ctrl:1
	s_nop 1
	v_mov_b32_dpp v117, v116 row_bcast:15 row_mask:0xa bank_mask:0xf
	v_add_f32_e32 v116, v116, v117
	v_mov_b32_e32 v117, 0
	s_nop 1
	v_mov_b32_dpp v117, v116 row_bcast:31 row_mask:0xc bank_mask:0xf
	v_add_f32_e32 v116, v116, v117
	v_mul_f32_e32 v117, v10, v71
	v_readlane_b32 s3, v116, 63
	s_nop 1
	v_add_f32_e32 v116, s3, v86
	v_rsq_f32_e32 v116, v116
	v_readlane_b32 s3, v102, 29
	v_mul_f32_e32 v12, v68, v116
	v_mul_f32_e32 v127, 0x3e000000, v12
	v_mov_b32_e32 v12, v128
	v_mov_b32_e32 v68, v129
	v_pk_add_f32 v[128:129], v[12:13], v[68:69]
	v_lshlrev_b32_e32 v13, 16, v79
	v_lshlrev_b32_e32 v12, 16, v145
	v_pk_mul_f32 v[68:69], v[4:5], v[52:53] op_sel_hi:[0,1]
	v_pk_fma_f32 v[72:73], v[2:3], v[72:73], v[68:69] op_sel_hi:[0,1,1]
	v_pk_mov_b32 v[68:69], v[52:53], v[12:13] op_sel:[1,0]
	v_mov_b32_e32 v116, v114
	v_pk_fma_f32 v[52:53], v[6:7], v[68:69], v[72:73] op_sel_hi:[0,1,1]
	v_pk_fma_f32 v[52:53], v[8:9], v[12:13], v[52:53] op_sel_hi:[0,1,1]
	v_mul_f32_e32 v72, 0xbfb8aa3b, v52
	v_exp_f32_e32 v79, v72
	v_mul_f32_e32 v72, 0xbfb8aa3b, v53
	v_exp_f32_e32 v114, v72
	v_pk_add_f32 v[72:73], v[128:129], v[116:117]
	v_add_f32_e32 v79, 1.0, v79
	v_rcp_f32_e32 v116, v79
	v_add_f32_e32 v79, 1.0, v114
	v_rcp_f32_e32 v117, v79
	v_lshlrev_b32_e32 v114, 16, v144
	v_cvt_pk_bf16_f32 v79, v127, s0
	v_mov_b32_e32 v127, s4
	v_pk_mul_f32 v[52:53], v[52:53], v[116:117]
	v_mul_f32_e32 v117, v11, v114
	v_mov_b32_e32 v116, v115
	v_pk_add_f32 v[72:73], v[72:73], v[116:117]
	v_pk_mul_f32 v[52:53], v[52:53], s[2:3]
	v_mul_f32_e32 v115, 0xbfb8aa3b, v72
	v_exp_f32_e32 v115, v115
	v_mul_f32_e32 v116, 0xbfb8aa3b, v73
	v_exp_f32_e32 v117, v116
	v_mul_f32_e32 v129, v9, v54
	v_add_f32_e32 v115, 1.0, v115
	v_rcp_f32_e32 v116, v115
	v_add_f32_e32 v115, 1.0, v117
	v_rcp_f32_e32 v117, v115
	v_mul_f32_e32 v128, s3, v127
	v_fmac_f32_e32 v129, v5, v126
	v_pk_mul_f32 v[126:127], v[14:15], v[70:71]
	v_pk_mul_f32 v[72:73], v[72:73], v[116:117]
	v_fmac_f32_e32 v129, v7, v142
	v_pk_mul_f32 v[116:117], v[72:73], v[72:73]
	v_fmac_f32_e32 v129, v105, v141
	v_mul_f32_e32 v9, v9, v142
	v_add_f32_dpp v115, v116, v116 quad_perm:[1,0,3,2] row_mask:0xf bank_mask:0xf bound_ctrl:1
	v_mov_b32_e32 v116, 0
	v_fmac_f32_e32 v9, v5, v54
	v_add_f32_dpp v115, v115, v115 quad_perm:[2,3,0,1] row_mask:0xf bank_mask:0xf bound_ctrl:1
	v_fmac_f32_e32 v9, v7, v141
	v_fmac_f32_e32 v9, v105, v143
	v_add_f32_dpp v115, v115, v115 row_half_mirror row_mask:0xf bank_mask:0xf bound_ctrl:1
	v_mul_f32_e32 v7, 0xbfb8aa3b, v9
	v_exp_f32_e32 v7, v7
	v_add_f32_dpp v115, v115, v115 row_mirror row_mask:0xf bank_mask:0xf bound_ctrl:1
	v_readlane_b32 s3, v3, 30
	v_readlane_b32 s4, v3, 31
	v_mov_b32_dpp v116, v115 row_bcast:15 row_mask:0xa bank_mask:0xf
	v_add_f32_e32 v115, v115, v116
	v_mov_b32_e32 v116, 0
	v_add_f32_e32 v7, 1.0, v7
	v_rcp_f32_e32 v7, v7
	v_mov_b32_dpp v116, v115 row_bcast:31 row_mask:0xc bank_mask:0xf
	v_add_f32_e32 v115, v115, v116
	v_mul_f32_e32 v7, v9, v7
	v_readlane_b32 s2, v115, 63
	v_mov_b32_e32 v9, 0
	s_nop 0
	v_add_f32_e32 v115, s2, v86
	v_rsq_f32_e32 v116, v115
	s_nop 0
	v_add_f32_dpp v115, v117, v117 quad_perm:[1,0,3,2] row_mask:0xf bank_mask:0xf bound_ctrl:1
	v_mov_b32_e32 v117, 0
	s_nop 0
	v_add_f32_dpp v115, v115, v115 quad_perm:[2,3,0,1] row_mask:0xf bank_mask:0xf bound_ctrl:1
	s_nop 1
	v_add_f32_dpp v115, v115, v115 row_half_mirror row_mask:0xf bank_mask:0xf bound_ctrl:1
	s_nop 1
	v_add_f32_dpp v115, v115, v115 row_mirror row_mask:0xf bank_mask:0xf bound_ctrl:1
	s_nop 1
	v_mov_b32_dpp v117, v115 row_bcast:15 row_mask:0xa bank_mask:0xf
	v_add_f32_e32 v115, v115, v117
	v_mov_b32_e32 v117, 0
	s_nop 1
	v_mov_b32_dpp v117, v115 row_bcast:31 row_mask:0xc bank_mask:0xf
	v_add_f32_e32 v115, v115, v117
	s_nop 0
	v_readlane_b32 s2, v115, 63
	s_nop 1
	v_add_f32_e32 v115, s2, v86
	v_rsq_f32_e32 v117, v115
	v_lshlrev_b32_e32 v115, 16, v78
	v_mov_b32_e32 v54, v115
	v_pk_mul_f32 v[72:73], v[72:73], v[116:117]
	s_nop 0
	v_cvt_pk_bf16_f32 v70, v72, s0
	ds_write_b16 v118, v70 offset:7680
	v_pk_mul_f32 v[116:117], v[10:11], v[114:115]
	v_add_f32_e32 v70, v126, v127
	v_add_f32_e32 v70, v70, v116
	ds_write_b16 v119, v79 offset:3712
	v_add_f32_e32 v70, v70, v117
	v_mul_f32_e32 v79, 0xbfb8aa3b, v129
	v_exp_f32_e32 v79, v79
	v_mul_f32_e32 v116, 0xbfb8aa3b, v70
	v_exp_f32_e32 v116, v116
	v_cvt_pk_bf16_f32 v117, v73, s0
	v_add_f32_e32 v79, 1.0, v79
	v_rcp_f32_e32 v118, v79
	v_add_f32_e32 v79, 1.0, v116
	v_rcp_f32_e32 v116, v79
	ds_write_b16 v119, v117 offset:7808
	v_mul_f32_e32 v117, v129, v118
	v_mov_b32_e32 v118, 0
	v_mul_f32_e32 v116, v70, v116
	v_mul_f32_e32 v70, v117, v117
	v_pk_mul_f32 v[10:11], v[10:11], v[54:55]
	v_lshlrev_b32_e32 v54, 16, v140
	v_mov_b32_dpp v118, v70 quad_perm:[1,0,3,2] row_mask:0xf bank_mask:0xf
	v_fmac_f32_e32 v118, v117, v117
	v_lshlrev_b32_e32 v55, 16, v139
	v_mul_f32_e32 v78, v72, v130
	v_add_f32_dpp v70, v118, v118 quad_perm:[2,3,0,1] row_mask:0xf bank_mask:0xf bound_ctrl:1
	v_mov_b32_e32 v118, 0
	v_mul_f32_e32 v79, v73, v128
	v_add_f32_dpp v70, v70, v70 row_half_mirror row_mask:0xf bank_mask:0xf bound_ctrl:1
	v_and_b32_e32 v127, 7, v22
	s_nop 0
	v_add_f32_dpp v70, v70, v70 row_mirror row_mask:0xf bank_mask:0xf bound_ctrl:1
	s_nop 1
	v_mov_b32_dpp v118, v70 row_bcast:15 row_mask:0xa bank_mask:0xf
	v_add_f32_e32 v70, v70, v118
	v_mov_b32_e32 v118, 0
	s_nop 1
	v_mov_b32_dpp v118, v70 row_bcast:31 row_mask:0xc bank_mask:0xf
	v_add_f32_e32 v70, v70, v118
	v_mov_b32_e32 v118, 0
	v_readlane_b32 s2, v70, 63
	v_mul_f32_e32 v70, v116, v116
	s_nop 0
	v_add_f32_e32 v119, s2, v86
	v_mov_b32_dpp v118, v70 quad_perm:[1,0,3,2] row_mask:0xf bank_mask:0xf
	v_fmac_f32_e32 v118, v116, v116
	v_rsq_f32_e32 v119, v119
	s_nop 0
	v_add_f32_dpp v70, v118, v118 quad_perm:[2,3,0,1] row_mask:0xf bank_mask:0xf bound_ctrl:1
	v_mov_b32_e32 v118, 0
	s_nop 0
	v_add_f32_dpp v70, v70, v70 row_half_mirror row_mask:0xf bank_mask:0xf bound_ctrl:1
	s_nop 1
	v_add_f32_dpp v70, v70, v70 row_mirror row_mask:0xf bank_mask:0xf bound_ctrl:1
	s_nop 1
	v_mov_b32_dpp v118, v70 row_bcast:15 row_mask:0xa bank_mask:0xf
	v_add_f32_e32 v70, v70, v118
	v_mov_b32_e32 v118, 0
	s_nop 1
	v_mov_b32_dpp v118, v70 row_bcast:31 row_mask:0xc bank_mask:0xf
	v_add_f32_e32 v70, v70, v118
	s_nop 0
	v_readlane_b32 s2, v70, 63
	v_mul_f32_e32 v70, v117, v119
	v_mul_f32_e32 v70, 0x3e000000, v70
	v_cvt_pk_bf16_f32 v70, v70, s0
	ds_write_b16 v124, v70 offset:3840
	v_pk_mov_b32 v[70:71], v[70:71], v[114:115] op_sel:[1,0]
	v_add_f32_e32 v117, s2, v86
	v_pk_mul_f32 v[14:15], v[14:15], v[70:71]
	v_rsq_f32_e32 v118, v117
	v_add_f32_e32 v5, v14, v15
	v_add_f32_e32 v5, v5, v10
	v_add_f32_e32 v5, v5, v11
	v_mul_f32_e32 v10, 0xbfb8aa3b, v5
	v_exp_f32_e32 v10, v10
	v_mov_b32_e32 v119, s3
	v_readlane_b32 s2, v102, 30
	v_mov_b32_e32 v15, s4
	v_add_f32_e32 v10, 1.0, v10
	v_rcp_f32_e32 v10, v10
	v_mov_b32_e32 v117, s2
	v_pk_mul_f32 v[116:117], v[116:117], v[118:119]
	v_add_u32_e32 v119, 4, v109
	v_mul_f32_e32 v10, v5, v10
	v_mul_f32_e32 v5, v7, v7
	v_cvt_pk_bf16_f32 v11, v116, s0
	ds_write_b16 v124, v11 offset:7936
	v_mov_b32_dpp v9, v5 quad_perm:[1,0,3,2] row_mask:0xf bank_mask:0xf
	v_fmac_f32_e32 v9, v7, v7
	v_mul_f32_e32 v105, v116, v117
	v_add_u32_e32 v117, 2, v109
	v_add_f32_dpp v5, v9, v9 quad_perm:[2,3,0,1] row_mask:0xf bank_mask:0xf bound_ctrl:1
	v_mov_b32_e32 v9, 0
	v_lshlrev_b32_e32 v115, 2, v109
	v_add_f32_dpp v5, v5, v5 row_half_mirror row_mask:0xf bank_mask:0xf bound_ctrl:1
	v_sub_u32_e32 v128, v96, v115
	s_movk_i32 s4, 0x50
	v_add_f32_dpp v5, v5, v5 row_mirror row_mask:0xf bank_mask:0xf bound_ctrl:1
	s_nop 1
	v_mov_b32_dpp v9, v5 row_bcast:15 row_mask:0xa bank_mask:0xf
	v_add_f32_e32 v5, v5, v9
	v_mov_b32_e32 v9, 0
	s_nop 1
	v_mov_b32_dpp v9, v5 row_bcast:31 row_mask:0xc bank_mask:0xf
	v_add_f32_e32 v5, v5, v9
	v_mov_b32_e32 v9, 0
	v_readlane_b32 s3, v5, 63
	v_mul_f32_e32 v5, v10, v10
	s_nop 0
	v_add_f32_e32 v11, s3, v86
	v_mov_b32_dpp v9, v5 quad_perm:[1,0,3,2] row_mask:0xf bank_mask:0xf
	v_fmac_f32_e32 v9, v10, v10
	v_rsq_f32_e32 v11, v11
	s_nop 0
	v_add_f32_dpp v5, v9, v9 quad_perm:[2,3,0,1] row_mask:0xf bank_mask:0xf bound_ctrl:1
	v_mov_b32_e32 v9, 0
	s_nop 0
	v_add_f32_dpp v5, v5, v5 row_half_mirror row_mask:0xf bank_mask:0xf bound_ctrl:1
	s_nop 1
	v_add_f32_dpp v5, v5, v5 row_mirror row_mask:0xf bank_mask:0xf bound_ctrl:1
	s_nop 1
	v_mov_b32_dpp v9, v5 row_bcast:15 row_mask:0xa bank_mask:0xf
	v_add_f32_e32 v5, v5, v9
	v_mov_b32_e32 v9, 0
	s_nop 1
	v_mov_b32_dpp v9, v5 row_bcast:31 row_mask:0xc bank_mask:0xf
	v_add_f32_e32 v5, v5, v9
	s_nop 0
	v_readlane_b32 s3, v5, 63
	v_mul_f32_e32 v5, v7, v11
	v_mul_f32_e32 v7, 0x3e000000, v5
	v_add_f32_e32 v5, s3, v86
	v_rsq_f32_e32 v14, v5
	v_pk_mul_f32 v[4:5], v[4:5], v[12:13] op_sel_hi:[0,1]
	v_pk_fma_f32 v[4:5], v[2:3], v[68:69], v[4:5] op_sel_hi:[0,1,1]
	v_pk_mov_b32 v[12:13], v[12:13], v[54:55] op_sel:[1,0]
	v_readlane_b32 s3, v102, 31
	v_pk_fma_f32 v[4:5], v[6:7], v[12:13], v[4:5] op_sel_hi:[0,1,1]
	v_pk_fma_f32 v[4:5], v[8:9], v[54:55], v[4:5] op_sel_hi:[0,1,1]
	v_mul_f32_e32 v2, 0xbfb8aa3b, v4
	v_exp_f32_e32 v2, v2
	v_mul_f32_e32 v6, 0xbfb8aa3b, v5
	v_exp_f32_e32 v8, v6
	v_cvt_pk_bf16_f32 v9, v7, s0
	v_add_f32_e32 v2, 1.0, v2
	v_rcp_f32_e32 v6, v2
	v_add_f32_e32 v2, 1.0, v8
	v_rcp_f32_e32 v7, v2
	v_mov_b32_e32 v11, s3
	v_pk_mul_f32 v[10:11], v[10:11], v[14:15]
	ds_write_b16 v125, v9 offset:3968
	v_pk_mul_f32 v[2:3], v[4:5], v[6:7]
	v_cvt_pk_bf16_f32 v4, v64, v65
	v_pk_mul_f32 v[54:55], v[2:3], s[2:3]
	v_cvt_pk_bf16_f32 v2, v10, s0
	ds_write_b16 v125, v2 offset:8064
	v_cvt_pk_bf16_f32 v2, v56, v57
	v_cvt_pk_bf16_f32 v3, v58, v59
	v_cvt_pk_bf16_f32 v5, v66, v67
	v_cvt_pk_bf16_f32 v6, v60, v61
	v_cvt_pk_bf16_f32 v7, v62, v63
	v_cvt_pk_bf16_f32 v8, v72, v73
	v_cvt_pk_bf16_f32 v9, v116, v10
	global_store_dwordx4 v[16:17], v[2:5], off offset:1024
	global_store_dwordx4 v[16:17], v[6:9], off offset:1536
	v_mul_f32_e32 v114, v10, v11
	v_lshlrev_b32_e32 v2, 7, v22
	v_and_b32_e32 v2, 0xf80, v2
	v_add_u32_e32 v64, s51, v2
	v_bitop3_b32 v2, v109, v22, 7 bitop3:0x78
	s_waitcnt lgkmcnt(0)
	v_lshl_add_u32 v116, v2, 4, v64
	ds_read_b128 v[2:5], v116 offset:4096
	ds_read_b128 v[6:9], v116
	s_waitcnt lgkmcnt(0)
	v_mfma_f32_32x32x16_bf16 v[2:17], v[2:5], v[6:9], 0
	v_bitop3_b32 v56, v117, v22, 7 bitop3:0x78
	v_lshl_add_u32 v118, v56, 4, v64
	ds_read_b128 v[56:59], v118 offset:4096
	ds_read_b128 v[60:63], v118
	v_add_u32_e32 v125, 6, v109
	v_readlane_b32 s2, v101, 0
	v_readlane_b32 s3, v101, 4
	s_waitcnt lgkmcnt(0)
	v_mfma_f32_32x32x16_bf16 v[2:17], v[56:59], v[60:63], v[2:17]
	v_bitop3_b32 v56, v119, v22, 7 bitop3:0x78
	v_lshl_add_u32 v124, v56, 4, v64
	ds_read_b128 v[56:59], v124 offset:4096
	ds_read_b128 v[60:63], v124
	s_waitcnt lgkmcnt(0)
	v_mfma_f32_32x32x16_bf16 v[2:17], v[56:59], v[60:63], v[2:17]
	v_bitop3_b32 v56, v125, v22, 7 bitop3:0x78
	v_lshl_add_u32 v126, v56, 4, v64
	ds_read_b128 v[56:59], v126 offset:4096
	ds_read_b128 v[60:63], v126
	s_waitcnt lgkmcnt(0)
	v_mfma_f32_32x32x16_bf16 v[2:17], v[56:59], v[60:63], v[2:17]
	v_mov_b32_e32 v56, s3
	v_mov_b32_e32 v57, s2
	v_cndmask_b32_e32 v56, v56, v57, vcc
	v_sub_f32_e32 v56, v101, v56
	v_mul_f32_e32 v56, 0x3fb8aa3b, v56
	v_readlane_b32 s2, v101, 1
	v_readlane_b32 s3, v101, 5
	v_exp_f32_e32 v64, v56
	v_mov_b32_e32 v57, s2
	v_mov_b32_e32 v56, s3
	v_cndmask_b32_e32 v56, v56, v57, vcc
	v_sub_f32_e32 v56, v101, v56
	v_mul_f32_e32 v56, 0x3fb8aa3b, v56
	v_readlane_b32 s2, v101, 2
	v_readlane_b32 s3, v101, 6
	v_exp_f32_e32 v65, v56
	v_mov_b32_e32 v57, s2
	v_mov_b32_e32 v56, s3
	v_cndmask_b32_e32 v56, v56, v57, vcc
	v_sub_f32_e32 v56, v101, v56
	v_mul_f32_e32 v56, 0x3fb8aa3b, v56
	v_readlane_b32 s2, v101, 3
	v_readlane_b32 s3, v101, 7
	v_exp_f32_e32 v62, v56
	v_mov_b32_e32 v57, s2
	v_mov_b32_e32 v56, s3
	v_cndmask_b32_e32 v56, v56, v57, vcc
	v_sub_f32_e32 v56, v101, v56
	v_mul_f32_e32 v56, 0x3fb8aa3b, v56
	v_readlane_b32 s2, v101, 8
	v_readlane_b32 s3, v101, 12
	v_exp_f32_e32 v63, v56
	v_mov_b32_e32 v57, s2
	v_mov_b32_e32 v56, s3
	v_cndmask_b32_e32 v56, v56, v57, vcc
	v_sub_f32_e32 v56, v101, v56
	v_mul_f32_e32 v56, 0x3fb8aa3b, v56
	v_readlane_b32 s2, v101, 9
	v_readlane_b32 s3, v101, 13
	v_exp_f32_e32 v60, v56
	v_mov_b32_e32 v57, s2
	v_mov_b32_e32 v56, s3
	v_cndmask_b32_e32 v56, v56, v57, vcc
	v_sub_f32_e32 v56, v101, v56
	v_mul_f32_e32 v56, 0x3fb8aa3b, v56
	v_readlane_b32 s2, v101, 10
	v_readlane_b32 s3, v101, 14
	v_exp_f32_e32 v61, v56
	v_mov_b32_e32 v57, s2
	v_mov_b32_e32 v56, s3
	v_cndmask_b32_e32 v56, v56, v57, vcc
	v_sub_f32_e32 v56, v101, v56
	v_mul_f32_e32 v56, 0x3fb8aa3b, v56
	v_readlane_b32 s2, v101, 11
	v_readlane_b32 s3, v101, 15
	v_exp_f32_e32 v58, v56
	v_mov_b32_e32 v57, s2
	v_mov_b32_e32 v56, s3
	v_cndmask_b32_e32 v56, v56, v57, vcc
	v_sub_f32_e32 v56, v101, v56
	v_mul_f32_e32 v56, 0x3fb8aa3b, v56
	v_readlane_b32 s2, v101, 16
	v_readlane_b32 s3, v101, 20
	v_exp_f32_e32 v59, v56
	v_mov_b32_e32 v57, s2
	v_mov_b32_e32 v56, s3
	v_cndmask_b32_e32 v56, v56, v57, vcc
	v_sub_f32_e32 v56, v101, v56
	v_mul_f32_e32 v56, 0x3fb8aa3b, v56
	v_readlane_b32 s2, v101, 17
	v_readlane_b32 s3, v101, 21
	v_exp_f32_e32 v72, v56
	v_mov_b32_e32 v57, s2
	v_mov_b32_e32 v56, s3
	v_cndmask_b32_e32 v56, v56, v57, vcc
	v_sub_f32_e32 v56, v101, v56
	v_mul_f32_e32 v56, 0x3fb8aa3b, v56
	v_readlane_b32 s2, v101, 18
	v_readlane_b32 s3, v101, 22
	v_exp_f32_e32 v73, v56
	v_mov_b32_e32 v57, s2
	v_mov_b32_e32 v56, s3
	v_cndmask_b32_e32 v56, v56, v57, vcc
	v_sub_f32_e32 v56, v101, v56
	v_mul_f32_e32 v56, 0x3fb8aa3b, v56
	v_readlane_b32 s2, v101, 19
	v_readlane_b32 s3, v101, 23
	v_exp_f32_e32 v70, v56
	v_mov_b32_e32 v57, s2
	v_mov_b32_e32 v56, s3
	v_cndmask_b32_e32 v56, v56, v57, vcc
	v_sub_f32_e32 v56, v101, v56
	v_mul_f32_e32 v56, 0x3fb8aa3b, v56
	v_readlane_b32 s2, v101, 24
	v_readlane_b32 s3, v101, 28
	v_exp_f32_e32 v71, v56
	v_mov_b32_e32 v57, s2
	v_mov_b32_e32 v56, s3
	v_cndmask_b32_e32 v56, v56, v57, vcc
	v_sub_f32_e32 v56, v101, v56
	v_mul_f32_e32 v56, 0x3fb8aa3b, v56
	v_readlane_b32 s2, v101, 25
	v_readlane_b32 s3, v101, 29
	v_exp_f32_e32 v68, v56
	v_mov_b32_e32 v57, s2
	v_mov_b32_e32 v56, s3
	v_cndmask_b32_e32 v56, v56, v57, vcc
	v_sub_f32_e32 v56, v101, v56
	v_mul_f32_e32 v56, 0x3fb8aa3b, v56
	v_readlane_b32 s2, v101, 26
	v_readlane_b32 s3, v101, 30
	v_exp_f32_e32 v69, v56
	v_mov_b32_e32 v57, s2
	v_mov_b32_e32 v56, s3
	v_cndmask_b32_e32 v56, v56, v57, vcc
	v_sub_f32_e32 v56, v101, v56
	v_mul_f32_e32 v56, 0x3fb8aa3b, v56
	v_readlane_b32 s2, v101, 27
	v_readlane_b32 s3, v101, 31
	v_pk_mul_f32 v[2:3], v[2:3], v[64:65]
	v_exp_f32_e32 v66, v56
	v_mov_b32_e32 v56, s3
	v_mov_b32_e32 v57, s2
	v_cndmask_b32_e32 v56, v56, v57, vcc
	v_cvt_pk_bf16_f32 v2, v2, v3
	v_cmp_lt_i32_e32 vcc, -1, v128
	v_pk_mul_f32 v[4:5], v[4:5], v[62:63]
	v_pk_mul_f32 v[6:7], v[6:7], v[60:61]
	v_cndmask_b32_e32 v3, 0, v2, vcc
	v_lshrrev_b32_e32 v2, 16, v2
	v_cmp_lt_i32_e32 vcc, 0, v128
	v_pk_mul_f32 v[8:9], v[8:9], v[58:59]
	v_sub_f32_e32 v56, v101, v56
	v_cndmask_b32_e32 v2, 0, v2, vcc
	v_perm_b32 v2, v2, v3, s15
	v_cvt_pk_bf16_f32 v3, v4, v5
	v_cmp_lt_i32_e32 vcc, 1, v128
	v_mul_f32_e32 v56, 0x3fb8aa3b, v56
	v_exp_f32_e32 v67, v56
	v_cndmask_b32_e32 v4, 0, v3, vcc
	v_lshrrev_b32_e32 v3, 16, v3
	v_cmp_lt_i32_e32 vcc, 2, v128
	s_add_u32 s2, s0, 0x2000
	v_lshlrev_b32_e32 v56, 4, v22
	v_cndmask_b32_e32 v3, 0, v3, vcc
	v_perm_b32 v3, v3, v4, s15
	v_cvt_pk_bf16_f32 v4, v6, v7
	v_cmp_lt_i32_e32 vcc, 7, v128
	s_addc_u32 s3, s1, 0
	v_ashrrev_i32_e32 v57, 31, v56
	v_cndmask_b32_e32 v5, 0, v4, vcc
	v_lshrrev_b32_e32 v4, 16, v4
	v_cmp_lt_i32_e32 vcc, 8, v128
	v_pk_mul_f32 v[10:11], v[10:11], v[72:73]
	v_pk_mul_f32 v[12:13], v[12:13], v[70:71]
	v_cndmask_b32_e32 v4, 0, v4, vcc
	v_perm_b32 v4, v4, v5, s15
	v_cvt_pk_bf16_f32 v5, v8, v9
	v_cmp_lt_i32_e32 vcc, 9, v128
	v_pk_mul_f32 v[14:15], v[14:15], v[68:69]
	v_pk_mul_f32 v[16:17], v[16:17], v[66:67]
	v_cndmask_b32_e32 v6, 0, v5, vcc
	v_lshrrev_b32_e32 v5, 16, v5
	v_cmp_lt_i32_e32 vcc, 10, v128
	v_lshl_add_u32 v101, v96, 7, s51
	v_lshl_add_u32 v8, v109, 3, v101
	v_cndmask_b32_e32 v5, 0, v5, vcc
	v_perm_b32 v5, v5, v6, s15
	v_lshl_add_u64 v[6:7], s[2:3], 0, v[56:57]
	flat_store_dwordx4 v[6:7], v[2:5]
	v_cmp_lt_i32_e32 vcc, 15, v128
	v_lshlrev_b32_e32 v9, 4, v127
	v_cvt_pk_bf16_f32 v2, v10, v11
	v_cndmask_b32_e32 v3, 0, v2, vcc
	v_lshrrev_b32_e32 v2, 16, v2
	v_cmp_lt_i32_e32 vcc, 16, v128
	v_lshlrev_b32_e32 v109, 9, v109
	s_nop 0
	v_cndmask_b32_e32 v2, 0, v2, vcc
	v_perm_b32 v2, v2, v3, s15
	v_cvt_pk_bf16_f32 v3, v12, v13
	v_cmp_lt_i32_e32 vcc, 17, v128
	s_nop 1
	v_cndmask_b32_e32 v4, 0, v3, vcc
	v_lshrrev_b32_e32 v3, 16, v3
	v_cmp_lt_i32_e32 vcc, 18, v128
	s_nop 1
	v_cndmask_b32_e32 v3, 0, v3, vcc
	v_perm_b32 v3, v3, v4, s15
	v_cvt_pk_bf16_f32 v4, v14, v15
	v_cmp_lt_i32_e32 vcc, 23, v128
	s_nop 1
	v_cndmask_b32_e32 v5, 0, v4, vcc
	v_lshrrev_b32_e32 v4, 16, v4
	v_cmp_lt_i32_e32 vcc, 24, v128
	s_nop 1
	v_cndmask_b32_e32 v4, 0, v4, vcc
	v_perm_b32 v4, v4, v5, s15
	v_cvt_pk_bf16_f32 v5, v16, v17
	v_cmp_lt_i32_e32 vcc, 25, v128
	s_nop 1
	v_cndmask_b32_e32 v6, 0, v5, vcc
	v_lshrrev_b32_e32 v5, 16, v5
	v_cmp_lt_i32_e32 vcc, 26, v128
	s_nop 1
	v_cndmask_b32_e32 v5, 0, v5, vcc
	v_perm_b32 v5, v5, v6, s15
	v_add_u32_e32 v6, 0x400, v56
	v_ashrrev_i32_e32 v7, 31, v6
	v_lshl_add_u64 v[6:7], s[2:3], 0, v[6:7]
	flat_store_dwordx4 v[6:7], v[2:5]
	s_add_u32 s2, s0, 0x1000
	v_or_b32_e32 v6, v109, v108
	v_add_u32_e32 v2, v8, v9
	v_xad_u32 v4, v9, 16, v8
	ds_read_b64 v[2:3], v2
	ds_read_b64 v[4:5], v4
	s_addc_u32 s3, s1, 0
	v_ashrrev_i32_e32 v7, 31, v6
	v_lshl_add_u64 v[6:7], s[2:3], 0, v[6:7]
	v_cmp_gt_i32_e32 vcc, v96, v115
	s_waitcnt lgkmcnt(0)
	flat_store_dwordx4 v[6:7], v[2:5]
	v_lshl_or_b32 v6, v117, 9, v108
	v_ashrrev_i32_e32 v7, 31, v6
	v_xad_u32 v2, v9, 32, v8
	v_xad_u32 v4, v9, 48, v8
	ds_read_b64 v[2:3], v2
	ds_read_b64 v[4:5], v4
	v_lshl_add_u64 v[6:7], s[2:3], 0, v[6:7]
	s_waitcnt lgkmcnt(0)
	flat_store_dwordx4 v[6:7], v[2:5]
	s_nop 1
	v_xad_u32 v2, v9, 64, v8
	v_xad_u32 v4, v9, s4, v8
	ds_read_b64 v[2:3], v2
	ds_read_b64 v[4:5], v4
	v_lshl_or_b32 v6, v119, 9, v108
	v_ashrrev_i32_e32 v7, 31, v6
	v_lshl_add_u64 v[6:7], s[2:3], 0, v[6:7]
	s_movk_i32 s4, 0x60
	s_waitcnt lgkmcnt(0)
	flat_store_dwordx4 v[6:7], v[2:5]
	v_lshl_or_b32 v6, v125, 9, v108
	v_ashrrev_i32_e32 v7, 31, v6
	v_xad_u32 v2, v9, s4, v8
	s_movk_i32 s4, 0x70
	v_xad_u32 v4, v9, s4, v8
	ds_read_b64 v[2:3], v2
	ds_read_b64 v[4:5], v4
	v_lshl_add_u64 v[6:7], s[2:3], 0, v[6:7]
	s_movk_i32 s2, 0xff84
	v_mad_i32_i24 v101, v96, s2, v101
	s_add_u32 s2, s0, 0x3800
	s_waitcnt lgkmcnt(0)
	flat_store_dwordx4 v[6:7], v[2:5]
	ds_read_b128 v[2:5], v116 offset:4096
	ds_read_b128 v[116:119], v118 offset:4096
	s_waitcnt lgkmcnt(0)
	v_mfma_f32_32x32x16_bf16 v[2:17], v[2:5], v[2:5], 0
	s_addc_u32 s3, s1, 0
	v_mfma_f32_32x32x16_bf16 v[2:17], v[116:119], v[116:119], v[2:17]
	ds_read_b128 v[116:119], v124 offset:4096
	ds_read_b128 v[124:127], v126 offset:4096
	s_waitcnt lgkmcnt(0)
	v_mfma_f32_32x32x16_bf16 v[2:17], v[116:119], v[116:119], v[2:17]
	v_mfma_f32_32x32x16_bf16 v[2:17], v[124:127], v[124:127], v[2:17]
	s_nop 11
	v_mul_f32_e32 v2, v102, v2
	v_mul_f32_e32 v2, v2, v64
	v_cndmask_b32_e32 v2, 0, v2, vcc
	v_add_u32_e32 v64, v101, v109
	ds_write_b32 v64, v2 offset:8192
	v_or_b32_e32 v2, 1, v115
	v_mul_f32_e32 v3, v102, v3
	v_mul_f32_e32 v3, v3, v65
	v_cmp_gt_i32_e32 vcc, v96, v2
	v_lshl_add_u32 v2, v2, 7, v101
	s_nop 0
	v_cndmask_b32_e32 v3, 0, v3, vcc
	ds_write_b32 v2, v3 offset:8192
	v_or_b32_e32 v2, 2, v115
	v_mul_f32_e32 v3, v102, v4
	v_mul_f32_e32 v3, v3, v62
	v_cmp_gt_i32_e32 vcc, v96, v2
	v_lshl_add_u32 v2, v2, 7, v101
	s_nop 0
	v_cndmask_b32_e32 v3, 0, v3, vcc
	ds_write_b32 v2, v3 offset:8192
	v_or_b32_e32 v2, 3, v115
	v_mul_f32_e32 v3, v102, v5
	v_mul_f32_e32 v3, v3, v63
	v_cmp_gt_i32_e32 vcc, v96, v2
	v_lshl_add_u32 v2, v2, 7, v101
	s_nop 0
	v_cndmask_b32_e32 v3, 0, v3, vcc
	ds_write_b32 v2, v3 offset:8192
	v_add_u32_e32 v2, 8, v115
	v_mul_f32_e32 v3, v102, v6
	v_mul_f32_e32 v3, v3, v60
	v_cmp_gt_i32_e32 vcc, v96, v2
	v_lshl_add_u32 v2, v2, 7, v101
	s_nop 0
	v_cndmask_b32_e32 v3, 0, v3, vcc
	ds_write_b32 v2, v3 offset:8192
	v_add_u32_e32 v2, 9, v115
	v_mul_f32_e32 v3, v102, v7
	v_mul_f32_e32 v3, v3, v61
	v_cmp_gt_i32_e32 vcc, v96, v2
	v_lshl_add_u32 v2, v2, 7, v101
	s_nop 0
	v_cndmask_b32_e32 v3, 0, v3, vcc
	ds_write_b32 v2, v3 offset:8192
	v_add_u32_e32 v2, 10, v115
	v_mul_f32_e32 v3, v102, v8
	v_mul_f32_e32 v3, v3, v58
	v_cmp_gt_i32_e32 vcc, v96, v2
	v_lshl_add_u32 v2, v2, 7, v101
	v_mov_b32_e32 v58, 0
	v_cndmask_b32_e32 v3, 0, v3, vcc
	ds_write_b32 v2, v3 offset:8192
	v_add_u32_e32 v2, 11, v115
	v_mul_f32_e32 v3, v102, v9
	v_mul_f32_e32 v3, v3, v59
	v_cmp_gt_i32_e32 vcc, v96, v2
	v_lshl_add_u32 v2, v2, 7, v101
	s_nop 0
	v_cndmask_b32_e32 v3, 0, v3, vcc
	ds_write_b32 v2, v3 offset:8192
	v_add_u32_e32 v2, 16, v115
	v_mul_f32_e32 v3, v102, v10
	v_mul_f32_e32 v3, v3, v72
	v_cmp_gt_i32_e32 vcc, v96, v2
	v_lshl_add_u32 v2, v2, 7, v101
	s_nop 0
	v_cndmask_b32_e32 v3, 0, v3, vcc
	ds_write_b32 v2, v3 offset:8192
	v_add_u32_e32 v2, 17, v115
	v_mul_f32_e32 v3, v102, v11
	v_mul_f32_e32 v3, v3, v73
	v_cmp_gt_i32_e32 vcc, v96, v2
	v_lshl_add_u32 v2, v2, 7, v101
	s_nop 0
	v_cndmask_b32_e32 v3, 0, v3, vcc
	ds_write_b32 v2, v3 offset:8192
	v_add_u32_e32 v2, 18, v115
	v_mul_f32_e32 v3, v102, v12
	v_mul_f32_e32 v3, v3, v70
	v_cmp_gt_i32_e32 vcc, v96, v2
	v_lshl_add_u32 v2, v2, 7, v101
	s_nop 0
	v_cndmask_b32_e32 v3, 0, v3, vcc
	ds_write_b32 v2, v3 offset:8192
	v_add_u32_e32 v2, 19, v115
	v_mul_f32_e32 v3, v102, v13
	v_mul_f32_e32 v3, v3, v71
	v_cmp_gt_i32_e32 vcc, v96, v2
	v_lshl_add_u32 v2, v2, 7, v101
	s_nop 0
	v_cndmask_b32_e32 v3, 0, v3, vcc
	ds_write_b32 v2, v3 offset:8192
	v_add_u32_e32 v2, 24, v115
	v_mul_f32_e32 v3, v102, v14
	v_mul_f32_e32 v3, v3, v68
	v_cmp_gt_i32_e32 vcc, v96, v2
	v_lshl_add_u32 v2, v2, 7, v101
	s_nop 0
	v_cndmask_b32_e32 v3, 0, v3, vcc
	ds_write_b32 v2, v3 offset:8192
	v_add_u32_e32 v2, 25, v115
	v_mul_f32_e32 v3, v102, v15
	v_mul_f32_e32 v3, v3, v69
	v_cmp_gt_i32_e32 vcc, v96, v2
	v_lshl_add_u32 v2, v2, 7, v101
	s_nop 0
	v_cndmask_b32_e32 v3, 0, v3, vcc
	ds_write_b32 v2, v3 offset:8192
	v_add_u32_e32 v2, 26, v115
	v_mul_f32_e32 v3, v102, v16
	v_mul_f32_e32 v3, v3, v66
	v_cmp_gt_i32_e32 vcc, v96, v2
	v_lshl_add_u32 v2, v2, 7, v101
	s_nop 0
	v_cndmask_b32_e32 v3, 0, v3, vcc
	ds_write_b32 v2, v3 offset:8192
	v_add_u32_e32 v2, 27, v115
	v_mul_f32_e32 v3, v102, v17
	v_mul_f32_e32 v3, v3, v67
	v_cmp_gt_i32_e32 vcc, v96, v2
	v_lshl_add_u32 v2, v2, 7, v101
	s_nop 0
	v_cndmask_b32_e32 v3, 0, v3, vcc
	ds_write_b32 v2, v3 offset:8192
	s_waitcnt lgkmcnt(0)
	s_nop 0
	v_add_u32_e32 v14, s51, v58
	ds_read_b128 v[2:5], v14 offset:8192
	ds_read_b128 v[6:9], v14 offset:8208
	ds_read_b128 v[10:13], v14 offset:8224
	ds_read_b128 v[14:17], v14 offset:8240
	s_waitcnt lgkmcnt(0)
	v_fma_f32 v36, -v14, v24, v36
	v_fma_f32 v104, -v14, v88, v104
	v_fma_f32 v39, -v17, v24, v39
	v_fma_f32 v25, -v3, v24, v25
	v_fma_f32 v90, -v3, v88, v90
	v_fma_f32 v26, -v4, v24, v26
	v_fma_f32 v89, -v4, v88, v89
	v_fma_f32 v27, -v5, v24, v27
	s_nop 0
	v_fma_f32 v91, -v5, v88, v91
	v_fma_f32 v28, -v6, v24, v28
	v_fma_f32 v92, -v6, v88, v92
	v_fma_f32 v29, -v7, v24, v29
	v_fma_f32 v93, -v7, v88, v93
	s_nop 0
	v_add_u32_e32 v14, s51, v58
	v_fma_f32 v30, -v8, v24, v30
	v_fma_f32 v94, -v8, v88, v94
	v_fma_f32 v31, -v9, v24, v31
	v_fma_f32 v95, -v9, v88, v95
	v_fma_f32 v32, -v10, v24, v32
	v_fma_f32 v98, -v10, v88, v98
	v_fma_f32 v33, -v11, v24, v33
	v_fma_f32 v97, -v11, v88, v97
	v_fma_f32 v34, -v12, v24, v34
	v_fma_f32 v100, -v12, v88, v100
	v_fma_f32 v35, -v13, v24, v35
	v_fma_f32 v99, -v13, v88, v99
	v_fma_f32 v37, -v15, v24, v37
	v_fma_f32 v103, -v15, v88, v103
	v_fma_f32 v38, -v16, v24, v38
	v_fma_f32 v107, -v16, v88, v107
	ds_read_b128 v[2:5], v14 offset:8256
	v_fma_f32 v106, -v17, v88, v106
	ds_read_b128 v[6:9], v14 offset:8272
	ds_read_b128 v[10:13], v14 offset:8288
	ds_read_b128 v[14:17], v14 offset:8304
	v_mov_b32_e32 v58, 0x80
	s_waitcnt lgkmcnt(0)
	v_fma_f32 v52, -v14, v24, v52
	v_fma_f32 v78, -v14, v88, v78
	v_fma_f32 v40, -v2, v24, v40
	v_fma_f32 v111, -v2, v88, v111
	v_fma_f32 v41, -v3, v24, v41
	v_fma_f32 v110, -v3, v88, v110
	v_fma_f32 v42, -v4, v24, v42
	s_nop 0
	v_add_u32_e32 v14, s51, v58
	v_fma_f32 v113, -v4, v88, v113
	v_fma_f32 v43, -v5, v24, v43
	v_fma_f32 v112, -v5, v88, v112
	v_fma_f32 v46, -v6, v24, v46
	v_fma_f32 v121, -v6, v88, v121
	v_fma_f32 v47, -v7, v24, v47
	v_fma_f32 v120, -v7, v88, v120
	v_fma_f32 v48, -v8, v24, v48
	v_fma_f32 v123, -v8, v88, v123
	v_fma_f32 v49, -v9, v24, v49
	v_fma_f32 v122, -v9, v88, v122
	v_fma_f32 v44, -v10, v24, v44
	v_fma_f32 v74, -v10, v88, v74
	v_fma_f32 v45, -v11, v24, v45
	v_fma_f32 v75, -v11, v88, v75
	v_fma_f32 v50, -v12, v24, v50
	v_fma_f32 v76, -v12, v88, v76
	v_fma_f32 v51, -v13, v24, v51
	v_fma_f32 v77, -v13, v88, v77
	v_fma_f32 v53, -v15, v24, v53
	v_fma_f32 v79, -v15, v88, v79
	v_fma_f32 v54, -v16, v24, v54
	v_fma_f32 v105, -v16, v88, v105
	v_fma_f32 v55, -v17, v24, v55
	ds_read_b128 v[2:5], v14 offset:8192
	v_fma_f32 v114, -v17, v88, v114
	ds_read_b128 v[6:9], v14 offset:8208
	ds_read_b128 v[10:13], v14 offset:8224
	ds_read_b128 v[14:17], v14 offset:8240
	s_waitcnt lgkmcnt(0)
	v_fma_f32 v36, -v14, v25, v36
	v_fma_f32 v104, -v14, v90, v104
	v_fma_f32 v39, -v17, v25, v39
	v_fma_f32 v26, -v4, v25, v26
	v_fma_f32 v89, -v4, v90, v89
	v_fma_f32 v27, -v5, v25, v27
	v_fma_f32 v91, -v5, v90, v91
	v_fma_f32 v28, -v6, v25, v28
	s_nop 0
	v_fma_f32 v92, -v6, v90, v92
	v_fma_f32 v29, -v7, v25, v29
	v_fma_f32 v93, -v7, v90, v93
	v_fma_f32 v30, -v8, v25, v30
	v_fma_f32 v94, -v8, v90, v94
	s_nop 0
	v_add_u32_e32 v14, s51, v58
	v_fma_f32 v31, -v9, v25, v31
	v_fma_f32 v95, -v9, v90, v95
	v_fma_f32 v32, -v10, v25, v32
	v_fma_f32 v98, -v10, v90, v98
	v_fma_f32 v33, -v11, v25, v33
	v_fma_f32 v97, -v11, v90, v97
	v_fma_f32 v34, -v12, v25, v34
	v_fma_f32 v100, -v12, v90, v100
	v_fma_f32 v35, -v13, v25, v35
	v_fma_f32 v99, -v13, v90, v99
	v_fma_f32 v37, -v15, v25, v37
	v_fma_f32 v103, -v15, v90, v103
	v_fma_f32 v38, -v16, v25, v38
	v_fma_f32 v107, -v16, v90, v107
	ds_read_b128 v[2:5], v14 offset:8256
	v_fma_f32 v106, -v17, v90, v106
	ds_read_b128 v[6:9], v14 offset:8272
	ds_read_b128 v[10:13], v14 offset:8288
	ds_read_b128 v[14:17], v14 offset:8304
	v_mov_b32_e32 v58, 0x100
	s_waitcnt lgkmcnt(0)
	v_fma_f32 v52, -v14, v25, v52
	v_fma_f32 v78, -v14, v90, v78
	v_fma_f32 v40, -v2, v25, v40
	v_fma_f32 v111, -v2, v90, v111
	v_fma_f32 v41, -v3, v25, v41
	v_fma_f32 v110, -v3, v90, v110
	v_fma_f32 v42, -v4, v25, v42
	s_nop 0
	v_add_u32_e32 v14, s51, v58
	v_fma_f32 v113, -v4, v90, v113
	v_fma_f32 v43, -v5, v25, v43
	v_fma_f32 v112, -v5, v90, v112
	v_fma_f32 v46, -v6, v25, v46
	v_fma_f32 v121, -v6, v90, v121
	v_fma_f32 v47, -v7, v25, v47
	v_fma_f32 v120, -v7, v90, v120
	v_fma_f32 v48, -v8, v25, v48
	v_fma_f32 v123, -v8, v90, v123
	v_fma_f32 v49, -v9, v25, v49
	v_fma_f32 v122, -v9, v90, v122
	v_fma_f32 v44, -v10, v25, v44
	v_fma_f32 v74, -v10, v90, v74
	v_fma_f32 v45, -v11, v25, v45
	v_fma_f32 v75, -v11, v90, v75
	v_fma_f32 v50, -v12, v25, v50
	v_fma_f32 v76, -v12, v90, v76
	v_fma_f32 v51, -v13, v25, v51
	v_fma_f32 v77, -v13, v90, v77
	v_fma_f32 v53, -v15, v25, v53
	v_fma_f32 v79, -v15, v90, v79
	v_fma_f32 v54, -v16, v25, v54
	v_fma_f32 v105, -v16, v90, v105
	v_fma_f32 v55, -v17, v25, v55
	ds_read_b128 v[2:5], v14 offset:8192
	v_fma_f32 v114, -v17, v90, v114
	ds_read_b128 v[6:9], v14 offset:8208
	ds_read_b128 v[10:13], v14 offset:8224
	ds_read_b128 v[14:17], v14 offset:8240
	s_waitcnt lgkmcnt(0)
	v_fma_f32 v36, -v14, v26, v36
	v_fma_f32 v104, -v14, v89, v104
	v_fma_f32 v39, -v17, v26, v39
	v_fma_f32 v27, -v5, v26, v27
	v_fma_f32 v91, -v5, v89, v91
	v_fma_f32 v28, -v6, v26, v28
	v_fma_f32 v92, -v6, v89, v92
	v_fma_f32 v29, -v7, v26, v29
	s_nop 0
	v_fma_f32 v93, -v7, v89, v93
	v_fma_f32 v30, -v8, v26, v30
	v_fma_f32 v94, -v8, v89, v94
	v_fma_f32 v31, -v9, v26, v31
	v_fma_f32 v95, -v9, v89, v95
	s_nop 0
	v_add_u32_e32 v14, s51, v58
	v_fma_f32 v32, -v10, v26, v32
	v_fma_f32 v98, -v10, v89, v98
	v_fma_f32 v33, -v11, v26, v33
	v_fma_f32 v97, -v11, v89, v97
	v_fma_f32 v34, -v12, v26, v34
	v_fma_f32 v100, -v12, v89, v100
	v_fma_f32 v35, -v13, v26, v35
	v_fma_f32 v99, -v13, v89, v99
	v_fma_f32 v37, -v15, v26, v37
	v_fma_f32 v103, -v15, v89, v103
	v_fma_f32 v38, -v16, v26, v38
	v_fma_f32 v107, -v16, v89, v107
	ds_read_b128 v[2:5], v14 offset:8256
	v_fma_f32 v106, -v17, v89, v106
	ds_read_b128 v[6:9], v14 offset:8272
	ds_read_b128 v[10:13], v14 offset:8288
	ds_read_b128 v[14:17], v14 offset:8304
	v_mov_b32_e32 v58, 0x180
	s_waitcnt lgkmcnt(0)
	v_fma_f32 v52, -v14, v26, v52
	v_fma_f32 v78, -v14, v89, v78
	v_fma_f32 v40, -v2, v26, v40
	v_fma_f32 v111, -v2, v89, v111
	v_fma_f32 v41, -v3, v26, v41
	v_fma_f32 v110, -v3, v89, v110
	v_fma_f32 v42, -v4, v26, v42
	s_nop 0
	v_add_u32_e32 v14, s51, v58
	v_fma_f32 v113, -v4, v89, v113
	v_fma_f32 v43, -v5, v26, v43
	v_fma_f32 v112, -v5, v89, v112
	v_fma_f32 v46, -v6, v26, v46
	v_fma_f32 v121, -v6, v89, v121
	v_fma_f32 v47, -v7, v26, v47
	v_fma_f32 v120, -v7, v89, v120
	v_fma_f32 v48, -v8, v26, v48
	v_fma_f32 v123, -v8, v89, v123
	v_fma_f32 v49, -v9, v26, v49
	v_fma_f32 v122, -v9, v89, v122
	v_fma_f32 v44, -v10, v26, v44
	v_fma_f32 v74, -v10, v89, v74
	v_fma_f32 v45, -v11, v26, v45
	v_fma_f32 v75, -v11, v89, v75
	v_fma_f32 v50, -v12, v26, v50
	v_fma_f32 v76, -v12, v89, v76
	v_fma_f32 v51, -v13, v26, v51
	v_fma_f32 v77, -v13, v89, v77
	v_fma_f32 v53, -v15, v26, v53
	v_fma_f32 v79, -v15, v89, v79
	v_fma_f32 v54, -v16, v26, v54
	v_fma_f32 v105, -v16, v89, v105
	v_fma_f32 v55, -v17, v26, v55
	ds_read_b128 v[2:5], v14 offset:8208
	v_fma_f32 v114, -v17, v89, v114
	ds_read_b128 v[6:9], v14 offset:8224
	ds_read_b128 v[10:13], v14 offset:8240
	ds_read_b128 v[14:17], v14 offset:8256
	s_waitcnt lgkmcnt(0)
	v_fma_f32 v36, -v10, v27, v36
	v_fma_f32 v104, -v10, v91, v104
	v_fma_f32 v43, -v17, v27, v43
	v_fma_f32 v28, -v2, v27, v28
	v_fma_f32 v92, -v2, v91, v92
	v_fma_f32 v29, -v3, v27, v29
	v_fma_f32 v93, -v3, v91, v93
	v_fma_f32 v30, -v4, v27, v30
	s_nop 0
	v_fma_f32 v94, -v4, v91, v94
	v_fma_f32 v31, -v5, v27, v31
	v_fma_f32 v95, -v5, v91, v95
	v_fma_f32 v32, -v6, v27, v32
	v_fma_f32 v98, -v6, v91, v98
	s_nop 0
	v_add_u32_e32 v10, s51, v58
	v_fma_f32 v33, -v7, v27, v33
	v_fma_f32 v97, -v7, v91, v97
	v_fma_f32 v34, -v8, v27, v34
	v_fma_f32 v100, -v8, v91, v100
	v_fma_f32 v35, -v9, v27, v35
	v_fma_f32 v99, -v9, v91, v99
	v_fma_f32 v37, -v11, v27, v37
	v_fma_f32 v103, -v11, v91, v103
	v_fma_f32 v38, -v12, v27, v38
	v_fma_f32 v107, -v12, v91, v107
	v_fma_f32 v39, -v13, v27, v39
	v_fma_f32 v106, -v13, v91, v106
	ds_read_b128 v[2:5], v10 offset:8272
	ds_read_b128 v[6:9], v10 offset:8288
	ds_read_b128 v[10:13], v10 offset:8304
	v_mov_b32_e32 v58, 0x200
	v_fma_f32 v40, -v14, v27, v40
	v_fma_f32 v111, -v14, v91, v111
	v_fma_f32 v41, -v15, v27, v41
	v_fma_f32 v110, -v15, v91, v110
	v_fma_f32 v42, -v16, v27, v42
	v_fma_f32 v113, -v16, v91, v113
	v_fma_f32 v112, -v17, v91, v112
	s_nop 0
	v_add_u32_e32 v14, s51, v58
	s_waitcnt lgkmcnt(0)
	v_fma_f32 v46, -v2, v27, v46
	v_fma_f32 v121, -v2, v91, v121
	v_fma_f32 v47, -v3, v27, v47
	v_fma_f32 v120, -v3, v91, v120
	v_fma_f32 v48, -v4, v27, v48
	v_fma_f32 v123, -v4, v91, v123
	v_fma_f32 v49, -v5, v27, v49
	v_fma_f32 v122, -v5, v91, v122
	v_fma_f32 v44, -v6, v27, v44
	v_fma_f32 v74, -v6, v91, v74
	v_fma_f32 v45, -v7, v27, v45
	v_fma_f32 v75, -v7, v91, v75
	v_fma_f32 v50, -v8, v27, v50
	v_fma_f32 v76, -v8, v91, v76
	v_fma_f32 v51, -v9, v27, v51
	v_fma_f32 v77, -v9, v91, v77
	v_fma_f32 v52, -v10, v27, v52
	v_fma_f32 v78, -v10, v91, v78
	v_fma_f32 v53, -v11, v27, v53
	v_fma_f32 v79, -v11, v91, v79
	v_fma_f32 v54, -v12, v27, v54
	v_fma_f32 v105, -v12, v91, v105
	v_fma_f32 v55, -v13, v27, v55
	ds_read_b128 v[2:5], v14 offset:8208
	v_fma_f32 v114, -v13, v91, v114
	ds_read_b128 v[6:9], v14 offset:8224
	ds_read_b128 v[10:13], v14 offset:8240
	ds_read_b128 v[14:17], v14 offset:8256
	s_waitcnt lgkmcnt(0)
	v_fma_f32 v36, -v10, v28, v36
	v_fma_f32 v104, -v10, v92, v104
	v_fma_f32 v43, -v17, v28, v43
	v_fma_f32 v29, -v3, v28, v29
	v_fma_f32 v93, -v3, v92, v93
	v_fma_f32 v30, -v4, v28, v30
	v_fma_f32 v94, -v4, v92, v94
	v_fma_f32 v31, -v5, v28, v31
	s_nop 0
	v_fma_f32 v95, -v5, v92, v95
	v_fma_f32 v32, -v6, v28, v32
	v_fma_f32 v98, -v6, v92, v98
	v_fma_f32 v33, -v7, v28, v33
	v_fma_f32 v97, -v7, v92, v97
	s_nop 0
	v_add_u32_e32 v10, s51, v58
	v_fma_f32 v34, -v8, v28, v34
	v_fma_f32 v100, -v8, v92, v100
	v_fma_f32 v35, -v9, v28, v35
	v_fma_f32 v99, -v9, v92, v99
	v_fma_f32 v37, -v11, v28, v37
	v_fma_f32 v103, -v11, v92, v103
	v_fma_f32 v38, -v12, v28, v38
	v_fma_f32 v107, -v12, v92, v107
	v_fma_f32 v39, -v13, v28, v39
	v_fma_f32 v106, -v13, v92, v106
	ds_read_b128 v[2:5], v10 offset:8272
	ds_read_b128 v[6:9], v10 offset:8288
	ds_read_b128 v[10:13], v10 offset:8304
	v_mov_b32_e32 v58, 0x280
	v_fma_f32 v40, -v14, v28, v40
	v_fma_f32 v111, -v14, v92, v111
	v_fma_f32 v41, -v15, v28, v41
	v_fma_f32 v110, -v15, v92, v110
	v_fma_f32 v42, -v16, v28, v42
	v_fma_f32 v113, -v16, v92, v113
	v_fma_f32 v112, -v17, v92, v112
	s_nop 0
	v_add_u32_e32 v14, s51, v58
	s_waitcnt lgkmcnt(0)
	v_fma_f32 v46, -v2, v28, v46
	v_fma_f32 v121, -v2, v92, v121
	v_fma_f32 v47, -v3, v28, v47
	v_fma_f32 v120, -v3, v92, v120
	v_fma_f32 v48, -v4, v28, v48
	v_fma_f32 v123, -v4, v92, v123
	v_fma_f32 v49, -v5, v28, v49
	v_fma_f32 v122, -v5, v92, v122
	v_fma_f32 v44, -v6, v28, v44
	v_fma_f32 v74, -v6, v92, v74
	v_fma_f32 v45, -v7, v28, v45
	v_fma_f32 v75, -v7, v92, v75
	v_fma_f32 v50, -v8, v28, v50
	v_fma_f32 v76, -v8, v92, v76
	v_fma_f32 v51, -v9, v28, v51
	v_fma_f32 v77, -v9, v92, v77
	v_fma_f32 v52, -v10, v28, v52
	v_fma_f32 v78, -v10, v92, v78
	v_fma_f32 v53, -v11, v28, v53
	v_fma_f32 v79, -v11, v92, v79
	v_fma_f32 v54, -v12, v28, v54
	v_fma_f32 v105, -v12, v92, v105
	v_fma_f32 v55, -v13, v28, v55
	ds_read_b128 v[2:5], v14 offset:8208
	v_fma_f32 v114, -v13, v92, v114
	ds_read_b128 v[6:9], v14 offset:8224
	ds_read_b128 v[10:13], v14 offset:8240
	ds_read_b128 v[14:17], v14 offset:8256
	s_waitcnt lgkmcnt(0)
	v_fma_f32 v36, -v10, v29, v36
	v_fma_f32 v104, -v10, v93, v104
	v_fma_f32 v43, -v17, v29, v43
	v_fma_f32 v30, -v4, v29, v30
	v_fma_f32 v94, -v4, v93, v94
	v_fma_f32 v31, -v5, v29, v31
	v_fma_f32 v95, -v5, v93, v95
	v_fma_f32 v32, -v6, v29, v32
	s_nop 0
	v_fma_f32 v98, -v6, v93, v98
	v_fma_f32 v33, -v7, v29, v33
	v_fma_f32 v97, -v7, v93, v97
	v_fma_f32 v34, -v8, v29, v34
	v_fma_f32 v100, -v8, v93, v100
	s_nop 0
	v_add_u32_e32 v10, s51, v58
	v_fma_f32 v35, -v9, v29, v35
	v_fma_f32 v99, -v9, v93, v99
	v_fma_f32 v37, -v11, v29, v37
	v_fma_f32 v103, -v11, v93, v103
	v_fma_f32 v38, -v12, v29, v38
	v_fma_f32 v107, -v12, v93, v107
	v_fma_f32 v39, -v13, v29, v39
	v_fma_f32 v106, -v13, v93, v106
	ds_read_b128 v[2:5], v10 offset:8272
	ds_read_b128 v[6:9], v10 offset:8288
	ds_read_b128 v[10:13], v10 offset:8304
	v_mov_b32_e32 v58, 0x300
	v_fma_f32 v40, -v14, v29, v40
	v_fma_f32 v111, -v14, v93, v111
	v_fma_f32 v41, -v15, v29, v41
	v_fma_f32 v110, -v15, v93, v110
	v_fma_f32 v42, -v16, v29, v42
	v_fma_f32 v113, -v16, v93, v113
	v_fma_f32 v112, -v17, v93, v112
	s_nop 0
	v_add_u32_e32 v14, s51, v58
	s_waitcnt lgkmcnt(0)
	v_fma_f32 v46, -v2, v29, v46
	v_fma_f32 v121, -v2, v93, v121
	v_fma_f32 v47, -v3, v29, v47
	v_fma_f32 v120, -v3, v93, v120
	v_fma_f32 v48, -v4, v29, v48
	v_fma_f32 v123, -v4, v93, v123
	v_fma_f32 v49, -v5, v29, v49
	v_fma_f32 v122, -v5, v93, v122
	v_fma_f32 v44, -v6, v29, v44
	v_fma_f32 v74, -v6, v93, v74
	v_fma_f32 v45, -v7, v29, v45
	v_fma_f32 v75, -v7, v93, v75
	v_fma_f32 v50, -v8, v29, v50
	v_fma_f32 v76, -v8, v93, v76
	v_fma_f32 v51, -v9, v29, v51
	v_fma_f32 v77, -v9, v93, v77
	v_fma_f32 v52, -v10, v29, v52
	v_fma_f32 v78, -v10, v93, v78
	v_fma_f32 v53, -v11, v29, v53
	v_fma_f32 v79, -v11, v93, v79
	v_fma_f32 v54, -v12, v29, v54
	v_fma_f32 v105, -v12, v93, v105
	v_fma_f32 v55, -v13, v29, v55
	ds_read_b128 v[2:5], v14 offset:8208
	v_fma_f32 v114, -v13, v93, v114
	ds_read_b128 v[6:9], v14 offset:8224
	ds_read_b128 v[10:13], v14 offset:8240
	ds_read_b128 v[14:17], v14 offset:8256
	s_waitcnt lgkmcnt(0)
	v_fma_f32 v36, -v10, v30, v36
	v_fma_f32 v104, -v10, v94, v104
	v_fma_f32 v43, -v17, v30, v43
	v_fma_f32 v31, -v5, v30, v31
	v_fma_f32 v95, -v5, v94, v95
	v_fma_f32 v32, -v6, v30, v32
	v_fma_f32 v98, -v6, v94, v98
	v_fma_f32 v33, -v7, v30, v33
	s_nop 0
	v_fma_f32 v97, -v7, v94, v97
	v_fma_f32 v34, -v8, v30, v34
	v_fma_f32 v100, -v8, v94, v100
	v_fma_f32 v35, -v9, v30, v35
	v_fma_f32 v99, -v9, v94, v99
	s_nop 0
	v_add_u32_e32 v10, s51, v58
	v_fma_f32 v37, -v11, v30, v37
	v_fma_f32 v103, -v11, v94, v103
	v_fma_f32 v38, -v12, v30, v38
	v_fma_f32 v107, -v12, v94, v107
	v_fma_f32 v39, -v13, v30, v39
	v_fma_f32 v106, -v13, v94, v106
	ds_read_b128 v[2:5], v10 offset:8272
	ds_read_b128 v[6:9], v10 offset:8288
	ds_read_b128 v[10:13], v10 offset:8304
	v_mov_b32_e32 v58, 0x380
	v_fma_f32 v40, -v14, v30, v40
	v_fma_f32 v111, -v14, v94, v111
	v_fma_f32 v41, -v15, v30, v41
	v_fma_f32 v110, -v15, v94, v110
	v_fma_f32 v42, -v16, v30, v42
	v_fma_f32 v113, -v16, v94, v113
	v_fma_f32 v112, -v17, v94, v112
	s_nop 0
	v_add_u32_e32 v14, s51, v58
	s_waitcnt lgkmcnt(0)
	v_fma_f32 v46, -v2, v30, v46
	v_fma_f32 v121, -v2, v94, v121
	v_fma_f32 v47, -v3, v30, v47
	v_fma_f32 v120, -v3, v94, v120
	v_fma_f32 v48, -v4, v30, v48
	v_fma_f32 v123, -v4, v94, v123
	v_fma_f32 v49, -v5, v30, v49
	v_fma_f32 v122, -v5, v94, v122
	v_fma_f32 v44, -v6, v30, v44
	v_fma_f32 v74, -v6, v94, v74
	v_fma_f32 v45, -v7, v30, v45
	v_fma_f32 v75, -v7, v94, v75
	v_fma_f32 v50, -v8, v30, v50
	v_fma_f32 v76, -v8, v94, v76
	v_fma_f32 v51, -v9, v30, v51
	v_fma_f32 v77, -v9, v94, v77
	v_fma_f32 v52, -v10, v30, v52
	v_fma_f32 v78, -v10, v94, v78
	v_fma_f32 v53, -v11, v30, v53
	v_fma_f32 v79, -v11, v94, v79
	v_fma_f32 v54, -v12, v30, v54
	v_fma_f32 v105, -v12, v94, v105
	v_fma_f32 v55, -v13, v30, v55
	ds_read_b128 v[2:5], v14 offset:8224
	v_fma_f32 v114, -v13, v94, v114
	ds_read_b128 v[6:9], v14 offset:8240
	ds_read_b128 v[10:13], v14 offset:8256
	ds_read_b128 v[14:17], v14 offset:8272
	s_waitcnt lgkmcnt(0)
	v_fma_f32 v49, -v17, v31, v49
	s_nop 0
	v_fma_f32 v36, -v6, v31, v36
	v_fma_f32 v104, -v6, v95, v104
	v_fma_f32 v32, -v2, v31, v32
	v_fma_f32 v98, -v2, v95, v98
	v_fma_f32 v33, -v3, v31, v33
	s_nop 0
	v_add_u32_e32 v6, s51, v58
	v_mov_b32_e32 v58, 0x400
	v_fma_f32 v97, -v3, v95, v97
	v_fma_f32 v34, -v4, v31, v34
	v_fma_f32 v100, -v4, v95, v100
	v_fma_f32 v35, -v5, v31, v35
	v_fma_f32 v99, -v5, v95, v99
	v_fma_f32 v37, -v7, v31, v37
	v_fma_f32 v103, -v7, v95, v103
	v_fma_f32 v38, -v8, v31, v38
	v_fma_f32 v107, -v8, v95, v107
	v_fma_f32 v39, -v9, v31, v39
	v_fma_f32 v106, -v9, v95, v106
	v_fma_f32 v46, -v14, v31, v46
	v_fma_f32 v121, -v14, v95, v121
	ds_read_b128 v[2:5], v6 offset:8288
	ds_read_b128 v[6:9], v6 offset:8304
	v_fma_f32 v40, -v10, v31, v40
	v_fma_f32 v111, -v10, v95, v111
	v_fma_f32 v41, -v11, v31, v41
	v_fma_f32 v110, -v11, v95, v110
	v_fma_f32 v42, -v12, v31, v42
	s_nop 0
	v_add_u32_e32 v14, s51, v58
	v_fma_f32 v113, -v12, v95, v113
	v_fma_f32 v43, -v13, v31, v43
	v_fma_f32 v112, -v13, v95, v112
	v_fma_f32 v47, -v15, v31, v47
	v_fma_f32 v120, -v15, v95, v120
	v_fma_f32 v48, -v16, v31, v48
	v_fma_f32 v123, -v16, v95, v123
	v_fma_f32 v122, -v17, v95, v122
	s_waitcnt lgkmcnt(0)
	v_fma_f32 v44, -v2, v31, v44
	v_fma_f32 v74, -v2, v95, v74
	v_fma_f32 v45, -v3, v31, v45
	v_fma_f32 v75, -v3, v95, v75
	v_fma_f32 v50, -v4, v31, v50
	v_fma_f32 v76, -v4, v95, v76
	v_fma_f32 v51, -v5, v31, v51
	v_fma_f32 v77, -v5, v95, v77
	v_fma_f32 v52, -v6, v31, v52
	v_fma_f32 v78, -v6, v95, v78
	v_fma_f32 v53, -v7, v31, v53
	v_fma_f32 v79, -v7, v95, v79
	v_fma_f32 v54, -v8, v31, v54
	v_fma_f32 v105, -v8, v95, v105
	v_fma_f32 v55, -v9, v31, v55
	ds_read_b128 v[2:5], v14 offset:8224
	v_fma_f32 v114, -v9, v95, v114
	ds_read_b128 v[6:9], v14 offset:8240
	ds_read_b128 v[10:13], v14 offset:8256
	ds_read_b128 v[14:17], v14 offset:8272
	s_waitcnt lgkmcnt(0)
	v_fma_f32 v49, -v17, v32, v49
	s_nop 0
	v_fma_f32 v36, -v6, v32, v36
	v_fma_f32 v104, -v6, v98, v104
	v_fma_f32 v33, -v3, v32, v33
	v_fma_f32 v97, -v3, v98, v97
	v_fma_f32 v34, -v4, v32, v34
	s_nop 0
	v_add_u32_e32 v6, s51, v58
	v_mov_b32_e32 v58, 0x480
	v_fma_f32 v100, -v4, v98, v100
	v_fma_f32 v35, -v5, v32, v35
	v_fma_f32 v99, -v5, v98, v99
	v_fma_f32 v37, -v7, v32, v37
	v_fma_f32 v103, -v7, v98, v103
	v_fma_f32 v38, -v8, v32, v38
	v_fma_f32 v107, -v8, v98, v107
	v_fma_f32 v39, -v9, v32, v39
	v_fma_f32 v106, -v9, v98, v106
	v_fma_f32 v46, -v14, v32, v46
	v_fma_f32 v121, -v14, v98, v121
	ds_read_b128 v[2:5], v6 offset:8288
	ds_read_b128 v[6:9], v6 offset:8304
	v_fma_f32 v40, -v10, v32, v40
	v_fma_f32 v111, -v10, v98, v111
	v_fma_f32 v41, -v11, v32, v41
	v_fma_f32 v110, -v11, v98, v110
	v_fma_f32 v42, -v12, v32, v42
	s_nop 0
	v_add_u32_e32 v14, s51, v58
	v_fma_f32 v113, -v12, v98, v113
	v_fma_f32 v43, -v13, v32, v43
	v_fma_f32 v112, -v13, v98, v112
	v_fma_f32 v47, -v15, v32, v47
	v_fma_f32 v120, -v15, v98, v120
	v_fma_f32 v48, -v16, v32, v48
	v_fma_f32 v123, -v16, v98, v123
	v_fma_f32 v122, -v17, v98, v122
	s_waitcnt lgkmcnt(0)
	v_fma_f32 v44, -v2, v32, v44
	v_fma_f32 v74, -v2, v98, v74
	v_fma_f32 v45, -v3, v32, v45
	v_fma_f32 v75, -v3, v98, v75
	v_fma_f32 v50, -v4, v32, v50
	v_fma_f32 v76, -v4, v98, v76
	v_fma_f32 v51, -v5, v32, v51
	v_fma_f32 v77, -v5, v98, v77
	v_fma_f32 v52, -v6, v32, v52
	v_fma_f32 v78, -v6, v98, v78
	v_fma_f32 v53, -v7, v32, v53
	v_fma_f32 v79, -v7, v98, v79
	v_fma_f32 v54, -v8, v32, v54
	v_fma_f32 v105, -v8, v98, v105
	v_fma_f32 v55, -v9, v32, v55
	ds_read_b128 v[2:5], v14 offset:8224
	v_fma_f32 v114, -v9, v98, v114
	ds_read_b128 v[6:9], v14 offset:8240
	ds_read_b128 v[10:13], v14 offset:8256
	ds_read_b128 v[14:17], v14 offset:8272
	s_waitcnt lgkmcnt(0)
	v_fma_f32 v49, -v17, v33, v49
	s_nop 0
	v_fma_f32 v36, -v6, v33, v36
	v_fma_f32 v104, -v6, v97, v104
	v_fma_f32 v34, -v4, v33, v34
	v_fma_f32 v100, -v4, v97, v100
	v_fma_f32 v35, -v5, v33, v35
	s_nop 0
	v_add_u32_e32 v6, s51, v58
	v_mov_b32_e32 v58, 0x500
	v_fma_f32 v99, -v5, v97, v99
	v_fma_f32 v37, -v7, v33, v37
	v_fma_f32 v103, -v7, v97, v103
	v_fma_f32 v38, -v8, v33, v38
	v_fma_f32 v107, -v8, v97, v107
	v_fma_f32 v39, -v9, v33, v39
	v_fma_f32 v106, -v9, v97, v106
	v_fma_f32 v46, -v14, v33, v46
	v_fma_f32 v121, -v14, v97, v121
	ds_read_b128 v[2:5], v6 offset:8288
	ds_read_b128 v[6:9], v6 offset:8304
	v_fma_f32 v40, -v10, v33, v40
	v_fma_f32 v111, -v10, v97, v111
	v_fma_f32 v41, -v11, v33, v41
	v_fma_f32 v110, -v11, v97, v110
	v_fma_f32 v42, -v12, v33, v42
	s_nop 0
	v_add_u32_e32 v14, s51, v58
	v_fma_f32 v113, -v12, v97, v113
	v_fma_f32 v43, -v13, v33, v43
	v_fma_f32 v112, -v13, v97, v112
	v_fma_f32 v47, -v15, v33, v47
	v_fma_f32 v120, -v15, v97, v120
	v_fma_f32 v48, -v16, v33, v48
	v_fma_f32 v123, -v16, v97, v123
	v_fma_f32 v122, -v17, v97, v122
	s_waitcnt lgkmcnt(0)
	v_fma_f32 v44, -v2, v33, v44
	v_fma_f32 v74, -v2, v97, v74
	v_fma_f32 v45, -v3, v33, v45
	v_fma_f32 v75, -v3, v97, v75
	v_fma_f32 v50, -v4, v33, v50
	v_fma_f32 v76, -v4, v97, v76
	v_fma_f32 v51, -v5, v33, v51
	v_fma_f32 v77, -v5, v97, v77
	v_fma_f32 v52, -v6, v33, v52
	v_fma_f32 v78, -v6, v97, v78
	v_fma_f32 v53, -v7, v33, v53
	v_fma_f32 v79, -v7, v97, v79
	v_fma_f32 v54, -v8, v33, v54
	v_fma_f32 v105, -v8, v97, v105
	v_fma_f32 v55, -v9, v33, v55
	ds_read_b128 v[2:5], v14 offset:8224
	v_fma_f32 v114, -v9, v97, v114
	ds_read_b128 v[6:9], v14 offset:8240
	ds_read_b128 v[10:13], v14 offset:8256
	ds_read_b128 v[14:17], v14 offset:8272
	s_waitcnt lgkmcnt(0)
	v_fma_f32 v49, -v17, v34, v49
	s_nop 0
	v_fma_f32 v36, -v6, v34, v36
	v_fma_f32 v104, -v6, v100, v104
	v_fma_f32 v35, -v5, v34, v35
	v_fma_f32 v99, -v5, v100, v99
	v_fma_f32 v37, -v7, v34, v37
	s_nop 0
	v_add_u32_e32 v6, s51, v58
	v_mov_b32_e32 v58, 0x580
	v_fma_f32 v103, -v7, v100, v103
	v_fma_f32 v38, -v8, v34, v38
	v_fma_f32 v107, -v8, v100, v107
	v_fma_f32 v39, -v9, v34, v39
	v_fma_f32 v106, -v9, v100, v106
	v_fma_f32 v46, -v14, v34, v46
	v_fma_f32 v121, -v14, v100, v121
	ds_read_b128 v[2:5], v6 offset:8288
	ds_read_b128 v[6:9], v6 offset:8304
	v_fma_f32 v40, -v10, v34, v40
	v_fma_f32 v111, -v10, v100, v111
	v_fma_f32 v41, -v11, v34, v41
	v_fma_f32 v110, -v11, v100, v110
	v_fma_f32 v42, -v12, v34, v42
	s_nop 0
	v_add_u32_e32 v14, s51, v58
	v_fma_f32 v113, -v12, v100, v113
	v_fma_f32 v43, -v13, v34, v43
	v_fma_f32 v112, -v13, v100, v112
	v_fma_f32 v47, -v15, v34, v47
	v_fma_f32 v120, -v15, v100, v120
	v_fma_f32 v48, -v16, v34, v48
	v_fma_f32 v123, -v16, v100, v123
	v_fma_f32 v122, -v17, v100, v122
	s_waitcnt lgkmcnt(0)
	v_fma_f32 v44, -v2, v34, v44
	v_fma_f32 v74, -v2, v100, v74
	v_fma_f32 v45, -v3, v34, v45
	v_fma_f32 v75, -v3, v100, v75
	v_fma_f32 v50, -v4, v34, v50
	v_fma_f32 v76, -v4, v100, v76
	v_fma_f32 v51, -v5, v34, v51
	v_fma_f32 v77, -v5, v100, v77
	v_fma_f32 v52, -v6, v34, v52
	v_fma_f32 v78, -v6, v100, v78
	v_fma_f32 v53, -v7, v34, v53
	v_fma_f32 v79, -v7, v100, v79
	v_fma_f32 v54, -v8, v34, v54
	v_fma_f32 v105, -v8, v100, v105
	v_fma_f32 v55, -v9, v34, v55
	ds_read_b128 v[2:5], v14 offset:8240
	v_fma_f32 v114, -v9, v100, v114
	ds_read_b128 v[6:9], v14 offset:8256
	ds_read_b128 v[10:13], v14 offset:8272
	ds_read_b128 v[14:17], v14 offset:8288
	s_waitcnt lgkmcnt(0)
	v_fma_f32 v51, -v17, v35, v51
	s_nop 0
	v_fma_f32 v36, -v2, v35, v36
	v_fma_f32 v104, -v2, v99, v104
	v_fma_f32 v37, -v3, v35, v37
	v_fma_f32 v103, -v3, v99, v103
	v_fma_f32 v38, -v4, v35, v38
	s_nop 0
	v_add_u32_e32 v2, s51, v58
	v_mov_b32_e32 v58, 0x600
	v_fma_f32 v107, -v4, v99, v107
	v_fma_f32 v39, -v5, v35, v39
	v_fma_f32 v106, -v5, v99, v106
	v_fma_f32 v44, -v14, v35, v44
	v_fma_f32 v74, -v14, v99, v74
	ds_read_b128 v[2:5], v2 offset:8304
	v_fma_f32 v40, -v6, v35, v40
	v_fma_f32 v111, -v6, v99, v111
	v_fma_f32 v41, -v7, v35, v41
	v_fma_f32 v110, -v7, v99, v110
	v_fma_f32 v42, -v8, v35, v42
	s_nop 0
	v_add_u32_e32 v14, s51, v58
	v_fma_f32 v113, -v8, v99, v113
	v_fma_f32 v43, -v9, v35, v43
	v_fma_f32 v112, -v9, v99, v112
	v_fma_f32 v46, -v10, v35, v46
	v_fma_f32 v121, -v10, v99, v121
	v_fma_f32 v47, -v11, v35, v47
	v_fma_f32 v120, -v11, v99, v120
	v_fma_f32 v48, -v12, v35, v48
	v_fma_f32 v123, -v12, v99, v123
	v_fma_f32 v49, -v13, v35, v49
	v_fma_f32 v122, -v13, v99, v122
	v_fma_f32 v45, -v15, v35, v45
	v_fma_f32 v75, -v15, v99, v75
	v_fma_f32 v50, -v16, v35, v50
	v_fma_f32 v76, -v16, v99, v76
	v_fma_f32 v77, -v17, v99, v77
	s_waitcnt lgkmcnt(0)
	v_fma_f32 v52, -v2, v35, v52
	v_fma_f32 v78, -v2, v99, v78
	v_fma_f32 v53, -v3, v35, v53
	v_fma_f32 v79, -v3, v99, v79
	v_fma_f32 v54, -v4, v35, v54
	v_fma_f32 v105, -v4, v99, v105
	v_fma_f32 v55, -v5, v35, v55
	ds_read_b128 v[6:9], v14 offset:8240
	v_fma_f32 v114, -v5, v99, v114
	ds_read_b128 v[2:5], v14 offset:8256
	ds_read_b128 v[10:13], v14 offset:8272
	ds_read_b128 v[14:17], v14 offset:8288
	s_waitcnt lgkmcnt(0)
	v_fma_f32 v51, -v17, v36, v51
	s_nop 0
	v_fma_f32 v40, -v2, v36, v40
	v_fma_f32 v111, -v2, v104, v111
	v_fma_f32 v37, -v7, v36, v37
	v_fma_f32 v103, -v7, v104, v103
	v_fma_f32 v41, -v3, v36, v41
	s_nop 0
	v_add_u32_e32 v2, s51, v58
	v_mov_b32_e32 v58, 0x680
	v_fma_f32 v110, -v3, v104, v110
	v_fma_f32 v42, -v4, v36, v42
	v_fma_f32 v113, -v4, v104, v113
	v_fma_f32 v43, -v5, v36, v43
	v_fma_f32 v112, -v5, v104, v112
	v_fma_f32 v44, -v14, v36, v44
	v_fma_f32 v74, -v14, v104, v74
	ds_read_b128 v[2:5], v2 offset:8304
	v_fma_f32 v38, -v8, v36, v38
	v_fma_f32 v107, -v8, v104, v107
	v_fma_f32 v39, -v9, v36, v39
	v_fma_f32 v106, -v9, v104, v106
	v_fma_f32 v46, -v10, v36, v46
	s_nop 0
	v_add_u32_e32 v14, s51, v58
	v_fma_f32 v121, -v10, v104, v121
	v_fma_f32 v47, -v11, v36, v47
	v_fma_f32 v120, -v11, v104, v120
	v_fma_f32 v48, -v12, v36, v48
	v_fma_f32 v123, -v12, v104, v123
	v_fma_f32 v49, -v13, v36, v49
	v_fma_f32 v122, -v13, v104, v122
	v_fma_f32 v45, -v15, v36, v45
	v_fma_f32 v75, -v15, v104, v75
	v_fma_f32 v50, -v16, v36, v50
	v_fma_f32 v76, -v16, v104, v76
	v_fma_f32 v77, -v17, v104, v77
	s_waitcnt lgkmcnt(0)
	v_fma_f32 v52, -v2, v36, v52
	v_fma_f32 v78, -v2, v104, v78
	v_fma_f32 v53, -v3, v36, v53
	v_fma_f32 v79, -v3, v104, v79
	v_fma_f32 v54, -v4, v36, v54
	v_fma_f32 v105, -v4, v104, v105
	v_fma_f32 v55, -v5, v36, v55
	ds_read_b128 v[6:9], v14 offset:8240
	v_fma_f32 v114, -v5, v104, v114
	ds_read_b128 v[2:5], v14 offset:8256
	ds_read_b128 v[10:13], v14 offset:8272
	ds_read_b128 v[14:17], v14 offset:8288
	s_waitcnt lgkmcnt(0)
	v_fma_f32 v51, -v17, v37, v51
	s_nop 0
	v_fma_f32 v40, -v2, v37, v40
	v_fma_f32 v111, -v2, v103, v111
	v_fma_f32 v38, -v8, v37, v38
	v_fma_f32 v107, -v8, v103, v107
	v_fma_f32 v41, -v3, v37, v41
	s_nop 0
	v_add_u32_e32 v2, s51, v58
	v_mov_b32_e32 v58, 0x700
	v_fma_f32 v110, -v3, v103, v110
	v_fma_f32 v42, -v4, v37, v42
	v_fma_f32 v113, -v4, v103, v113
	v_fma_f32 v43, -v5, v37, v43
	v_fma_f32 v112, -v5, v103, v112
	v_fma_f32 v44, -v14, v37, v44
	v_fma_f32 v74, -v14, v103, v74
	ds_read_b128 v[2:5], v2 offset:8304
	v_fma_f32 v39, -v9, v37, v39
	v_fma_f32 v106, -v9, v103, v106
	v_fma_f32 v46, -v10, v37, v46
	v_fma_f32 v121, -v10, v103, v121
	v_fma_f32 v47, -v11, v37, v47
	s_nop 0
	v_add_u32_e32 v14, s51, v58
	v_fma_f32 v120, -v11, v103, v120
	v_fma_f32 v48, -v12, v37, v48
	v_fma_f32 v123, -v12, v103, v123
	v_fma_f32 v49, -v13, v37, v49
	v_fma_f32 v122, -v13, v103, v122
	v_fma_f32 v45, -v15, v37, v45
	v_fma_f32 v75, -v15, v103, v75
	v_fma_f32 v50, -v16, v37, v50
	v_fma_f32 v76, -v16, v103, v76
	v_fma_f32 v77, -v17, v103, v77
	s_waitcnt lgkmcnt(0)
	v_fma_f32 v52, -v2, v37, v52
	v_fma_f32 v78, -v2, v103, v78
	v_fma_f32 v53, -v3, v37, v53
	v_fma_f32 v79, -v3, v103, v79
	v_fma_f32 v54, -v4, v37, v54
	v_fma_f32 v105, -v4, v103, v105
	v_fma_f32 v55, -v5, v37, v55
	ds_read_b128 v[6:9], v14 offset:8240
	v_fma_f32 v114, -v5, v103, v114
	ds_read_b128 v[2:5], v14 offset:8256
	ds_read_b128 v[10:13], v14 offset:8272
	ds_read_b128 v[14:17], v14 offset:8288
	s_waitcnt lgkmcnt(0)
	v_fma_f32 v40, -v2, v38, v40
	v_fma_f32 v111, -v2, v107, v111
	v_fma_f32 v51, -v17, v38, v51
	v_fma_f32 v41, -v3, v38, v41
	v_fma_f32 v110, -v3, v107, v110
	v_fma_f32 v42, -v4, v38, v42
	v_fma_f32 v113, -v4, v107, v113
	v_fma_f32 v43, -v5, v38, v43
	s_nop 0
	v_fma_f32 v112, -v5, v107, v112
	v_fma_f32 v39, -v9, v38, v39
	v_fma_f32 v106, -v9, v107, v106
	v_fma_f32 v44, -v14, v38, v44
	v_fma_f32 v74, -v14, v107, v74
	s_nop 0
	v_add_u32_e32 v2, s51, v58
	ds_read_b128 v[2:5], v2 offset:8304
	s_waitcnt lgkmcnt(0)
	v_fma_f32 v52, -v2, v38, v52
	v_fma_f32 v78, -v2, v107, v78
	v_mov_b32_e32 v2, 0x780
	v_fma_f32 v46, -v10, v38, v46
	v_fma_f32 v121, -v10, v107, v121
	v_fma_f32 v47, -v11, v38, v47
	v_fma_f32 v120, -v11, v107, v120
	v_fma_f32 v48, -v12, v38, v48
	s_nop 0
	v_add_u32_e32 v14, s51, v2
	v_fma_f32 v123, -v12, v107, v123
	v_fma_f32 v49, -v13, v38, v49
	v_fma_f32 v122, -v13, v107, v122
	v_fma_f32 v45, -v15, v38, v45
	v_fma_f32 v75, -v15, v107, v75
	v_fma_f32 v50, -v16, v38, v50
	v_fma_f32 v76, -v16, v107, v76
	v_fma_f32 v77, -v17, v107, v77
	v_fma_f32 v53, -v3, v38, v53
	v_fma_f32 v79, -v3, v107, v79
	v_fma_f32 v54, -v4, v38, v54
	v_fma_f32 v105, -v4, v107, v105
	v_fma_f32 v55, -v5, v38, v55
	ds_read_b128 v[6:9], v14 offset:8256
	v_fma_f32 v114, -v5, v107, v114
	ds_read_b128 v[2:5], v14 offset:8272
	ds_read_b128 v[10:13], v14 offset:8288
	ds_read_b128 v[14:17], v14 offset:8304
	s_waitcnt lgkmcnt(0)
	v_fma_f32 v46, -v2, v39, v46
	v_fma_f32 v121, -v2, v106, v121
	v_mov_b32_e32 v2, 0x800
	v_fma_f32 v40, -v6, v39, v40
	v_fma_f32 v111, -v6, v106, v111
	v_fma_f32 v52, -v14, v39, v52
	v_fma_f32 v78, -v14, v106, v78
	v_fma_f32 v41, -v7, v39, v41
	v_fma_f32 v110, -v7, v106, v110
	v_fma_f32 v42, -v8, v39, v42
	s_nop 0
	v_fma_f32 v113, -v8, v106, v113
	v_fma_f32 v43, -v9, v39, v43
	v_fma_f32 v112, -v9, v106, v112
	v_fma_f32 v47, -v3, v39, v47
	v_fma_f32 v120, -v3, v106, v120
	s_nop 0
	v_add_u32_e32 v14, s51, v2
	v_fma_f32 v48, -v4, v39, v48
	v_fma_f32 v123, -v4, v106, v123
	v_fma_f32 v49, -v5, v39, v49
	v_fma_f32 v122, -v5, v106, v122
	v_fma_f32 v44, -v10, v39, v44
	v_fma_f32 v74, -v10, v106, v74
	v_fma_f32 v45, -v11, v39, v45
	v_fma_f32 v75, -v11, v106, v75
	v_fma_f32 v50, -v12, v39, v50
	v_fma_f32 v76, -v12, v106, v76
	v_fma_f32 v51, -v13, v39, v51
	v_fma_f32 v77, -v13, v106, v77
	v_fma_f32 v53, -v15, v39, v53
	v_fma_f32 v79, -v15, v106, v79
	v_fma_f32 v54, -v16, v39, v54
	v_fma_f32 v105, -v16, v106, v105
	v_fma_f32 v55, -v17, v39, v55
	ds_read_b128 v[2:5], v14 offset:8256
	v_fma_f32 v114, -v17, v106, v114
	ds_read_b128 v[6:9], v14 offset:8272
	ds_read_b128 v[10:13], v14 offset:8288
	ds_read_b128 v[14:17], v14 offset:8304
	s_waitcnt lgkmcnt(0)
	v_mov_b32_e32 v2, 0x880
	v_fma_f32 v41, -v3, v40, v41
	v_fma_f32 v110, -v3, v111, v110
	v_fma_f32 v52, -v14, v40, v52
	v_fma_f32 v78, -v14, v111, v78
	s_nop 0
	v_fma_f32 v42, -v4, v40, v42
	v_fma_f32 v113, -v4, v111, v113
	v_fma_f32 v43, -v5, v40, v43
	v_fma_f32 v112, -v5, v111, v112
	v_fma_f32 v46, -v6, v40, v46
	s_nop 0
	v_add_u32_e32 v14, s51, v2
	v_fma_f32 v121, -v6, v111, v121
	v_fma_f32 v47, -v7, v40, v47
	v_fma_f32 v120, -v7, v111, v120
	v_fma_f32 v48, -v8, v40, v48
	v_fma_f32 v123, -v8, v111, v123
	v_fma_f32 v49, -v9, v40, v49
	v_fma_f32 v122, -v9, v111, v122
	v_fma_f32 v44, -v10, v40, v44
	v_fma_f32 v74, -v10, v111, v74
	v_fma_f32 v45, -v11, v40, v45
	v_fma_f32 v75, -v11, v111, v75
	v_fma_f32 v50, -v12, v40, v50
	v_fma_f32 v76, -v12, v111, v76
	v_fma_f32 v51, -v13, v40, v51
	v_fma_f32 v77, -v13, v111, v77
	v_fma_f32 v53, -v15, v40, v53
	v_fma_f32 v79, -v15, v111, v79
	v_fma_f32 v54, -v16, v40, v54
	v_fma_f32 v105, -v16, v111, v105
	v_fma_f32 v55, -v17, v40, v55
	ds_read_b128 v[2:5], v14 offset:8256
	v_fma_f32 v114, -v17, v111, v114
	ds_read_b128 v[6:9], v14 offset:8272
	ds_read_b128 v[10:13], v14 offset:8288
	ds_read_b128 v[14:17], v14 offset:8304
	s_waitcnt lgkmcnt(0)
	v_mov_b32_e32 v2, 0x900
	v_fma_f32 v42, -v4, v41, v42
	v_fma_f32 v113, -v4, v110, v113
	v_fma_f32 v52, -v14, v41, v52
	v_fma_f32 v78, -v14, v110, v78
	s_nop 0
	v_fma_f32 v43, -v5, v41, v43
	v_fma_f32 v112, -v5, v110, v112
	v_fma_f32 v46, -v6, v41, v46
	v_fma_f32 v121, -v6, v110, v121
	v_fma_f32 v47, -v7, v41, v47
	s_nop 0
	v_add_u32_e32 v14, s51, v2
	v_fma_f32 v120, -v7, v110, v120
	v_fma_f32 v48, -v8, v41, v48
	v_fma_f32 v123, -v8, v110, v123
	v_fma_f32 v49, -v9, v41, v49
	v_fma_f32 v122, -v9, v110, v122
	v_fma_f32 v44, -v10, v41, v44
	v_fma_f32 v74, -v10, v110, v74
	v_fma_f32 v45, -v11, v41, v45
	v_fma_f32 v75, -v11, v110, v75
	v_fma_f32 v50, -v12, v41, v50
	v_fma_f32 v76, -v12, v110, v76
	v_fma_f32 v51, -v13, v41, v51
	v_fma_f32 v77, -v13, v110, v77
	v_fma_f32 v53, -v15, v41, v53
	v_fma_f32 v79, -v15, v110, v79
	v_fma_f32 v54, -v16, v41, v54
	v_fma_f32 v105, -v16, v110, v105
	v_fma_f32 v55, -v17, v41, v55
	ds_read_b128 v[2:5], v14 offset:8256
	v_fma_f32 v114, -v17, v110, v114
	ds_read_b128 v[6:9], v14 offset:8272
	ds_read_b128 v[10:13], v14 offset:8288
	ds_read_b128 v[14:17], v14 offset:8304
	s_waitcnt lgkmcnt(0)
	v_mov_b32_e32 v2, 0x980
	v_fma_f32 v43, -v5, v42, v43
	v_fma_f32 v112, -v5, v113, v112
	v_fma_f32 v44, -v10, v42, v44
	v_fma_f32 v74, -v10, v113, v74
	v_fma_f32 v46, -v6, v42, v46
	v_fma_f32 v121, -v6, v113, v121
	v_fma_f32 v47, -v7, v42, v47
	s_nop 0
	v_fma_f32 v120, -v7, v113, v120
	v_fma_f32 v48, -v8, v42, v48
	v_fma_f32 v123, -v8, v113, v123
	v_fma_f32 v49, -v9, v42, v49
	v_fma_f32 v122, -v9, v113, v122
	s_nop 0
	v_add_u32_e32 v10, s51, v2
	v_fma_f32 v45, -v11, v42, v45
	v_fma_f32 v75, -v11, v113, v75
	v_fma_f32 v50, -v12, v42, v50
	v_fma_f32 v76, -v12, v113, v76
	v_fma_f32 v51, -v13, v42, v51
	v_fma_f32 v77, -v13, v113, v77
	ds_read_b128 v[2:5], v10 offset:8272
	ds_read_b128 v[6:9], v10 offset:8288
	ds_read_b128 v[10:13], v10 offset:8304
	v_fma_f32 v52, -v14, v42, v52
	v_fma_f32 v78, -v14, v113, v78
	s_waitcnt lgkmcnt(0)
	v_fma_f32 v46, -v2, v43, v46
	v_fma_f32 v121, -v2, v112, v121
	v_mov_b32_e32 v2, 0xa00
	v_fma_f32 v53, -v15, v42, v53
	v_fma_f32 v79, -v15, v113, v79
	v_fma_f32 v54, -v16, v42, v54
	v_fma_f32 v105, -v16, v113, v105
	v_fma_f32 v55, -v17, v42, v55
	v_fma_f32 v114, -v17, v113, v114
	v_fma_f32 v52, -v10, v43, v52
	v_fma_f32 v78, -v10, v112, v78
	v_fma_f32 v47, -v3, v43, v47
	v_fma_f32 v120, -v3, v112, v120
	v_fma_f32 v48, -v4, v43, v48
	v_fma_f32 v123, -v4, v112, v123
	v_fma_f32 v49, -v5, v43, v49
	s_nop 0
	v_add_u32_e32 v10, s51, v2
	v_fma_f32 v122, -v5, v112, v122
	v_fma_f32 v44, -v6, v43, v44
	v_fma_f32 v74, -v6, v112, v74
	v_fma_f32 v45, -v7, v43, v45
	v_fma_f32 v75, -v7, v112, v75
	v_fma_f32 v50, -v8, v43, v50
	v_fma_f32 v76, -v8, v112, v76
	v_fma_f32 v51, -v9, v43, v51
	v_fma_f32 v77, -v9, v112, v77
	v_fma_f32 v53, -v11, v43, v53
	v_fma_f32 v79, -v11, v112, v79
	v_fma_f32 v54, -v12, v43, v54
	v_fma_f32 v105, -v12, v112, v105
	ds_read_b128 v[2:5], v10 offset:8272
	v_fma_f32 v55, -v13, v43, v55
	v_fma_f32 v114, -v13, v112, v114
	ds_read_b128 v[6:9], v10 offset:8288
	ds_read_b128 v[10:13], v10 offset:8304
	s_waitcnt lgkmcnt(0)
	v_mov_b32_e32 v2, 0xa80
	v_fma_f32 v47, -v3, v46, v47
	v_fma_f32 v120, -v3, v121, v120
	v_fma_f32 v52, -v10, v46, v52
	v_fma_f32 v78, -v10, v121, v78
	s_nop 0
	v_fma_f32 v48, -v4, v46, v48
	v_fma_f32 v123, -v4, v121, v123
	v_fma_f32 v49, -v5, v46, v49
	v_fma_f32 v122, -v5, v121, v122
	v_fma_f32 v44, -v6, v46, v44
	s_nop 0
	v_add_u32_e32 v10, s51, v2
	v_fma_f32 v74, -v6, v121, v74
	v_fma_f32 v45, -v7, v46, v45
	v_fma_f32 v75, -v7, v121, v75
	v_fma_f32 v50, -v8, v46, v50
	v_fma_f32 v76, -v8, v121, v76
	v_fma_f32 v51, -v9, v46, v51
	v_fma_f32 v77, -v9, v121, v77
	v_fma_f32 v53, -v11, v46, v53
	v_fma_f32 v79, -v11, v121, v79
	v_fma_f32 v54, -v12, v46, v54
	v_fma_f32 v105, -v12, v121, v105
	ds_read_b128 v[2:5], v10 offset:8272
	v_fma_f32 v55, -v13, v46, v55
	v_fma_f32 v114, -v13, v121, v114
	ds_read_b128 v[6:9], v10 offset:8288
	ds_read_b128 v[10:13], v10 offset:8304
	s_waitcnt lgkmcnt(0)
	v_mov_b32_e32 v2, 0xb00
	v_fma_f32 v48, -v4, v47, v48
	v_fma_f32 v123, -v4, v120, v123
	v_fma_f32 v52, -v10, v47, v52
	v_fma_f32 v78, -v10, v120, v78
	s_nop 0
	v_fma_f32 v49, -v5, v47, v49
	v_fma_f32 v122, -v5, v120, v122
	v_fma_f32 v44, -v6, v47, v44
	v_fma_f32 v74, -v6, v120, v74
	v_fma_f32 v45, -v7, v47, v45
	s_nop 0
	v_add_u32_e32 v10, s51, v2
	ds_read_b128 v[2:5], v10 offset:8272
	v_fma_f32 v75, -v7, v120, v75
	v_fma_f32 v50, -v8, v47, v50
	v_fma_f32 v76, -v8, v120, v76
	v_fma_f32 v51, -v9, v47, v51
	v_fma_f32 v77, -v9, v120, v77
	ds_read_b128 v[6:9], v10 offset:8288
	s_waitcnt lgkmcnt(0)
	v_mov_b32_e32 v2, 0xb80
	v_fma_f32 v53, -v11, v47, v53
	v_fma_f32 v79, -v11, v120, v79
	v_fma_f32 v54, -v12, v47, v54
	v_fma_f32 v105, -v12, v120, v105
	v_fma_f32 v55, -v13, v47, v55
	v_fma_f32 v114, -v13, v120, v114
	ds_read_b128 v[10:13], v10 offset:8304
	v_fma_f32 v49, -v5, v48, v49
	v_fma_f32 v122, -v5, v123, v122
	v_fma_f32 v44, -v6, v48, v44
	v_fma_f32 v74, -v6, v123, v74
	v_fma_f32 v45, -v7, v48, v45
	v_fma_f32 v75, -v7, v123, v75
	v_fma_f32 v50, -v8, v48, v50
	s_nop 0
	v_fma_f32 v76, -v8, v123, v76
	v_fma_f32 v51, -v9, v48, v51
	v_fma_f32 v77, -v9, v123, v77
	s_waitcnt lgkmcnt(0)
	v_fma_f32 v52, -v10, v48, v52
	v_fma_f32 v78, -v10, v123, v78
	v_add_u32_e32 v6, s51, v2
	ds_read_b128 v[2:5], v6 offset:8288
	ds_read_b128 v[6:9], v6 offset:8304
	s_waitcnt lgkmcnt(0)
	v_fma_f32 v44, -v2, v49, v44
	v_fma_f32 v74, -v2, v122, v74
	v_mov_b32_e32 v2, 0xc00
	v_fma_f32 v52, -v6, v49, v52
	v_fma_f32 v78, -v6, v122, v78
	v_fma_f32 v53, -v11, v48, v53
	v_fma_f32 v79, -v11, v123, v79
	v_fma_f32 v54, -v12, v48, v54
	v_fma_f32 v105, -v12, v123, v105
	v_fma_f32 v55, -v13, v48, v55
	s_nop 0
	v_add_u32_e32 v6, s51, v2
	v_fma_f32 v114, -v13, v123, v114
	v_fma_f32 v45, -v3, v49, v45
	v_fma_f32 v75, -v3, v122, v75
	v_fma_f32 v50, -v4, v49, v50
	v_fma_f32 v76, -v4, v122, v76
	v_fma_f32 v51, -v5, v49, v51
	v_fma_f32 v77, -v5, v122, v77
	ds_read_b128 v[2:5], v6 offset:8288
	v_fma_f32 v53, -v7, v49, v53
	v_fma_f32 v79, -v7, v122, v79
	v_fma_f32 v54, -v8, v49, v54
	v_fma_f32 v105, -v8, v122, v105
	v_fma_f32 v55, -v9, v49, v55
	v_fma_f32 v114, -v9, v122, v114
	ds_read_b128 v[6:9], v6 offset:8304
	s_waitcnt lgkmcnt(0)
	v_mov_b32_e32 v2, 0xc80
	v_fma_f32 v45, -v3, v44, v45
	v_fma_f32 v75, -v3, v74, v75
	v_fma_f32 v52, -v6, v44, v52
	v_fma_f32 v78, -v6, v74, v78
	v_fma_f32 v50, -v4, v44, v50
	v_fma_f32 v76, -v4, v74, v76
	v_fma_f32 v51, -v5, v44, v51
	s_nop 0
	v_fma_f32 v77, -v5, v74, v77
	v_fma_f32 v53, -v7, v44, v53
	v_fma_f32 v79, -v7, v74, v79
	v_fma_f32 v54, -v8, v44, v54
	v_fma_f32 v105, -v8, v74, v105
	s_nop 0
	v_add_u32_e32 v6, s51, v2
	ds_read_b128 v[2:5], v6 offset:8288
	v_fma_f32 v55, -v9, v44, v55
	v_fma_f32 v114, -v9, v74, v114
	ds_read_b128 v[6:9], v6 offset:8304
	s_waitcnt lgkmcnt(0)
	v_mov_b32_e32 v2, 0xd00
	v_fma_f32 v50, -v4, v45, v50
	v_fma_f32 v76, -v4, v75, v76
	v_fma_f32 v52, -v6, v45, v52
	v_fma_f32 v78, -v6, v75, v78
	v_fma_f32 v51, -v5, v45, v51
	v_fma_f32 v77, -v5, v75, v77
	v_fma_f32 v53, -v7, v45, v53
	s_nop 0
	v_fma_f32 v79, -v7, v75, v79
	v_fma_f32 v54, -v8, v45, v54
	v_fma_f32 v105, -v8, v75, v105
	v_fma_f32 v55, -v9, v45, v55
	v_fma_f32 v114, -v9, v75, v114
	s_nop 0
	v_add_u32_e32 v6, s51, v2
	ds_read_b128 v[2:5], v6 offset:8288
	ds_read_b128 v[10:13], v6 offset:8304
	s_waitcnt lgkmcnt(0)
	v_mov_b32_e32 v2, 0xd80
	v_fma_f32 v51, -v5, v50, v51
	v_fma_f32 v77, -v5, v76, v77
	v_fma_f32 v52, -v10, v50, v52
	v_fma_f32 v78, -v10, v76, v78
	v_fma_f32 v53, -v11, v50, v53
	v_fma_f32 v79, -v11, v76, v79
	v_fma_f32 v54, -v12, v50, v54
	s_nop 0
	v_fma_f32 v105, -v12, v76, v105
	v_fma_f32 v55, -v13, v50, v55
	v_fma_f32 v114, -v13, v76, v114
	s_nop 0
	v_add_u32_e32 v2, s51, v2
	ds_read_b128 v[2:5], v2 offset:8304
	s_waitcnt lgkmcnt(0)
	v_fma_f32 v52, -v2, v51, v52
	v_fma_f32 v78, -v2, v77, v78
	v_mov_b32_e32 v2, 0xe00
	v_fma_f32 v53, -v3, v51, v53
	v_fma_f32 v79, -v3, v77, v79
	v_fma_f32 v54, -v4, v51, v54
	v_fma_f32 v105, -v4, v77, v105
	v_fma_f32 v55, -v5, v51, v55
	s_nop 0
	v_add_u32_e32 v2, s51, v2
	ds_read_b128 v[6:9], v2 offset:8304
	v_mov_b32_e32 v2, 0xe80
	s_waitcnt lgkmcnt(0)
	v_fma_f32 v53, -v7, v52, v53
	v_fma_f32 v79, -v7, v78, v79
	v_fma_f32 v54, -v8, v52, v54
	v_fma_f32 v105, -v8, v78, v105
	v_fma_f32 v114, -v5, v77, v114
	v_fma_f32 v55, -v9, v52, v55
	v_add_u32_e32 v8, s51, v56
	v_fma_f32 v114, -v9, v78, v114
	s_nop 0
	v_add_u32_e32 v2, s51, v2
	ds_read_b128 v[10:13], v2 offset:8304
	v_mov_b32_e32 v2, 0xf00
	s_waitcnt lgkmcnt(0)
	v_fma_f32 v54, -v12, v53, v54
	v_fma_f32 v105, -v12, v79, v105
	v_fma_f32 v55, -v13, v53, v55
	v_fma_f32 v114, -v13, v79, v114
	s_nop 0
	s_nop 0
	v_add_u32_e32 v2, s51, v2
	ds_read_b128 v[2:5], v2 offset:8304
	s_waitcnt lgkmcnt(0)
	v_lshlrev_b64 v[2:3], 2, v[22:23]
	v_fma_f32 v55, -v5, v54, v55
	v_fma_f32 v114, -v5, v105, v114
	v_lshl_add_u64 v[4:5], s[2:3], 0, v[2:3]
	flat_store_dword v[4:5], v24
	v_lshlrev_b64 v[4:5], 2, v[22:23]
	v_lshl_add_u64 v[6:7], s[2:3], 0, v[4:5]
	s_add_u32 s2, s0, 0x4800
	s_addc_u32 s3, s1, 0
	v_lshl_add_u64 v[2:3], s[2:3], 0, v[2:3]
	flat_store_dword v[6:7], v25 offset:256
	flat_store_dword v[6:7], v26 offset:512
	flat_store_dword v[6:7], v27 offset:768
	flat_store_dword v[6:7], v28 offset:1024
	flat_store_dword v[6:7], v29 offset:1280
	flat_store_dword v[6:7], v30 offset:1536
	flat_store_dword v[6:7], v31 offset:1792
	flat_store_dword v[6:7], v32 offset:2048
	flat_store_dword v[6:7], v33 offset:2304
	flat_store_dword v[6:7], v34 offset:2560
	flat_store_dword v[6:7], v35 offset:2816
	flat_store_dword v[6:7], v36 offset:3072
	flat_store_dword v[6:7], v37 offset:3328
	flat_store_dword v[6:7], v38 offset:3584
	flat_store_dword v[6:7], v39 offset:3840
	flat_store_dword v[2:3], v40
	v_lshl_add_u64 v[2:3], s[2:3], 0, v[4:5]
	flat_store_dword v[2:3], v41 offset:256
	flat_store_dword v[2:3], v42 offset:512
	flat_store_dword v[2:3], v43 offset:768
	flat_store_dword v[2:3], v46 offset:1024
	flat_store_dword v[2:3], v47 offset:1280
	flat_store_dword v[2:3], v48 offset:1536
	flat_store_dword v[2:3], v49 offset:1792
	flat_store_dword v[2:3], v44 offset:2048
	flat_store_dword v[2:3], v45 offset:2304
	flat_store_dword v[2:3], v50 offset:2560
	flat_store_dword v[2:3], v51 offset:2816
	flat_store_dword v[2:3], v52 offset:3072
	flat_store_dword v[2:3], v53 offset:3328
	flat_store_dword v[2:3], v54 offset:3584
	flat_store_dword v[2:3], v55 offset:3840
	v_bfe_u32 v2, v22, 2, 1
	s_mov_b32 s2, 0x7ffffe
	v_and_or_b32 v2, v21, s2, v2
	v_and_b32_e32 v3, 6, v87
	v_and_b32_e32 v4, 8, v22
	v_lshl_add_u32 v2, v2, 9, s51
	v_add3_u32 v2, v2, v4, v3
	v_cvt_pk_bf16_f32 v3, -v88, s0
	s_waitcnt lgkmcnt(0)
	ds_write_b16 v2, v3
	v_cvt_pk_bf16_f32 v3, -v90, s0
	ds_write_b16 v2, v3 offset:16
	v_cvt_pk_bf16_f32 v3, -v89, s0
	ds_write_b16 v2, v3 offset:32
	v_cvt_pk_bf16_f32 v3, -v91, s0
	ds_write_b16 v2, v3 offset:48
	v_cvt_pk_bf16_f32 v3, -v92, s0
	ds_write_b16 v2, v3 offset:64
	v_cvt_pk_bf16_f32 v3, -v93, s0
	ds_write_b16 v2, v3 offset:80
	v_cvt_pk_bf16_f32 v3, -v94, s0
	ds_write_b16 v2, v3 offset:96
	v_cvt_pk_bf16_f32 v3, -v95, s0
	ds_write_b16 v2, v3 offset:112
	v_cvt_pk_bf16_f32 v3, -v98, s0
	ds_write_b16 v2, v3 offset:128
	v_cvt_pk_bf16_f32 v3, -v97, s0
	ds_write_b16 v2, v3 offset:144
	v_cvt_pk_bf16_f32 v3, -v100, s0
	ds_write_b16 v2, v3 offset:160
	v_cvt_pk_bf16_f32 v3, -v99, s0
	ds_write_b16 v2, v3 offset:176
	v_cvt_pk_bf16_f32 v3, -v104, s0
	ds_write_b16 v2, v3 offset:192
	v_cvt_pk_bf16_f32 v3, -v103, s0
	ds_write_b16 v2, v3 offset:208
	v_cvt_pk_bf16_f32 v3, -v107, s0
	ds_write_b16 v2, v3 offset:224
	v_cvt_pk_bf16_f32 v3, -v106, s0
	ds_write_b16 v2, v3 offset:240
	v_cvt_pk_bf16_f32 v3, -v111, s0
	ds_write_b16 v2, v3 offset:256
	v_cvt_pk_bf16_f32 v3, -v110, s0
	ds_write_b16 v2, v3 offset:272
	v_cvt_pk_bf16_f32 v3, -v113, s0
	ds_write_b16 v2, v3 offset:288
	v_cvt_pk_bf16_f32 v3, -v112, s0
	ds_write_b16 v2, v3 offset:304
	v_cvt_pk_bf16_f32 v3, -v121, s0
	ds_write_b16 v2, v3 offset:320
	v_cvt_pk_bf16_f32 v3, -v120, s0
	ds_write_b16 v2, v3 offset:336
	v_cvt_pk_bf16_f32 v3, -v123, s0
	ds_write_b16 v2, v3 offset:352
	v_cvt_pk_bf16_f32 v3, -v122, s0
	ds_write_b16 v2, v3 offset:368
	v_cvt_pk_bf16_f32 v3, -v74, s0
	ds_write_b16 v2, v3 offset:384
	v_cvt_pk_bf16_f32 v3, -v75, s0
	ds_write_b16 v2, v3 offset:400
	v_cvt_pk_bf16_f32 v3, -v76, s0
	ds_write_b16 v2, v3 offset:416
	v_cvt_pk_bf16_f32 v3, -v77, s0
	ds_write_b16 v2, v3 offset:432
	v_cvt_pk_bf16_f32 v3, -v78, s0
	ds_write_b16 v2, v3 offset:448
	v_cvt_pk_bf16_f32 v3, -v79, s0
	ds_write_b16 v2, v3 offset:464
	v_cvt_pk_bf16_f32 v3, -v105, s0
	ds_write_b16 v2, v3 offset:480
	v_cvt_pk_bf16_f32 v3, -v114, s0
	ds_write_b16 v2, v3 offset:496
	s_waitcnt lgkmcnt(0)
	ds_read_b128 v[2:5], v8
	v_lshl_add_u64 v[6:7], s[0:1], 0, v[56:57]
	v_readlane_b32 s3, v245, 63
	s_add_i32 s76, s76, s3
	s_add_i32 s10, s10, s11
	s_waitcnt lgkmcnt(0)
	flat_store_dwordx4 v[6:7], v[2:5]
	ds_read_b128 v[2:5], v8 offset:1024
	s_mul_i32 s2, s3, 0x5a00
	s_add_u32 s0, s0, s2
	s_mul_hi_i32 s2, s3, 0x5a00
	s_addc_u32 s1, s1, s2
	s_waitcnt lgkmcnt(0)
	flat_store_dwordx4 v[6:7], v[2:5] offset:1024
	ds_read_b128 v[2:5], v8 offset:2048
	s_cmpk_gt_i32 s76, 0xfff
	s_waitcnt lgkmcnt(0)
	flat_store_dwordx4 v[6:7], v[2:5] offset:2048
	ds_read_b128 v[2:5], v8 offset:3072
	s_waitcnt lgkmcnt(0)
	flat_store_dwordx4 v[6:7], v[2:5] offset:3072
	s_waitcnt lgkmcnt(0)
	s_cbranch_scc1 .LBB0_1077
